# S5: 108 flat_load_dwordx4 of the table fragments turned into global_load_dwordx4 (same addresses; lgkmcnt waits for LDS no longer stall on global latency); OUT(0) row-statistics loads issued together;
# speedup vs baseline: 1.0031x; 1.0031x over previous
; DEV int opaque_tid() { int t = threadIdx.x; asm volatile("" : "+v"(t)); return t; }
; #define LAS __attribute__((address_space(3)))
; DEV void s5_phase(LAS char* shm, const bf16_t* Uin, bf16_t* Yout, const char* tab, const float* dskip) {
;     ...
;     for (int item = blockIdx.x; item < BATCH * NG; item += gridDim.x) {
;         const int tid = opaque_tid(), wid = __builtin_amdgcn_readfirstlane(tid >> 6), lane = tid & 63, fr = lane & 15, fq = lane >> 4;
;         const int xcd_ = item & 7, j_ = (item >> 3) & 31, g = xcd_ * 8 + (j_ & 7), b = (j_ >> 3) + 4 * (item >> 8);
;         const bf16_t* Ub = Uin + ((size_t)g * MTOK + (size_t)b * SEQ) * 16;
;         bf16_t* Yb = Yout + ((size_t)g * MTOK + (size_t)b * SEQ) * 16;
;         bf16x8 wfr[8];
;         const bf16_t* wsp = WS + (size_t)g * WS_G + ((size_t)(wid * 16) * 64 + lane) * 8; asm volatile("" : "+v"(wsp));
; #pragma unroll
;         for (int sp = 0; sp < 8; ++sp) wfr[sp] = *(const bf16x8*)(wsp + (size_t)sp * 64 * 8);
;         __syncthreads();
; #pragma unroll
;         for (int i = 0; i < 8; ++i) {
;             const int idx = tid + 512 * i, tok = idx >> 1, hf = idx & 1;
;             const uint4 uv = *(const uint4*)(Ub + (size_t)tok * 16 + hf * 8);
;             *(LAS u32x4*)(shm + hf * PLANE + (tok >> 5) * 528 + (tok & 31) * 16) = (u32x4){uv.x, uv.y, uv.z, uv.w};
;         }
;         for (int idx = tid; idx < 33 * 32; idx += 512) {
;             const uint4 kv = *(const uint4*)(KT + (size_t)g * KT_G + idx * 8);
;             *(LAS u32x4*)(shm + KTL + idx * 16) = (u32x4){kv.x, kv.y, kv.z, kv.w};
;         }
.LBB0_288:
	s_lshl_b32 s0, s44, 3
	s_and_b32 s0, s0, 56
	s_bfe_u32 s1, s44, 0x30003
	s_or_b32 s47, s0, s1
	s_ashr_i32 s1, s44, 6
	s_bfe_u32 s0, s44, 0x20006
	s_and_b32 s1, s1, -4
	v_mov_b32_e32 v172, v254
	s_or_b32 s0, s0, s1
	s_ashr_i32 s1, s0, 31
	v_readfirstlane_b32 s46, v172
	s_ashr_i32 s45, s46, 6
	s_lshl_b64 s[0:1], s[0:1], 15
	s_lshl_b32 s6, s47, 18
	s_add_u32 s0, s6, s0
	s_addc_u32 s1, 0, s1
	s_lshl_b64 s[8:9], s[0:1], 1
	s_add_u32 s0, s17, s8
	s_addc_u32 s1, s18, s9
	s_lshl_b32 s6, s47, 17
	s_add_u32 s12, s23, s6
	s_addc_u32 s13, s24, 0
	s_lshl_b32 s6, s45, 4
	s_ashr_i32 s7, s6, 31
	s_lshl_b64 s[10:11], s[6:7], 10
	v_and_b32_e32 v173, 63, v172
	s_add_u32 s10, s12, s10
	s_addc_u32 s11, s13, s11
	v_lshlrev_b32_e32 v166, 4, v173
	v_lshl_add_u64 v[168:169], s[10:11], 0, v[166:167]
	v_and_b32_e32 v0, 1, v172
	v_add_co_u32_e32 v2, vcc, s27, v168
	v_ashrrev_i32_e32 v66, 1, v172
	s_nop 0
	v_addc_co_u32_e32 v3, vcc, 0, v169, vcc
	global_load_dwordx4 v[46:49], v[168:169], off
	global_load_dwordx4 v[42:45], v[168:169], off offset:1024
	global_load_dwordx4 v[38:41], v[168:169], off offset:2048
	global_load_dwordx4 v[34:37], v[168:169], off offset:3072
	global_load_dwordx4 v[30:33], v[2:3], off
	global_load_dwordx4 v[26:29], v[2:3], off offset:1024
	global_load_dwordx4 v[22:25], v[2:3], off offset:2048
	global_load_dwordx4 v[18:21], v[2:3], off offset:3072
	v_lshlrev_b32_e32 v2, 4, v0
	v_mov_b32_e32 v3, v167
	v_ashrrev_i32_e32 v67, 31, v66
	v_lshl_add_u64 v[62:63], s[0:1], 0, v[2:3]
	v_lshlrev_b64 v[2:3], 5, v[66:67]
	v_add_u32_e32 v1, 0x200, v172
	v_lshl_add_u64 v[2:3], v[62:63], 0, v[2:3]
	v_ashrrev_i32_e32 v68, 1, v1
	s_waitcnt lgkmcnt(0)
	s_barrier
	global_load_dwordx4 v[2:5], v[2:3], off
	v_ashrrev_i32_e32 v69, 31, v68
	v_lshlrev_b64 v[6:7], 5, v[68:69]
	v_add_u32_e32 v67, 0x400, v172
	v_lshl_add_u64 v[6:7], v[62:63], 0, v[6:7]
	v_ashrrev_i32_e32 v70, 1, v67
	global_load_dwordx4 v[6:9], v[6:7], off
	v_ashrrev_i32_e32 v71, 31, v70
	v_lshlrev_b64 v[10:11], 5, v[70:71]
	v_add_u32_e32 v69, 0x600, v172
	v_lshl_add_u64 v[10:11], v[62:63], 0, v[10:11]
	v_ashrrev_i32_e32 v72, 1, v69
	global_load_dwordx4 v[10:13], v[10:11], off
	v_ashrrev_i32_e32 v73, 31, v72
	v_lshlrev_b64 v[14:15], 5, v[72:73]
	v_add_u32_e32 v71, 0x800, v172
	v_lshl_add_u64 v[14:15], v[62:63], 0, v[14:15]
	v_ashrrev_i32_e32 v74, 1, v71
	global_load_dwordx4 v[14:17], v[14:15], off
	v_ashrrev_i32_e32 v75, 31, v74
	v_lshlrev_b64 v[50:51], 5, v[74:75]
	v_add_u32_e32 v73, 0xa00, v172
	v_lshl_add_u64 v[50:51], v[62:63], 0, v[50:51]
	v_ashrrev_i32_e32 v76, 1, v73
	global_load_dwordx4 v[50:53], v[50:51], off
	v_ashrrev_i32_e32 v77, 31, v76
	v_lshlrev_b64 v[54:55], 5, v[76:77]
	v_add_u32_e32 v75, 0xc00, v172
	v_lshl_add_u64 v[54:55], v[62:63], 0, v[54:55]
	v_ashrrev_i32_e32 v78, 1, v75
	global_load_dwordx4 v[54:57], v[54:55], off
	v_ashrrev_i32_e32 v79, 31, v78
	v_lshlrev_b64 v[58:59], 5, v[78:79]
	v_add_u32_e32 v77, 0xe00, v172
	v_lshl_add_u64 v[58:59], v[62:63], 0, v[58:59]
	v_ashrrev_i32_e32 v80, 1, v77
	global_load_dwordx4 v[58:61], v[58:59], off
	v_ashrrev_i32_e32 v81, 31, v80
	v_lshlrev_b64 v[64:65], 5, v[80:81]
	v_lshl_add_u64 v[62:63], v[62:63], 0, v[64:65]
	global_load_dwordx4 v[62:65], v[62:63], off
	v_ashrrev_i32_e32 v79, 6, v172
	v_lshlrev_b32_e32 v66, 4, v66
	v_mad_u32_u24 v0, v0, s28, 0
	v_mul_lo_u32 v79, v79, s29
	v_and_b32_e32 v66, 0x1f0, v66
	v_add3_u32 v66, v0, v79, v66
	v_ashrrev_i32_e32 v1, 6, v1
	v_mul_lo_u32 v1, v1, s29
	v_cmp_gt_i32_e32 vcc, s30, v172
	s_waitcnt vmcnt(0)
	ds_write_b128 v66, v[2:5]
	v_lshlrev_b32_e32 v2, 4, v68
	v_and_b32_e32 v2, 0x1f0, v2
	v_add3_u32 v1, v0, v1, v2
	v_lshlrev_b32_e32 v2, 4, v70
	v_and_b32_e32 v2, 0x1f0, v2
	ds_write_b128 v1, v[6:9]
	v_ashrrev_i32_e32 v1, 6, v67
	v_mul_lo_u32 v1, v1, s29
	v_add3_u32 v1, v0, v1, v2
	v_lshlrev_b32_e32 v2, 4, v72
	v_and_b32_e32 v2, 0x1f0, v2
	ds_write_b128 v1, v[10:13]
	v_ashrrev_i32_e32 v1, 6, v69
	v_mul_lo_u32 v1, v1, s29
	v_add3_u32 v1, v0, v1, v2
	v_lshlrev_b32_e32 v2, 4, v74
	v_and_b32_e32 v2, 0x1f0, v2
	ds_write_b128 v1, v[14:17]
	v_ashrrev_i32_e32 v1, 6, v71
	v_mul_lo_u32 v1, v1, s29
	v_add3_u32 v1, v0, v1, v2
	v_lshlrev_b32_e32 v2, 4, v76
	v_and_b32_e32 v2, 0x1f0, v2
	ds_write_b128 v1, v[50:53]
	v_ashrrev_i32_e32 v1, 6, v73
	v_mul_lo_u32 v1, v1, s29
	v_add3_u32 v1, v0, v1, v2
	v_lshlrev_b32_e32 v2, 4, v78
	v_and_b32_e32 v2, 0x1f0, v2
	ds_write_b128 v1, v[54:57]
	v_ashrrev_i32_e32 v1, 6, v75
	v_mul_lo_u32 v1, v1, s29
	v_add3_u32 v1, v0, v1, v2
	v_lshlrev_b32_e32 v2, 4, v80
	v_and_b32_e32 v2, 0x1f0, v2
	ds_write_b128 v1, v[58:61]
	v_ashrrev_i32_e32 v1, 6, v77
	v_mul_lo_u32 v1, v1, s29
	v_add3_u32 v0, v0, v1, v2
	ds_write_b128 v0, v[62:65]
	s_and_saveexec_b64 s[0:1], vcc
	s_cbranch_execz .LBB0_291
	s_mul_i32 s7, s47, 0x4200
	s_add_u32 s10, s21, s7
	s_addc_u32 s11, s22, 0
	v_add_u32_e32 v4, 0xfffffe00, v172
	v_lshl_add_u32 v5, v172, 4, s31
	v_lshlrev_b32_e32 v2, 3, v172
	s_mov_b64 s[12:13], 0

; #define LAS __attribute__((address_space(3)))
; template <int H2>
; DEV void s5_p1_all(LAS char* shm, int wid, int fr, int fq, bf16x8 (&wfr)[8], const bf16_t* wsp, f32x4 (&acc)[4][4], f32x4 (&sac)[4]) {
;     ...
;     const LAS char* ub = shm + (fq & 1) * PLANE + fr * 528 + (fq >> 1) * 16;
;     const LAS char* kb = shm + KTL + (1 - (fq >> 1)) * 512 + fr * 32 + (fq & 1) * 16 + (wid - 30) * 512;
;     ...
;     bf16x8 bu[4];
; #pragma unroll
;     for (int nt = 0; nt < 4; ++nt) bu[nt] = *(const LAS bf16x8*)(ub + nt * 16 * 528);
; #pragma unroll
;     for (int sp = 0; sp < 16; ++sp) {
;         bf16x8 bn[4], kf[4];
; #pragma unroll
;         for (int q = 0; q < 4; ++q) if (q >= S5_Q0(sp)) kf[q] = *(const LAS bf16x8*)(kb + (8 * q - 2 * sp + 30) * 512);
; #pragma unroll
;         for (int nt = 0; nt < 4; ++nt) bn[nt] = bu[nt];
;         if (sp < 15) {
; #pragma unroll
;             for (int nt = 0; nt < 4; ++nt) bn[nt] = *(const LAS bf16x8*)(ub + nt * 16 * 528 + (sp + 1) * 32);
;         }
; #pragma unroll
;         for (int nt = 0; nt < 4; ++nt) sac[nt] = __builtin_amdgcn_mfma_f32_16x16x32_bf16(wfr[sp & 7], bu[nt], sac[nt], 0, 0, 0);
;         if (sp < 8) wfr[sp & 7] = *(const bf16x8*)(wsp + (size_t)(sp + 8) * 64 * 8);
.LBB0_291:
	s_or_b64 exec, exec, s[0:1]
	s_lshl_b32 s7, s47, 16
	v_and_b32_e32 v175, 15, v172
	v_bfe_u32 v0, v173, 4, 1
	v_lshrrev_b32_e32 v174, 5, v173
	s_mov_b64 s[0:1], -1
	s_cmpk_gt_u32 s46, 0x7f
	v_lshlrev_b32_e32 v170, 5, v175
	v_mad_u32_u24 v179, v0, s28, 0
	v_mul_u32_u24_e32 v176, 0x210, v175
	v_lshlrev_b32_e32 v180, 4, v174
	v_lshlrev_b32_e32 v178, 9, v174
	v_lshlrev_b32_e32 v177, 4, v0
	s_waitcnt lgkmcnt(0)
	s_barrier
	s_cbranch_scc0 .LBB0_298
	v_add_co_u32_e32 v2, vcc, 0x2000, v168
	v_xor_b32_e32 v0, 0x200, v178
	s_nop 0
	v_addc_co_u32_e32 v3, vcc, 0, v169, vcc
	global_load_dwordx4 v[82:85], v[2:3], off
	v_mul_u32_u24_e32 v171, 0x210, v175
	s_lshl_b32 s50, s45, 9
	v_add3_u32 v0, s31, v0, v170
	v_add3_u32 v181, v179, v171, v180
	v_add3_u32 v182, v0, v177, s50
	ds_read_b128 v[118:121], v181
	ds_read_b128 v[86:89], v181 offset:32
	ds_read_b128 v[146:149], v182
	ds_read_b128 v[142:145], v182 offset:4096
	ds_read_b128 v[130:133], v182 offset:8192
	ds_read_b128 v[122:125], v182 offset:12288
	ds_read_b128 v[126:129], v181 offset:8448
	ds_read_b128 v[94:97], v181 offset:8480
	ds_read_b128 v[134:137], v181 offset:16896
	ds_read_b128 v[98:101], v181 offset:16928
	ds_read_b128 v[138:141], v181 offset:25344
	ds_read_b128 v[90:93], v181 offset:25376
	s_ashr_i32 s51, s46, 7
	s_mov_b64 s[10:11], 0
	s_cmp_lt_i32 s51, 2
	s_mov_b64 s[12:13], 0
	s_cbranch_scc0 .LBB0_308
	s_and_b64 vcc, exec, s[0:1]
	s_cbranch_vccnz .LBB0_311

; #define LAS __attribute__((address_space(3)))
; template <int H2>
; DEV void s5_p1_all(LAS char* shm, int wid, int fr, int fq, bf16x8 (&wfr)[8], const bf16_t* wsp, f32x4 (&acc)[4][4], f32x4 (&sac)[4]) {
;     ...
;     for (int sp = 0; sp < 16; ++sp) {
;         bf16x8 bn[4], kf[4];
; #pragma unroll
;         for (int q = 0; q < 4; ++q) if (q >= S5_Q0(sp)) kf[q] = *(const LAS bf16x8*)(kb + (8 * q - 2 * sp + 30) * 512);
; #pragma unroll
;         for (int nt = 0; nt < 4; ++nt) bn[nt] = bu[nt];
;         if (sp < 15) {
; #pragma unroll
;             for (int nt = 0; nt < 4; ++nt) bn[nt] = *(const LAS bf16x8*)(ub + nt * 16 * 528 + (sp + 1) * 32);
;         }
; #pragma unroll
;         for (int nt = 0; nt < 4; ++nt) sac[nt] = __builtin_amdgcn_mfma_f32_16x16x32_bf16(wfr[sp & 7], bu[nt], sac[nt], 0, 0, 0);
;         if (sp < 8) wfr[sp & 7] = *(const bf16x8*)(wsp + (size_t)(sp + 8) * 64 * 8);
; #pragma unroll
;         for (int q = 0; q < 4; ++q) {
;             if (q >= S5_Q0(sp)) {
; #pragma unroll
;                 for (int nt = 0; nt < 4; ++nt) acc[q][nt] = __builtin_amdgcn_mfma_f32_16x16x32_bf16(kf[q], bu[nt], acc[q][nt], 0, 0, 0);
;             }
;         }
; #pragma unroll
;         for (int nt = 0; nt < 4; ++nt) bu[nt] = bn[nt];
;         __builtin_amdgcn_sched_barrier(0);
;     }
.LBB0_296:
	s_waitcnt lgkmcnt(0)
	v_mfma_f32_16x16x32_bf16 v[2:5], v[46:49], v[118:121], 0
	v_mfma_f32_16x16x32_bf16 v[6:9], v[46:49], v[126:129], 0
	v_mfma_f32_16x16x32_bf16 v[10:13], v[46:49], v[134:137], 0
	v_mfma_f32_16x16x32_bf16 v[14:17], v[46:49], v[138:141], 0
	v_mfma_f32_16x16x32_bf16 v[50:53], v[146:149], v[118:121], 0
	v_mfma_f32_16x16x32_bf16 v[54:57], v[146:149], v[126:129], 0
	v_mfma_f32_16x16x32_bf16 v[58:61], v[146:149], v[134:137], 0
	v_mfma_f32_16x16x32_bf16 v[62:65], v[146:149], v[138:141], 0
	v_mfma_f32_16x16x32_bf16 v[66:69], v[142:145], v[118:121], 0
	v_mfma_f32_16x16x32_bf16 v[70:73], v[142:145], v[126:129], 0
	v_mfma_f32_16x16x32_bf16 v[74:77], v[142:145], v[134:137], 0
	v_mfma_f32_16x16x32_bf16 v[78:81], v[142:145], v[138:141], 0
	v_mfma_f32_16x16x32_bf16 v[102:105], v[130:133], v[118:121], 0
	v_mfma_f32_16x16x32_bf16 v[106:109], v[130:133], v[126:129], 0
	v_mfma_f32_16x16x32_bf16 v[110:113], v[130:133], v[134:137], 0
	v_mfma_f32_16x16x32_bf16 v[114:117], v[130:133], v[138:141], 0
	v_mfma_f32_16x16x32_bf16 v[118:121], v[122:125], v[118:121], 0
	v_mfma_f32_16x16x32_bf16 v[126:129], v[122:125], v[126:129], 0
	v_mfma_f32_16x16x32_bf16 v[130:133], v[122:125], v[134:137], 0
	v_mfma_f32_16x16x32_bf16 v[122:125], v[122:125], v[138:141], 0
	v_mfma_f32_16x16x32_bf16 v[134:137], v[42:45], v[86:89], v[2:5]
	v_add_co_u32_e32 v150, vcc, s34, v168
	s_nop 1
	ds_read_b128 v[2:5], v183
	v_mfma_f32_16x16x32_bf16 v[142:145], v[42:45], v[98:101], v[10:13]
	v_addc_co_u32_e32 v151, vcc, 0, v169, vcc
	v_mfma_f32_16x16x32_bf16 v[146:149], v[42:45], v[90:93], v[14:17]
	s_waitcnt lgkmcnt(0)
	v_mfma_f32_16x16x32_bf16 v[14:17], v[2:5], v[86:89], v[50:53]
	v_mfma_f32_16x16x32_bf16 v[10:13], v[2:5], v[94:97], v[54:57]
	s_nop 1
	ds_read_b128 v[50:53], v182 offset:3072
	ds_read_b128 v[54:57], v182 offset:7168
	v_mfma_f32_16x16x32_bf16 v[138:141], v[42:45], v[94:97], v[6:9]
	v_mfma_f32_16x16x32_bf16 v[6:9], v[2:5], v[98:101], v[58:61]
	s_waitcnt lgkmcnt(0)
	v_mfma_f32_16x16x32_bf16 v[58:61], v[50:53], v[86:89], v[66:69]
	v_mfma_f32_16x16x32_bf16 v[66:69], v[50:53], v[98:101], v[74:77]
	v_mfma_f32_16x16x32_bf16 v[74:77], v[54:57], v[94:97], v[106:109]
	s_nop 2
	global_load_dwordx4 v[106:109], v[150:151], off offset:1024
	v_mfma_f32_16x16x32_bf16 v[2:5], v[2:5], v[90:93], v[62:65]
	v_mfma_f32_16x16x32_bf16 v[62:65], v[50:53], v[94:97], v[70:73]
	v_mfma_f32_16x16x32_bf16 v[70:73], v[54:57], v[86:89], v[102:105]
	s_nop 2
	ds_read_b128 v[102:105], v182 offset:11264
	v_mfma_f32_16x16x32_bf16 v[50:53], v[50:53], v[90:93], v[78:81]
	v_mfma_f32_16x16x32_bf16 v[78:81], v[54:57], v[98:101], v[110:113]
	v_mfma_f32_16x16x32_bf16 v[54:57], v[54:57], v[90:93], v[114:117]
	s_waitcnt lgkmcnt(0)
	v_mfma_f32_16x16x32_bf16 v[86:89], v[102:105], v[86:89], v[118:121]
	v_mfma_f32_16x16x32_bf16 v[94:97], v[102:105], v[94:97], v[126:129]
	ds_read_b128 v[110:113], v181 offset:64
	ds_read_b128 v[114:117], v181 offset:8512
	ds_read_b128 v[118:121], v181 offset:16960
	ds_read_b128 v[126:129], v181 offset:25408
	v_mfma_f32_16x16x32_bf16 v[98:101], v[102:105], v[98:101], v[130:133]
	v_mfma_f32_16x16x32_bf16 v[90:93], v[102:105], v[90:93], v[122:125]
	s_waitcnt lgkmcnt(0)
	v_mfma_f32_16x16x32_bf16 v[122:125], v[38:41], v[114:117], v[138:141]
	v_mfma_f32_16x16x32_bf16 v[130:133], v[38:41], v[118:121], v[142:145]
	s_nop 1
	ds_read_b128 v[138:141], v182 offset:2048
	ds_read_b128 v[142:145], v182 offset:6144
	s_waitcnt lgkmcnt(0)
	v_mfma_f32_16x16x32_bf16 v[58:61], v[138:141], v[110:113], v[58:61]
	v_mfma_f32_16x16x32_bf16 v[62:65], v[138:141], v[114:117], v[62:65]
	v_mfma_f32_16x16x32_bf16 v[66:69], v[138:141], v[118:121], v[66:69]
	v_mfma_f32_16x16x32_bf16 v[50:53], v[138:141], v[126:129], v[50:53]
	ds_read_b128 v[138:141], v182 offset:10240
	v_mfma_f32_16x16x32_bf16 v[102:105], v[38:41], v[110:113], v[134:137]
	v_mfma_f32_16x16x32_bf16 v[70:73], v[142:145], v[110:113], v[70:73]
	s_waitcnt lgkmcnt(0)
	v_mfma_f32_16x16x32_bf16 v[86:89], v[138:141], v[110:113], v[86:89]
	global_load_dwordx4 v[110:113], v[150:151], off offset:2048
	v_mfma_f32_16x16x32_bf16 v[134:137], v[38:41], v[126:129], v[146:149]
	v_mfma_f32_16x16x32_bf16 v[74:77], v[142:145], v[114:117], v[74:77]
	v_mfma_f32_16x16x32_bf16 v[78:81], v[142:145], v[118:121], v[78:81]
	v_mfma_f32_16x16x32_bf16 v[54:57], v[142:145], v[126:129], v[54:57]
	v_mfma_f32_16x16x32_bf16 v[94:97], v[138:141], v[114:117], v[94:97]
	v_mfma_f32_16x16x32_bf16 v[98:101], v[138:141], v[118:121], v[98:101]
	ds_read_b128 v[114:117], v181 offset:96
	ds_read_b128 v[118:121], v181 offset:8544
	ds_read_b128 v[142:145], v181 offset:16992
	ds_read_b128 v[146:149], v181 offset:25440
	v_mfma_f32_16x16x32_bf16 v[90:93], v[138:141], v[126:129], v[90:93]
	s_waitcnt lgkmcnt(0)
	v_mfma_f32_16x16x32_bf16 v[126:129], v[34:37], v[142:145], v[130:133]
	v_mfma_f32_16x16x32_bf16 v[130:133], v[34:37], v[146:149], v[134:137]
	s_nop 2
	ds_read_b128 v[134:137], v182 offset:1024
	ds_read_b128 v[138:141], v182 offset:5120
	s_waitcnt lgkmcnt(0)
	v_mfma_f32_16x16x32_bf16 v[58:61], v[134:137], v[114:117], v[58:61]
	v_mfma_f32_16x16x32_bf16 v[62:65], v[134:137], v[118:121], v[62:65]
	v_mfma_f32_16x16x32_bf16 v[66:69], v[134:137], v[142:145], v[66:69]
	v_mfma_f32_16x16x32_bf16 v[50:53], v[134:137], v[146:149], v[50:53]
	ds_read_b128 v[134:137], v182 offset:9216
	v_mfma_f32_16x16x32_bf16 v[102:105], v[34:37], v[114:117], v[102:105]
	v_mfma_f32_16x16x32_bf16 v[70:73], v[138:141], v[114:117], v[70:73]
	s_waitcnt lgkmcnt(0)
; #define LAS __attribute__((address_space(3)))
; template <int H2>
; DEV void s5_p1_all(LAS char* shm, int wid, int fr, int fq, bf16x8 (&wfr)[8], const bf16_t* wsp, f32x4 (&acc)[4][4], f32x4 (&sac)[4]) {
;     ...
;     for (int sp = 0; sp < 16; ++sp) {
;         bf16x8 bn[4], kf[4];
; #pragma unroll
;         for (int q = 0; q < 4; ++q) if (q >= S5_Q0(sp)) kf[q] = *(const LAS bf16x8*)(kb + (8 * q - 2 * sp + 30) * 512);
; #pragma unroll
;         for (int nt = 0; nt < 4; ++nt) bn[nt] = bu[nt];
;         if (sp < 15) {
; #pragma unroll
;             for (int nt = 0; nt < 4; ++nt) bn[nt] = *(const LAS bf16x8*)(ub + nt * 16 * 528 + (sp + 1) * 32);
;         }
; #pragma unroll
;         for (int nt = 0; nt < 4; ++nt) sac[nt] = __builtin_amdgcn_mfma_f32_16x16x32_bf16(wfr[sp & 7], bu[nt], sac[nt], 0, 0, 0);
;         if (sp < 8) wfr[sp & 7] = *(const bf16x8*)(wsp + (size_t)(sp + 8) * 64 * 8);
; #pragma unroll
;         for (int q = 0; q < 4; ++q) {
;             if (q >= S5_Q0(sp)) {
; #pragma unroll
;                 for (int nt = 0; nt < 4; ++nt) acc[q][nt] = __builtin_amdgcn_mfma_f32_16x16x32_bf16(kf[q], bu[nt], acc[q][nt], 0, 0, 0);
;             }
;         }
; #pragma unroll
;         for (int nt = 0; nt < 4; ++nt) bu[nt] = bn[nt];
;         __builtin_amdgcn_sched_barrier(0);
;     }
	v_mfma_f32_16x16x32_bf16 v[86:89], v[134:137], v[114:117], v[86:89]
	global_load_dwordx4 v[114:117], v[150:151], off offset:3072
	v_mfma_f32_16x16x32_bf16 v[122:125], v[34:37], v[118:121], v[122:125]
	v_mfma_f32_16x16x32_bf16 v[74:77], v[138:141], v[118:121], v[74:77]
	v_mfma_f32_16x16x32_bf16 v[78:81], v[138:141], v[142:145], v[78:81]
	v_mfma_f32_16x16x32_bf16 v[54:57], v[138:141], v[146:149], v[54:57]
	v_mfma_f32_16x16x32_bf16 v[94:97], v[134:137], v[118:121], v[94:97]
	v_mfma_f32_16x16x32_bf16 v[98:101], v[134:137], v[142:145], v[98:101]
	ds_read_b128 v[118:121], v181 offset:128
	ds_read_b128 v[138:141], v181 offset:8576
	ds_read_b128 v[142:145], v181 offset:17024
	ds_read_b128 v[150:153], v181 offset:25472
	v_mfma_f32_16x16x32_bf16 v[90:93], v[134:137], v[146:149], v[90:93]
	ds_read_b128 v[134:137], v182
	ds_read_b128 v[146:149], v182 offset:4096
	v_add_co_u32_e32 v184, vcc, s38, v168
	s_waitcnt lgkmcnt(0)
	v_mfma_f32_16x16x32_bf16 v[102:105], v[30:33], v[118:121], v[102:105]
	v_addc_co_u32_e32 v185, vcc, 0, v169, vcc
	v_mfma_f32_16x16x32_bf16 v[58:61], v[134:137], v[118:121], v[58:61]
	v_mfma_f32_16x16x32_bf16 v[154:157], v[134:137], v[138:141], v[62:65]
	v_mfma_f32_16x16x32_bf16 v[66:69], v[134:137], v[142:145], v[66:69]
	v_mfma_f32_16x16x32_bf16 v[50:53], v[134:137], v[150:153], v[50:53]
	v_mfma_f32_16x16x32_bf16 v[134:137], v[146:149], v[150:153], v[54:57]
	s_nop 2
	ds_read_b128 v[54:57], v182 offset:8192
	v_mfma_f32_16x16x32_bf16 v[70:73], v[146:149], v[118:121], v[70:73]
	s_waitcnt lgkmcnt(0)
	v_mfma_f32_16x16x32_bf16 v[86:89], v[54:57], v[118:121], v[86:89]
	global_load_dwordx4 v[118:121], v[184:185], off
	v_mfma_f32_16x16x32_bf16 v[122:125], v[30:33], v[138:141], v[122:125]
	v_mfma_f32_16x16x32_bf16 v[126:129], v[30:33], v[142:145], v[126:129]
	v_mfma_f32_16x16x32_bf16 v[74:77], v[146:149], v[138:141], v[74:77]
	v_mfma_f32_16x16x32_bf16 v[78:81], v[146:149], v[142:145], v[78:81]
	v_mfma_f32_16x16x32_bf16 v[94:97], v[54:57], v[138:141], v[94:97]
	v_mfma_f32_16x16x32_bf16 v[98:101], v[54:57], v[142:145], v[98:101]
	ds_read_b128 v[138:141], v181 offset:160
	ds_read_b128 v[142:145], v181 offset:8608
	ds_read_b128 v[146:149], v181 offset:17056
	ds_read_b128 v[158:161], v181 offset:25504
	v_mfma_f32_16x16x32_bf16 v[130:133], v[30:33], v[150:153], v[130:133]
	v_mfma_f32_16x16x32_bf16 v[90:93], v[54:57], v[150:153], v[90:93]
	ds_read_b128 v[150:153], v183
	s_waitcnt lgkmcnt(0)
	v_mfma_f32_16x16x32_bf16 v[102:105], v[26:29], v[138:141], v[102:105]
	v_mfma_f32_16x16x32_bf16 v[122:125], v[26:29], v[142:145], v[122:125]
	v_mfma_f32_16x16x32_bf16 v[62:65], v[150:153], v[138:141], v[58:61]
	v_mfma_f32_16x16x32_bf16 v[58:61], v[150:153], v[142:145], v[154:157]
	v_mfma_f32_16x16x32_bf16 v[54:57], v[150:153], v[146:149], v[66:69]
	v_mfma_f32_16x16x32_bf16 v[50:53], v[150:153], v[158:161], v[50:53]
	s_nop 1
	ds_read_b128 v[66:69], v182 offset:3072
	ds_read_b128 v[150:153], v182 offset:7168
	s_waitcnt lgkmcnt(0)
	v_mfma_f32_16x16x32_bf16 v[70:73], v[66:69], v[138:141], v[70:73]
	v_mfma_f32_16x16x32_bf16 v[74:77], v[66:69], v[142:145], v[74:77]
	v_mfma_f32_16x16x32_bf16 v[78:81], v[66:69], v[146:149], v[78:81]
	v_mfma_f32_16x16x32_bf16 v[66:69], v[66:69], v[158:161], v[134:137]
	s_nop 2
	global_load_dwordx4 v[134:137], v[184:185], off offset:1024
	v_mfma_f32_16x16x32_bf16 v[126:129], v[26:29], v[146:149], v[126:129]
	v_mfma_f32_16x16x32_bf16 v[86:89], v[150:153], v[138:141], v[86:89]
	v_mfma_f32_16x16x32_bf16 v[94:97], v[150:153], v[142:145], v[94:97]
	v_mfma_f32_16x16x32_bf16 v[98:101], v[150:153], v[146:149], v[98:101]
	ds_read_b128 v[138:141], v181 offset:192
	ds_read_b128 v[142:145], v181 offset:8640
	ds_read_b128 v[146:149], v181 offset:17088
	ds_read_b128 v[154:157], v181 offset:25536
	v_mfma_f32_16x16x32_bf16 v[130:133], v[26:29], v[158:161], v[130:133]
	v_mfma_f32_16x16x32_bf16 v[90:93], v[150:153], v[158:161], v[90:93]
	ds_read_b128 v[150:153], v182 offset:2048
	ds_read_b128 v[158:161], v182 offset:6144
	s_waitcnt lgkmcnt(0)
	v_mfma_f32_16x16x32_bf16 v[102:105], v[22:25], v[138:141], v[102:105]
	v_mfma_f32_16x16x32_bf16 v[70:73], v[150:153], v[138:141], v[70:73]
	v_mfma_f32_16x16x32_bf16 v[86:89], v[158:161], v[138:141], v[86:89]
	global_load_dwordx4 v[138:141], v[184:185], off offset:2048
	v_mfma_f32_16x16x32_bf16 v[122:125], v[22:25], v[142:145], v[122:125]
	v_mfma_f32_16x16x32_bf16 v[126:129], v[22:25], v[146:149], v[126:129]
	v_mfma_f32_16x16x32_bf16 v[74:77], v[150:153], v[142:145], v[74:77]
	v_mfma_f32_16x16x32_bf16 v[78:81], v[150:153], v[146:149], v[78:81]
	v_mfma_f32_16x16x32_bf16 v[66:69], v[150:153], v[154:157], v[66:69]
	v_mfma_f32_16x16x32_bf16 v[94:97], v[158:161], v[142:145], v[94:97]
	v_mfma_f32_16x16x32_bf16 v[98:101], v[158:161], v[146:149], v[98:101]
	ds_read_b128 v[142:145], v181 offset:224
	ds_read_b128 v[146:149], v181 offset:8672
	ds_read_b128 v[150:153], v181 offset:17120
	ds_read_b128 v[162:165], v181 offset:25568
	v_mfma_f32_16x16x32_bf16 v[130:133], v[22:25], v[154:157], v[130:133]
	v_mfma_f32_16x16x32_bf16 v[90:93], v[158:161], v[154:157], v[90:93]
	ds_read_b128 v[154:157], v182 offset:1024
	ds_read_b128 v[158:161], v182 offset:5120
	s_waitcnt lgkmcnt(0)
; #define LAS __attribute__((address_space(3)))
; template <int H2>
; DEV void s5_p1_all(LAS char* shm, int wid, int fr, int fq, bf16x8 (&wfr)[8], const bf16_t* wsp, f32x4 (&acc)[4][4], f32x4 (&sac)[4]) {
;     ...
;     for (int sp = 0; sp < 16; ++sp) {
;         bf16x8 bn[4], kf[4];
; #pragma unroll
;         for (int q = 0; q < 4; ++q) if (q >= S5_Q0(sp)) kf[q] = *(const LAS bf16x8*)(kb + (8 * q - 2 * sp + 30) * 512);
; #pragma unroll
;         for (int nt = 0; nt < 4; ++nt) bn[nt] = bu[nt];
;         if (sp < 15) {
; #pragma unroll
;             for (int nt = 0; nt < 4; ++nt) bn[nt] = *(const LAS bf16x8*)(ub + nt * 16 * 528 + (sp + 1) * 32);
;         }
; #pragma unroll
;         for (int nt = 0; nt < 4; ++nt) sac[nt] = __builtin_amdgcn_mfma_f32_16x16x32_bf16(wfr[sp & 7], bu[nt], sac[nt], 0, 0, 0);
;         if (sp < 8) wfr[sp & 7] = *(const bf16x8*)(wsp + (size_t)(sp + 8) * 64 * 8);
; #pragma unroll
;         for (int q = 0; q < 4; ++q) {
;             if (q >= S5_Q0(sp)) {
; #pragma unroll
;                 for (int nt = 0; nt < 4; ++nt) acc[q][nt] = __builtin_amdgcn_mfma_f32_16x16x32_bf16(kf[q], bu[nt], acc[q][nt], 0, 0, 0);
;             }
;         }
; #pragma unroll
;         for (int nt = 0; nt < 4; ++nt) bu[nt] = bn[nt];
;         __builtin_amdgcn_sched_barrier(0);
;     }
	v_mfma_f32_16x16x32_bf16 v[102:105], v[18:21], v[142:145], v[102:105]
	v_mfma_f32_16x16x32_bf16 v[70:73], v[154:157], v[142:145], v[70:73]
	v_mfma_f32_16x16x32_bf16 v[86:89], v[158:161], v[142:145], v[86:89]
	global_load_dwordx4 v[142:145], v[184:185], off offset:3072
	v_mfma_f32_16x16x32_bf16 v[122:125], v[18:21], v[146:149], v[122:125]
	v_mfma_f32_16x16x32_bf16 v[126:129], v[18:21], v[150:153], v[126:129]
	v_mfma_f32_16x16x32_bf16 v[74:77], v[154:157], v[146:149], v[74:77]
	v_mfma_f32_16x16x32_bf16 v[78:81], v[154:157], v[150:153], v[78:81]
	v_mfma_f32_16x16x32_bf16 v[66:69], v[154:157], v[162:165], v[66:69]
	v_mfma_f32_16x16x32_bf16 v[94:97], v[158:161], v[146:149], v[94:97]
	v_mfma_f32_16x16x32_bf16 v[98:101], v[158:161], v[150:153], v[98:101]
	ds_read_b128 v[146:149], v181 offset:256
	ds_read_b128 v[150:153], v181 offset:8704
	ds_read_b128 v[154:157], v181 offset:17152
	ds_read_b128 v[184:187], v181 offset:25600
	v_mfma_f32_16x16x32_bf16 v[130:133], v[18:21], v[162:165], v[130:133]
	v_mfma_f32_16x16x32_bf16 v[90:93], v[158:161], v[162:165], v[90:93]
	s_waitcnt vmcnt(0) lgkmcnt(0)
	v_mfma_f32_16x16x32_bf16 v[102:105], v[82:85], v[146:149], v[102:105]
	v_mfma_f32_16x16x32_bf16 v[122:125], v[82:85], v[150:153], v[122:125]
	v_mfma_f32_16x16x32_bf16 v[126:129], v[82:85], v[154:157], v[126:129]
	v_mfma_f32_16x16x32_bf16 v[82:85], v[82:85], v[184:187], v[130:133]
	s_nop 2
	ds_read_b128 v[130:133], v182
	ds_read_b128 v[158:161], v182 offset:4096
	s_waitcnt lgkmcnt(1)
	v_mfma_f32_16x16x32_bf16 v[70:73], v[130:133], v[146:149], v[70:73]
	v_mfma_f32_16x16x32_bf16 v[74:77], v[130:133], v[150:153], v[74:77]
	v_mfma_f32_16x16x32_bf16 v[162:165], v[130:133], v[154:157], v[78:81]
	v_mfma_f32_16x16x32_bf16 v[66:69], v[130:133], v[184:187], v[66:69]
	s_waitcnt lgkmcnt(0)
	v_mfma_f32_16x16x32_bf16 v[86:89], v[158:161], v[146:149], v[86:89]
	v_mfma_f32_16x16x32_bf16 v[94:97], v[158:161], v[150:153], v[94:97]
	v_mfma_f32_16x16x32_bf16 v[98:101], v[158:161], v[154:157], v[98:101]
	ds_read_b128 v[130:133], v181 offset:288
	ds_read_b128 v[146:149], v181 offset:8736
	ds_read_b128 v[150:153], v181 offset:17184
	ds_read_b128 v[154:157], v181 offset:25632
	v_mfma_f32_16x16x32_bf16 v[90:93], v[158:161], v[184:187], v[90:93]
	s_waitcnt lgkmcnt(3)
	v_mfma_f32_16x16x32_bf16 v[102:105], v[106:109], v[130:133], v[102:105]
	s_waitcnt lgkmcnt(2)
	v_mfma_f32_16x16x32_bf16 v[122:125], v[106:109], v[146:149], v[122:125]
	s_waitcnt lgkmcnt(1)
	v_mfma_f32_16x16x32_bf16 v[126:129], v[106:109], v[150:153], v[126:129]
	s_waitcnt lgkmcnt(0)
	v_mfma_f32_16x16x32_bf16 v[82:85], v[106:109], v[154:157], v[82:85]
	ds_read_b128 v[106:109], v183
	ds_read_b128 v[158:161], v182 offset:3072
	s_waitcnt lgkmcnt(1)
	v_mfma_f32_16x16x32_bf16 v[78:81], v[106:109], v[130:133], v[70:73]
	v_mfma_f32_16x16x32_bf16 v[74:77], v[106:109], v[146:149], v[74:77]
	v_mfma_f32_16x16x32_bf16 v[70:73], v[106:109], v[150:153], v[162:165]
	v_mfma_f32_16x16x32_bf16 v[66:69], v[106:109], v[154:157], v[66:69]
	s_waitcnt lgkmcnt(0)
	v_mfma_f32_16x16x32_bf16 v[86:89], v[158:161], v[130:133], v[86:89]
	v_mfma_f32_16x16x32_bf16 v[94:97], v[158:161], v[146:149], v[94:97]
	v_mfma_f32_16x16x32_bf16 v[98:101], v[158:161], v[150:153], v[98:101]
	ds_read_b128 v[106:109], v181 offset:320
	ds_read_b128 v[130:133], v181 offset:8768
	ds_read_b128 v[146:149], v181 offset:17216
	ds_read_b128 v[150:153], v181 offset:25664
	v_mfma_f32_16x16x32_bf16 v[90:93], v[158:161], v[154:157], v[90:93]
	s_waitcnt lgkmcnt(3)
	v_mfma_f32_16x16x32_bf16 v[102:105], v[110:113], v[106:109], v[102:105]
	s_waitcnt lgkmcnt(2)
	v_mfma_f32_16x16x32_bf16 v[122:125], v[110:113], v[130:133], v[122:125]
	s_waitcnt lgkmcnt(1)
	v_mfma_f32_16x16x32_bf16 v[126:129], v[110:113], v[146:149], v[126:129]
	s_waitcnt lgkmcnt(0)
	v_mfma_f32_16x16x32_bf16 v[82:85], v[110:113], v[150:153], v[82:85]
	ds_read_b128 v[110:113], v182 offset:2048
	s_waitcnt lgkmcnt(0)
; #define LAS __attribute__((address_space(3)))
; template <int H2>
; DEV void s5_p1_all(LAS char* shm, int wid, int fr, int fq, bf16x8 (&wfr)[8], const bf16_t* wsp, f32x4 (&acc)[4][4], f32x4 (&sac)[4]) {
;     ...
;     for (int sp = 0; sp < 16; ++sp) {
;         bf16x8 bn[4], kf[4];
; #pragma unroll
;         for (int q = 0; q < 4; ++q) if (q >= S5_Q0(sp)) kf[q] = *(const LAS bf16x8*)(kb + (8 * q - 2 * sp + 30) * 512);
; #pragma unroll
;         for (int nt = 0; nt < 4; ++nt) bn[nt] = bu[nt];
;         if (sp < 15) {
; #pragma unroll
;             for (int nt = 0; nt < 4; ++nt) bn[nt] = *(const LAS bf16x8*)(ub + nt * 16 * 528 + (sp + 1) * 32);
;         }
; #pragma unroll
;         for (int nt = 0; nt < 4; ++nt) sac[nt] = __builtin_amdgcn_mfma_f32_16x16x32_bf16(wfr[sp & 7], bu[nt], sac[nt], 0, 0, 0);
;         if (sp < 8) wfr[sp & 7] = *(const bf16x8*)(wsp + (size_t)(sp + 8) * 64 * 8);
; #pragma unroll
;         for (int q = 0; q < 4; ++q) {
;             if (q >= S5_Q0(sp)) {
; #pragma unroll
;                 for (int nt = 0; nt < 4; ++nt) acc[q][nt] = __builtin_amdgcn_mfma_f32_16x16x32_bf16(kf[q], bu[nt], acc[q][nt], 0, 0, 0);
;             }
;         }
; #pragma unroll
;         for (int nt = 0; nt < 4; ++nt) bu[nt] = bn[nt];
;         __builtin_amdgcn_sched_barrier(0);
;     }
	v_mfma_f32_16x16x32_bf16 v[86:89], v[110:113], v[106:109], v[86:89]
	v_mfma_f32_16x16x32_bf16 v[94:97], v[110:113], v[130:133], v[94:97]
	v_mfma_f32_16x16x32_bf16 v[98:101], v[110:113], v[146:149], v[98:101]
	ds_read_b128 v[106:109], v181 offset:352
	ds_read_b128 v[130:133], v181 offset:8800
	ds_read_b128 v[146:149], v181 offset:17248
	ds_read_b128 v[154:157], v181 offset:25696
	v_mfma_f32_16x16x32_bf16 v[90:93], v[110:113], v[150:153], v[90:93]
	s_waitcnt lgkmcnt(3)
	v_mfma_f32_16x16x32_bf16 v[102:105], v[114:117], v[106:109], v[102:105]
	s_waitcnt lgkmcnt(2)
	v_mfma_f32_16x16x32_bf16 v[110:113], v[114:117], v[130:133], v[122:125]
	s_waitcnt lgkmcnt(1)
	v_mfma_f32_16x16x32_bf16 v[122:125], v[114:117], v[146:149], v[126:129]
	s_waitcnt lgkmcnt(0)
	v_mfma_f32_16x16x32_bf16 v[82:85], v[114:117], v[154:157], v[82:85]
	ds_read_b128 v[114:117], v182 offset:1024
	s_waitcnt lgkmcnt(0)
	v_mfma_f32_16x16x32_bf16 v[86:89], v[114:117], v[106:109], v[86:89]
	v_mfma_f32_16x16x32_bf16 v[94:97], v[114:117], v[130:133], v[94:97]
	v_mfma_f32_16x16x32_bf16 v[98:101], v[114:117], v[146:149], v[98:101]
	ds_read_b128 v[106:109], v181 offset:384
	ds_read_b128 v[126:129], v181 offset:8832
	ds_read_b128 v[130:133], v181 offset:17280
	ds_read_b128 v[146:149], v181 offset:25728
	v_mfma_f32_16x16x32_bf16 v[90:93], v[114:117], v[154:157], v[90:93]
	s_waitcnt lgkmcnt(3)
	v_mfma_f32_16x16x32_bf16 v[102:105], v[118:121], v[106:109], v[102:105]
	s_waitcnt lgkmcnt(2)
	v_mfma_f32_16x16x32_bf16 v[110:113], v[118:121], v[126:129], v[110:113]
	s_waitcnt lgkmcnt(1)
	v_mfma_f32_16x16x32_bf16 v[114:117], v[118:121], v[130:133], v[122:125]
	s_waitcnt lgkmcnt(0)
	v_mfma_f32_16x16x32_bf16 v[82:85], v[118:121], v[146:149], v[82:85]
	ds_read_b128 v[118:121], v182
	s_waitcnt lgkmcnt(0)
	v_mfma_f32_16x16x32_bf16 v[86:89], v[118:121], v[106:109], v[86:89]
	v_mfma_f32_16x16x32_bf16 v[94:97], v[118:121], v[126:129], v[94:97]
	v_mfma_f32_16x16x32_bf16 v[98:101], v[118:121], v[130:133], v[98:101]
	ds_read_b128 v[106:109], v181 offset:416
	ds_read_b128 v[122:125], v181 offset:8864
	ds_read_b128 v[126:129], v181 offset:17312
	ds_read_b128 v[130:133], v181 offset:25760
	v_mfma_f32_16x16x32_bf16 v[90:93], v[118:121], v[146:149], v[90:93]
	s_waitcnt lgkmcnt(1)
	v_mfma_f32_16x16x32_bf16 v[150:153], v[134:137], v[126:129], v[114:117]
	s_nop 2
	ds_read_b128 v[114:117], v183
	v_mfma_f32_16x16x32_bf16 v[118:121], v[134:137], v[106:109], v[102:105]
	v_mfma_f32_16x16x32_bf16 v[146:149], v[134:137], v[122:125], v[110:113]
	s_waitcnt lgkmcnt(0)
	v_mfma_f32_16x16x32_bf16 v[110:113], v[114:117], v[106:109], v[86:89]
	v_mfma_f32_16x16x32_bf16 v[106:109], v[114:117], v[122:125], v[94:97]
	v_mfma_f32_16x16x32_bf16 v[102:105], v[114:117], v[126:129], v[98:101]
	s_nop 0
	ds_read_b128 v[86:89], v181 offset:448
	ds_read_b128 v[94:97], v181 offset:8896
	ds_read_b128 v[98:101], v181 offset:17344
	ds_read_b128 v[122:125], v181 offset:25792
	v_mfma_f32_16x16x32_bf16 v[114:117], v[114:117], v[130:133], v[90:93]
	v_mfma_f32_16x16x32_bf16 v[82:85], v[134:137], v[130:133], v[82:85]
	s_waitcnt lgkmcnt(3)
	v_mfma_f32_16x16x32_bf16 v[86:89], v[138:141], v[86:89], v[118:121]
	s_waitcnt lgkmcnt(2)
	v_mfma_f32_16x16x32_bf16 v[90:93], v[138:141], v[94:97], v[146:149]
	s_waitcnt lgkmcnt(1)
	v_mfma_f32_16x16x32_bf16 v[94:97], v[138:141], v[98:101], v[150:153]
	ds_read_b128 v[98:101], v181 offset:480
	ds_read_b128 v[118:121], v181 offset:8928
	ds_read_b128 v[126:129], v181 offset:17376
	ds_read_b128 v[130:133], v181 offset:25824
	s_waitcnt lgkmcnt(4)
	v_mfma_f32_16x16x32_bf16 v[82:85], v[138:141], v[122:125], v[82:85]
	s_waitcnt lgkmcnt(3)
	v_mfma_f32_16x16x32_bf16 v[162:165], v[142:145], v[98:101], v[86:89]
	s_waitcnt lgkmcnt(2)
	v_mfma_f32_16x16x32_bf16 v[158:161], v[142:145], v[118:121], v[90:93]
	s_waitcnt lgkmcnt(1)
	v_mfma_f32_16x16x32_bf16 v[154:157], v[142:145], v[126:129], v[94:97]
	s_waitcnt lgkmcnt(0)
	v_mfma_f32_16x16x32_bf16 v[150:153], v[142:145], v[130:133], v[82:85]

; #define LAS __attribute__((address_space(3)))
; template <int H2>
; DEV void s5_p1_all(LAS char* shm, int wid, int fr, int fq, bf16x8 (&wfr)[8], const bf16_t* wsp, f32x4 (&acc)[4][4], f32x4 (&sac)[4]) {
;     ...
;     for (int sp = 0; sp < 16; ++sp) {
;         bf16x8 bn[4], kf[4];
; #pragma unroll
;         for (int q = 0; q < 4; ++q) if (q >= S5_Q0(sp)) kf[q] = *(const LAS bf16x8*)(kb + (8 * q - 2 * sp + 30) * 512);
; #pragma unroll
;         for (int nt = 0; nt < 4; ++nt) bn[nt] = bu[nt];
;         if (sp < 15) {
; #pragma unroll
;             for (int nt = 0; nt < 4; ++nt) bn[nt] = *(const LAS bf16x8*)(ub + nt * 16 * 528 + (sp + 1) * 32);
;         }
; #pragma unroll
;         for (int nt = 0; nt < 4; ++nt) sac[nt] = __builtin_amdgcn_mfma_f32_16x16x32_bf16(wfr[sp & 7], bu[nt], sac[nt], 0, 0, 0);
;         if (sp < 8) wfr[sp & 7] = *(const bf16x8*)(wsp + (size_t)(sp + 8) * 64 * 8);
; #pragma unroll
;         for (int q = 0; q < 4; ++q) {
;             if (q >= S5_Q0(sp)) {
; #pragma unroll
;                 for (int nt = 0; nt < 4; ++nt) acc[q][nt] = __builtin_amdgcn_mfma_f32_16x16x32_bf16(kf[q], bu[nt], acc[q][nt], 0, 0, 0);
;             }
;         }
; #pragma unroll
;         for (int nt = 0; nt < 4; ++nt) bu[nt] = bn[nt];
;         __builtin_amdgcn_sched_barrier(0);
;     }
.LBB0_298:
	s_and_b64 vcc, exec, s[0:1]
	s_cbranch_vccz .LBB0_300
	v_xor_b32_e32 v1, 0x200, v178
	s_lshl_b32 s0, s45, 9
	v_add3_u32 v1, s31, v1, v170
	v_add_co_u32_e32 v138, vcc, s34, v168
	v_add3_u32 v0, v179, v176, v180
	v_add3_u32 v1, v1, v177, s0
	v_addc_co_u32_e32 v139, vcc, 0, v169, vcc
	ds_read_b128 v[50:53], v0
	ds_read_b128 v[54:57], v0 offset:8448
	ds_read_b128 v[58:61], v0 offset:32
	ds_read_b128 v[66:69], v0 offset:16896
	ds_read_b128 v[70:73], v0 offset:8480
	ds_read_b128 v[78:81], v0 offset:25344
	s_waitcnt vmcnt(0)
	ds_read_b128 v[82:85], v0 offset:16928
	ds_read_b128 v[90:93], v0 offset:25376
	ds_read_b128 v[2:5], v1
	ds_read_b128 v[94:97], v1 offset:4096
	ds_read_b128 v[110:113], v1 offset:8192
	ds_read_b128 v[114:117], v1 offset:12288
	global_load_dwordx4 v[130:133], v[138:139], off
	s_waitcnt lgkmcnt(0)
	v_mfma_f32_16x16x32_bf16 v[62:65], v[46:49], v[50:53], 0
	v_mfma_f32_16x16x32_bf16 v[74:77], v[46:49], v[54:57], 0
	v_mfma_f32_16x16x32_bf16 v[86:89], v[46:49], v[66:69], 0
	v_mfma_f32_16x16x32_bf16 v[46:49], v[46:49], v[78:81], 0
	v_mfma_f32_16x16x32_bf16 v[14:17], v[2:5], v[50:53], 0
	v_mfma_f32_16x16x32_bf16 v[10:13], v[2:5], v[54:57], 0
	v_mfma_f32_16x16x32_bf16 v[6:9], v[2:5], v[66:69], 0
	v_mfma_f32_16x16x32_bf16 v[2:5], v[2:5], v[78:81], 0
	v_mfma_f32_16x16x32_bf16 v[98:101], v[94:97], v[50:53], 0
	v_mfma_f32_16x16x32_bf16 v[102:105], v[94:97], v[54:57], 0
	v_mfma_f32_16x16x32_bf16 v[106:109], v[94:97], v[66:69], 0
	v_mfma_f32_16x16x32_bf16 v[94:97], v[94:97], v[78:81], 0
	v_mfma_f32_16x16x32_bf16 v[118:121], v[110:113], v[50:53], 0
	v_mfma_f32_16x16x32_bf16 v[122:125], v[110:113], v[54:57], 0
	v_mfma_f32_16x16x32_bf16 v[126:129], v[110:113], v[66:69], 0
	v_mfma_f32_16x16x32_bf16 v[110:113], v[110:113], v[78:81], 0
	v_mfma_f32_16x16x32_bf16 v[50:53], v[114:117], v[50:53], 0
	v_mfma_f32_16x16x32_bf16 v[54:57], v[114:117], v[54:57], 0
	v_mfma_f32_16x16x32_bf16 v[66:69], v[114:117], v[66:69], 0
	v_mfma_f32_16x16x32_bf16 v[78:81], v[114:117], v[78:81], 0
	v_mfma_f32_16x16x32_bf16 v[62:65], v[42:45], v[58:61], v[62:65]
	v_mfma_f32_16x16x32_bf16 v[74:77], v[42:45], v[70:73], v[74:77]
	v_mfma_f32_16x16x32_bf16 v[86:89], v[42:45], v[82:85], v[86:89]
	v_mfma_f32_16x16x32_bf16 v[42:45], v[42:45], v[90:93], v[46:49]
	s_nop 2
	ds_read_b128 v[46:49], v1 offset:3072
	ds_read_b128 v[114:117], v1 offset:7168
	s_waitcnt lgkmcnt(0)
	v_mfma_f32_16x16x32_bf16 v[98:101], v[46:49], v[58:61], v[98:101]
	v_mfma_f32_16x16x32_bf16 v[102:105], v[46:49], v[70:73], v[102:105]
	v_mfma_f32_16x16x32_bf16 v[106:109], v[46:49], v[82:85], v[106:109]
	v_mfma_f32_16x16x32_bf16 v[46:49], v[46:49], v[90:93], v[94:97]
	v_mfma_f32_16x16x32_bf16 v[94:97], v[114:117], v[58:61], v[118:121]
	v_mfma_f32_16x16x32_bf16 v[118:121], v[114:117], v[70:73], v[122:125]
	v_mfma_f32_16x16x32_bf16 v[122:125], v[114:117], v[82:85], v[126:129]
	s_nop 2
	global_load_dwordx4 v[126:129], v[138:139], off offset:1024
	v_mfma_f32_16x16x32_bf16 v[110:113], v[114:117], v[90:93], v[110:113]
	ds_read_b128 v[114:117], v1 offset:11264
	s_waitcnt lgkmcnt(0)
	v_mfma_f32_16x16x32_bf16 v[50:53], v[114:117], v[58:61], v[50:53]
	v_mfma_f32_16x16x32_bf16 v[54:57], v[114:117], v[70:73], v[54:57]
	v_mfma_f32_16x16x32_bf16 v[58:61], v[114:117], v[82:85], v[66:69]
	s_nop 2
	ds_read_b128 v[66:69], v0 offset:64
	ds_read_b128 v[70:73], v0 offset:8512
	ds_read_b128 v[82:85], v0 offset:16960
	ds_read_b128 v[134:137], v0 offset:25408
	v_mfma_f32_16x16x32_bf16 v[78:81], v[114:117], v[90:93], v[78:81]
	s_waitcnt lgkmcnt(0)
	v_mfma_f32_16x16x32_bf16 v[62:65], v[38:41], v[66:69], v[62:65]
	v_mfma_f32_16x16x32_bf16 v[74:77], v[38:41], v[70:73], v[74:77]
	v_mfma_f32_16x16x32_bf16 v[86:89], v[38:41], v[82:85], v[86:89]
	v_mfma_f32_16x16x32_bf16 v[38:41], v[38:41], v[134:137], v[42:45]
	s_nop 2
	ds_read_b128 v[42:45], v1 offset:2048
	ds_read_b128 v[90:93], v1 offset:6144
	s_waitcnt lgkmcnt(0)
	v_mfma_f32_16x16x32_bf16 v[98:101], v[42:45], v[66:69], v[98:101]
	v_mfma_f32_16x16x32_bf16 v[102:105], v[42:45], v[70:73], v[102:105]
	v_mfma_f32_16x16x32_bf16 v[106:109], v[42:45], v[82:85], v[106:109]
	v_mfma_f32_16x16x32_bf16 v[42:45], v[42:45], v[134:137], v[46:49]
	v_mfma_f32_16x16x32_bf16 v[46:49], v[90:93], v[66:69], v[94:97]
	v_mfma_f32_16x16x32_bf16 v[94:97], v[90:93], v[70:73], v[118:121]
	s_nop 2
	global_load_dwordx4 v[118:121], v[138:139], off offset:2048
	v_mfma_f32_16x16x32_bf16 v[114:117], v[90:93], v[82:85], v[122:125]
	v_mfma_f32_16x16x32_bf16 v[90:93], v[90:93], v[134:137], v[110:113]
	s_nop 2
	ds_read_b128 v[110:113], v1 offset:10240
	s_waitcnt lgkmcnt(0)
	v_mfma_f32_16x16x32_bf16 v[50:53], v[110:113], v[66:69], v[50:53]
	v_mfma_f32_16x16x32_bf16 v[54:57], v[110:113], v[70:73], v[54:57]
	v_mfma_f32_16x16x32_bf16 v[58:61], v[110:113], v[82:85], v[58:61]
	ds_read_b128 v[66:69], v0 offset:96
	ds_read_b128 v[70:73], v0 offset:8544
	ds_read_b128 v[82:85], v0 offset:16992
	ds_read_b128 v[122:125], v0 offset:25440
	v_mfma_f32_16x16x32_bf16 v[78:81], v[110:113], v[134:137], v[78:81]
	s_waitcnt lgkmcnt(0)
	v_mfma_f32_16x16x32_bf16 v[62:65], v[34:37], v[66:69], v[62:65]
	v_mfma_f32_16x16x32_bf16 v[74:77], v[34:37], v[70:73], v[74:77]
	v_mfma_f32_16x16x32_bf16 v[86:89], v[34:37], v[82:85], v[86:89]
	v_mfma_f32_16x16x32_bf16 v[34:37], v[34:37], v[122:125], v[38:41]
	s_nop 2
	ds_read_b128 v[38:41], v1 offset:1024
	ds_read_b128 v[110:113], v1 offset:5120
	s_waitcnt lgkmcnt(0)
; #define LAS __attribute__((address_space(3)))
; template <int H2>
; DEV void s5_p1_all(LAS char* shm, int wid, int fr, int fq, bf16x8 (&wfr)[8], const bf16_t* wsp, f32x4 (&acc)[4][4], f32x4 (&sac)[4]) {
;     ...
;     for (int sp = 0; sp < 16; ++sp) {
;         bf16x8 bn[4], kf[4];
; #pragma unroll
;         for (int q = 0; q < 4; ++q) if (q >= S5_Q0(sp)) kf[q] = *(const LAS bf16x8*)(kb + (8 * q - 2 * sp + 30) * 512);
; #pragma unroll
;         for (int nt = 0; nt < 4; ++nt) bn[nt] = bu[nt];
;         if (sp < 15) {
; #pragma unroll
;             for (int nt = 0; nt < 4; ++nt) bn[nt] = *(const LAS bf16x8*)(ub + nt * 16 * 528 + (sp + 1) * 32);
;         }
; #pragma unroll
;         for (int nt = 0; nt < 4; ++nt) sac[nt] = __builtin_amdgcn_mfma_f32_16x16x32_bf16(wfr[sp & 7], bu[nt], sac[nt], 0, 0, 0);
;         if (sp < 8) wfr[sp & 7] = *(const bf16x8*)(wsp + (size_t)(sp + 8) * 64 * 8);
; #pragma unroll
;         for (int q = 0; q < 4; ++q) {
;             if (q >= S5_Q0(sp)) {
; #pragma unroll
;                 for (int nt = 0; nt < 4; ++nt) acc[q][nt] = __builtin_amdgcn_mfma_f32_16x16x32_bf16(kf[q], bu[nt], acc[q][nt], 0, 0, 0);
;             }
;         }
; #pragma unroll
;         for (int nt = 0; nt < 4; ++nt) bu[nt] = bn[nt];
;         __builtin_amdgcn_sched_barrier(0);
;     }
	v_mfma_f32_16x16x32_bf16 v[98:101], v[38:41], v[66:69], v[98:101]
	v_mfma_f32_16x16x32_bf16 v[102:105], v[38:41], v[70:73], v[102:105]
	v_mfma_f32_16x16x32_bf16 v[106:109], v[38:41], v[82:85], v[106:109]
	v_mfma_f32_16x16x32_bf16 v[38:41], v[38:41], v[122:125], v[42:45]
	v_mfma_f32_16x16x32_bf16 v[42:45], v[110:113], v[66:69], v[46:49]
	v_mfma_f32_16x16x32_bf16 v[46:49], v[110:113], v[70:73], v[94:97]
	v_mfma_f32_16x16x32_bf16 v[94:97], v[110:113], v[82:85], v[114:117]
	s_nop 2
	global_load_dwordx4 v[114:117], v[138:139], off offset:3072
	v_mfma_f32_16x16x32_bf16 v[90:93], v[110:113], v[122:125], v[90:93]
	ds_read_b128 v[110:113], v1 offset:9216
	ds_read_b128 v[134:137], v0 offset:128
	ds_read_b128 v[138:141], v0 offset:8576
	ds_read_b128 v[142:145], v0 offset:17024
	ds_read_b128 v[146:149], v0 offset:25472
	s_waitcnt lgkmcnt(0)
	v_mfma_f32_16x16x32_bf16 v[66:69], v[110:113], v[66:69], v[50:53]
	v_mfma_f32_16x16x32_bf16 v[70:73], v[110:113], v[70:73], v[54:57]
	v_mfma_f32_16x16x32_bf16 v[78:81], v[110:113], v[122:125], v[78:81]
	v_mfma_f32_16x16x32_bf16 v[82:85], v[110:113], v[82:85], v[58:61]
	v_mfma_f32_16x16x32_bf16 v[110:113], v[30:33], v[134:137], v[62:65]
	v_add_co_u32_e32 v150, vcc, s38, v168
	v_mfma_f32_16x16x32_bf16 v[74:77], v[30:33], v[138:141], v[74:77]
	s_nop 0
	v_addc_co_u32_e32 v151, vcc, 0, v169, vcc
	v_mfma_f32_16x16x32_bf16 v[86:89], v[30:33], v[142:145], v[86:89]
	v_mfma_f32_16x16x32_bf16 v[30:33], v[30:33], v[146:149], v[34:37]
	s_nop 2
	ds_read_b128 v[34:37], v1
	ds_read_b128 v[122:125], v1 offset:4096
	s_waitcnt lgkmcnt(0)
	v_mfma_f32_16x16x32_bf16 v[62:65], v[34:37], v[134:137], v[98:101]
	v_mfma_f32_16x16x32_bf16 v[58:61], v[34:37], v[138:141], v[102:105]
	v_mfma_f32_16x16x32_bf16 v[54:57], v[34:37], v[142:145], v[106:109]
	v_mfma_f32_16x16x32_bf16 v[50:53], v[34:37], v[146:149], v[38:41]
	v_mfma_f32_16x16x32_bf16 v[34:37], v[122:125], v[134:137], v[42:45]
	v_mfma_f32_16x16x32_bf16 v[42:45], v[122:125], v[142:145], v[94:97]
	s_nop 2
	global_load_dwordx4 v[94:97], v[150:151], off
	v_mfma_f32_16x16x32_bf16 v[38:41], v[122:125], v[138:141], v[46:49]
	v_mfma_f32_16x16x32_bf16 v[46:49], v[122:125], v[146:149], v[90:93]
	s_nop 2
	ds_read_b128 v[90:93], v1 offset:8192
	ds_read_b128 v[98:101], v0 offset:160
	ds_read_b128 v[102:105], v0 offset:8608
	ds_read_b128 v[106:109], v0 offset:17056
	ds_read_b128 v[122:125], v0 offset:25504
	s_waitcnt lgkmcnt(0)
	v_mfma_f32_16x16x32_bf16 v[66:69], v[90:93], v[134:137], v[66:69]
	v_mfma_f32_16x16x32_bf16 v[70:73], v[90:93], v[138:141], v[70:73]
	v_mfma_f32_16x16x32_bf16 v[78:81], v[90:93], v[146:149], v[78:81]
	v_mfma_f32_16x16x32_bf16 v[82:85], v[90:93], v[142:145], v[82:85]
	v_mfma_f32_16x16x32_bf16 v[90:93], v[26:29], v[98:101], v[110:113]
	v_mfma_f32_16x16x32_bf16 v[74:77], v[26:29], v[102:105], v[74:77]
	v_mfma_f32_16x16x32_bf16 v[86:89], v[26:29], v[106:109], v[86:89]
	v_mfma_f32_16x16x32_bf16 v[26:29], v[26:29], v[122:125], v[30:33]
	s_nop 2
	ds_read_b128 v[30:33], v1 offset:3072
	ds_read_b128 v[110:113], v1 offset:7168
	s_waitcnt lgkmcnt(0)
	v_mfma_f32_16x16x32_bf16 v[34:37], v[30:33], v[98:101], v[34:37]
	v_mfma_f32_16x16x32_bf16 v[38:41], v[30:33], v[102:105], v[38:41]
	v_mfma_f32_16x16x32_bf16 v[42:45], v[30:33], v[106:109], v[42:45]
	v_mfma_f32_16x16x32_bf16 v[30:33], v[30:33], v[122:125], v[46:49]
	v_mfma_f32_16x16x32_bf16 v[46:49], v[110:113], v[98:101], v[66:69]
	global_load_dwordx4 v[98:101], v[150:151], off offset:1024
	v_mfma_f32_16x16x32_bf16 v[66:69], v[110:113], v[102:105], v[70:73]
	v_mfma_f32_16x16x32_bf16 v[70:73], v[110:113], v[106:109], v[82:85]
	s_nop 2
	ds_read_b128 v[82:85], v0 offset:192
	ds_read_b128 v[102:105], v0 offset:8640
	ds_read_b128 v[106:109], v0 offset:17088
	ds_read_b128 v[134:137], v0 offset:25536
	v_mfma_f32_16x16x32_bf16 v[78:81], v[110:113], v[122:125], v[78:81]
	s_waitcnt lgkmcnt(0)
	v_mfma_f32_16x16x32_bf16 v[90:93], v[22:25], v[82:85], v[90:93]
	v_mfma_f32_16x16x32_bf16 v[74:77], v[22:25], v[102:105], v[74:77]
	v_mfma_f32_16x16x32_bf16 v[86:89], v[22:25], v[106:109], v[86:89]
	v_mfma_f32_16x16x32_bf16 v[22:25], v[22:25], v[134:137], v[26:29]
	s_nop 2
	ds_read_b128 v[26:29], v1 offset:2048
	ds_read_b128 v[110:113], v1 offset:6144
	s_waitcnt lgkmcnt(0)
	v_mfma_f32_16x16x32_bf16 v[34:37], v[26:29], v[82:85], v[34:37]
	v_mfma_f32_16x16x32_bf16 v[38:41], v[26:29], v[102:105], v[38:41]
	v_mfma_f32_16x16x32_bf16 v[42:45], v[26:29], v[106:109], v[42:45]
	v_mfma_f32_16x16x32_bf16 v[26:29], v[26:29], v[134:137], v[30:33]
	v_mfma_f32_16x16x32_bf16 v[30:33], v[110:113], v[82:85], v[46:49]
	global_load_dwordx4 v[82:85], v[150:151], off offset:2048
	v_mfma_f32_16x16x32_bf16 v[46:49], v[110:113], v[102:105], v[66:69]
	v_mfma_f32_16x16x32_bf16 v[66:69], v[110:113], v[106:109], v[70:73]
	s_nop 2
	ds_read_b128 v[70:73], v0 offset:224
	ds_read_b128 v[102:105], v0 offset:8672
	ds_read_b128 v[106:109], v0 offset:17120
	ds_read_b128 v[122:125], v0 offset:25568
	v_mfma_f32_16x16x32_bf16 v[78:81], v[110:113], v[134:137], v[78:81]
	s_waitcnt lgkmcnt(0)
	v_mfma_f32_16x16x32_bf16 v[90:93], v[18:21], v[70:73], v[90:93]
	v_mfma_f32_16x16x32_bf16 v[74:77], v[18:21], v[102:105], v[74:77]
	v_mfma_f32_16x16x32_bf16 v[86:89], v[18:21], v[106:109], v[86:89]
	v_mfma_f32_16x16x32_bf16 v[18:21], v[18:21], v[122:125], v[22:25]
	s_nop 2
	ds_read_b128 v[22:25], v1 offset:1024
	ds_read_b128 v[110:113], v1 offset:5120
	s_waitcnt lgkmcnt(0)
; #define LAS __attribute__((address_space(3)))
; template <int H2>
; DEV void s5_p1_all(LAS char* shm, int wid, int fr, int fq, bf16x8 (&wfr)[8], const bf16_t* wsp, f32x4 (&acc)[4][4], f32x4 (&sac)[4]) {
;     ...
;     for (int sp = 0; sp < 16; ++sp) {
;         bf16x8 bn[4], kf[4];
; #pragma unroll
;         for (int q = 0; q < 4; ++q) if (q >= S5_Q0(sp)) kf[q] = *(const LAS bf16x8*)(kb + (8 * q - 2 * sp + 30) * 512);
; #pragma unroll
;         for (int nt = 0; nt < 4; ++nt) bn[nt] = bu[nt];
;         if (sp < 15) {
; #pragma unroll
;             for (int nt = 0; nt < 4; ++nt) bn[nt] = *(const LAS bf16x8*)(ub + nt * 16 * 528 + (sp + 1) * 32);
;         }
; #pragma unroll
;         for (int nt = 0; nt < 4; ++nt) sac[nt] = __builtin_amdgcn_mfma_f32_16x16x32_bf16(wfr[sp & 7], bu[nt], sac[nt], 0, 0, 0);
;         if (sp < 8) wfr[sp & 7] = *(const bf16x8*)(wsp + (size_t)(sp + 8) * 64 * 8);
; #pragma unroll
;         for (int q = 0; q < 4; ++q) {
;             if (q >= S5_Q0(sp)) {
; #pragma unroll
;                 for (int nt = 0; nt < 4; ++nt) acc[q][nt] = __builtin_amdgcn_mfma_f32_16x16x32_bf16(kf[q], bu[nt], acc[q][nt], 0, 0, 0);
;             }
;         }
; #pragma unroll
;         for (int nt = 0; nt < 4; ++nt) bu[nt] = bn[nt];
;         __builtin_amdgcn_sched_barrier(0);
;     }
	v_mfma_f32_16x16x32_bf16 v[34:37], v[22:25], v[70:73], v[34:37]
	v_mfma_f32_16x16x32_bf16 v[38:41], v[22:25], v[102:105], v[38:41]
	v_mfma_f32_16x16x32_bf16 v[42:45], v[22:25], v[106:109], v[42:45]
	v_mfma_f32_16x16x32_bf16 v[22:25], v[22:25], v[122:125], v[26:29]
	v_mfma_f32_16x16x32_bf16 v[26:29], v[110:113], v[70:73], v[30:33]
	v_mfma_f32_16x16x32_bf16 v[30:33], v[110:113], v[102:105], v[46:49]
	s_nop 2
	global_load_dwordx4 v[46:49], v[150:151], off offset:3072
	v_mfma_f32_16x16x32_bf16 v[102:105], v[110:113], v[106:109], v[66:69]
	ds_read_b128 v[106:109], v0 offset:256
	ds_read_b128 v[134:137], v0 offset:8704
	ds_read_b128 v[138:141], v0 offset:17152
	ds_read_b128 v[142:145], v0 offset:25600
	v_mfma_f32_16x16x32_bf16 v[110:113], v[110:113], v[122:125], v[78:81]
	s_waitcnt vmcnt(0) lgkmcnt(0)
	v_mfma_f32_16x16x32_bf16 v[90:93], v[130:133], v[106:109], v[90:93]
	v_mfma_f32_16x16x32_bf16 v[122:125], v[130:133], v[134:137], v[74:77]
	v_mfma_f32_16x16x32_bf16 v[86:89], v[130:133], v[138:141], v[86:89]
	v_mfma_f32_16x16x32_bf16 v[18:21], v[130:133], v[142:145], v[18:21]
	ds_read_b128 v[66:69], v1
	ds_read_b128 v[130:133], v1 offset:4096
	s_waitcnt lgkmcnt(1)
	v_mfma_f32_16x16x32_bf16 v[78:81], v[66:69], v[106:109], v[34:37]
	v_mfma_f32_16x16x32_bf16 v[74:77], v[66:69], v[134:137], v[38:41]
	v_mfma_f32_16x16x32_bf16 v[70:73], v[66:69], v[138:141], v[42:45]
	v_mfma_f32_16x16x32_bf16 v[66:69], v[66:69], v[142:145], v[22:25]
	s_waitcnt lgkmcnt(0)
	v_mfma_f32_16x16x32_bf16 v[22:25], v[130:133], v[106:109], v[26:29]
	v_mfma_f32_16x16x32_bf16 v[26:29], v[130:133], v[134:137], v[30:33]
	v_mfma_f32_16x16x32_bf16 v[30:33], v[130:133], v[138:141], v[102:105]
	ds_read_b128 v[34:37], v0 offset:288
	ds_read_b128 v[38:41], v0 offset:8736
	ds_read_b128 v[42:45], v0 offset:17184
	ds_read_b128 v[102:105], v0 offset:25632
	v_mfma_f32_16x16x32_bf16 v[106:109], v[130:133], v[142:145], v[110:113]
	s_waitcnt lgkmcnt(2)
	v_mfma_f32_16x16x32_bf16 v[110:113], v[126:129], v[38:41], v[122:125]
	s_nop 2
	ds_read_b128 v[122:125], v1 offset:3072
	v_mfma_f32_16x16x32_bf16 v[90:93], v[126:129], v[34:37], v[90:93]
	s_waitcnt lgkmcnt(2)
	v_mfma_f32_16x16x32_bf16 v[86:89], v[126:129], v[42:45], v[86:89]
	s_waitcnt lgkmcnt(1)
	v_mfma_f32_16x16x32_bf16 v[18:21], v[126:129], v[102:105], v[18:21]
	s_waitcnt lgkmcnt(0)
	v_mfma_f32_16x16x32_bf16 v[22:25], v[122:125], v[34:37], v[22:25]
	v_mfma_f32_16x16x32_bf16 v[26:29], v[122:125], v[38:41], v[26:29]
	v_mfma_f32_16x16x32_bf16 v[30:33], v[122:125], v[42:45], v[30:33]
	ds_read_b128 v[34:37], v0 offset:320
	ds_read_b128 v[38:41], v0 offset:8768
	ds_read_b128 v[42:45], v0 offset:17216
	ds_read_b128 v[126:129], v0 offset:25664
	v_mfma_f32_16x16x32_bf16 v[102:105], v[122:125], v[102:105], v[106:109]
	s_waitcnt lgkmcnt(2)
	v_mfma_f32_16x16x32_bf16 v[106:109], v[118:121], v[38:41], v[110:113]
	s_nop 2
	ds_read_b128 v[110:113], v1 offset:2048
	v_mfma_f32_16x16x32_bf16 v[90:93], v[118:121], v[34:37], v[90:93]
	s_waitcnt lgkmcnt(2)
	v_mfma_f32_16x16x32_bf16 v[86:89], v[118:121], v[42:45], v[86:89]
	s_waitcnt lgkmcnt(1)
	v_mfma_f32_16x16x32_bf16 v[18:21], v[118:121], v[126:129], v[18:21]
	s_waitcnt lgkmcnt(0)
	v_mfma_f32_16x16x32_bf16 v[22:25], v[110:113], v[34:37], v[22:25]
	v_mfma_f32_16x16x32_bf16 v[26:29], v[110:113], v[38:41], v[26:29]
	v_mfma_f32_16x16x32_bf16 v[30:33], v[110:113], v[42:45], v[30:33]
	ds_read_b128 v[34:37], v0 offset:352
	ds_read_b128 v[38:41], v0 offset:8800
	ds_read_b128 v[42:45], v0 offset:17248
	ds_read_b128 v[118:121], v0 offset:25696
	v_mfma_f32_16x16x32_bf16 v[102:105], v[110:113], v[126:129], v[102:105]
	ds_read_b128 v[110:113], v1 offset:1024
	s_waitcnt lgkmcnt(4)
	v_mfma_f32_16x16x32_bf16 v[90:93], v[114:117], v[34:37], v[90:93]
	s_waitcnt lgkmcnt(3)
	v_mfma_f32_16x16x32_bf16 v[106:109], v[114:117], v[38:41], v[106:109]
	s_waitcnt lgkmcnt(2)
	v_mfma_f32_16x16x32_bf16 v[86:89], v[114:117], v[42:45], v[86:89]
	s_waitcnt lgkmcnt(1)
	v_mfma_f32_16x16x32_bf16 v[18:21], v[114:117], v[118:121], v[18:21]
	s_waitcnt lgkmcnt(0)
	v_mfma_f32_16x16x32_bf16 v[22:25], v[110:113], v[34:37], v[22:25]
	v_mfma_f32_16x16x32_bf16 v[26:29], v[110:113], v[38:41], v[26:29]
	v_mfma_f32_16x16x32_bf16 v[30:33], v[110:113], v[42:45], v[30:33]
	ds_read_b128 v[34:37], v0 offset:384
	ds_read_b128 v[38:41], v0 offset:8832
	ds_read_b128 v[42:45], v0 offset:17280
	ds_read_b128 v[114:117], v0 offset:25728
	v_mfma_f32_16x16x32_bf16 v[118:121], v[110:113], v[118:121], v[102:105]
	s_waitcnt lgkmcnt(3)
	v_mfma_f32_16x16x32_bf16 v[90:93], v[94:97], v[34:37], v[90:93]
	s_waitcnt lgkmcnt(2)
	v_mfma_f32_16x16x32_bf16 v[122:125], v[94:97], v[38:41], v[106:109]
	s_waitcnt lgkmcnt(1)
	v_mfma_f32_16x16x32_bf16 v[86:89], v[94:97], v[42:45], v[86:89]
	s_waitcnt lgkmcnt(0)
	v_mfma_f32_16x16x32_bf16 v[18:21], v[94:97], v[114:117], v[18:21]
	ds_read_b128 v[94:97], v1
	s_waitcnt lgkmcnt(0)
	v_mfma_f32_16x16x32_bf16 v[110:113], v[94:97], v[34:37], v[22:25]
	v_mfma_f32_16x16x32_bf16 v[106:109], v[94:97], v[38:41], v[26:29]
	v_mfma_f32_16x16x32_bf16 v[102:105], v[94:97], v[42:45], v[30:33]
	s_nop 0
	ds_read_b128 v[22:25], v0 offset:416
	ds_read_b128 v[26:29], v0 offset:8864
	ds_read_b128 v[30:33], v0 offset:17312
	ds_read_b128 v[34:37], v0 offset:25760
	v_mfma_f32_16x16x32_bf16 v[114:117], v[94:97], v[114:117], v[118:121]
	s_waitcnt lgkmcnt(3)
	v_mfma_f32_16x16x32_bf16 v[22:25], v[98:101], v[22:25], v[90:93]
	s_waitcnt lgkmcnt(1)
	v_mfma_f32_16x16x32_bf16 v[30:33], v[98:101], v[30:33], v[86:89]
	ds_read_b128 v[38:41], v0 offset:448
	ds_read_b128 v[42:45], v0 offset:8896
	s_nop 0
	ds_read_b128 v[86:89], v0 offset:17344
	ds_read_b128 v[90:93], v0 offset:25792
	v_mfma_f32_16x16x32_bf16 v[26:29], v[98:101], v[26:29], v[122:125]
	s_waitcnt lgkmcnt(4)
	v_mfma_f32_16x16x32_bf16 v[18:21], v[98:101], v[34:37], v[18:21]
	s_waitcnt lgkmcnt(3)
	v_mfma_f32_16x16x32_bf16 v[22:25], v[82:85], v[38:41], v[22:25]
	s_waitcnt lgkmcnt(2)
	v_mfma_f32_16x16x32_bf16 v[26:29], v[82:85], v[42:45], v[26:29]
	s_waitcnt lgkmcnt(1)
	v_mfma_f32_16x16x32_bf16 v[30:33], v[82:85], v[86:89], v[30:33]
	ds_read_b128 v[34:37], v0 offset:480
	ds_read_b128 v[38:41], v0 offset:8928
	ds_read_b128 v[42:45], v0 offset:17376
	ds_read_b128 v[86:89], v0 offset:25824
	s_waitcnt lgkmcnt(4)
	v_mfma_f32_16x16x32_bf16 v[18:21], v[82:85], v[90:93], v[18:21]
	s_waitcnt lgkmcnt(3)
	v_mfma_f32_16x16x32_bf16 v[162:165], v[46:49], v[34:37], v[22:25]
	s_waitcnt lgkmcnt(2)
	v_mfma_f32_16x16x32_bf16 v[158:161], v[46:49], v[38:41], v[26:29]
	s_waitcnt lgkmcnt(1)
	v_mfma_f32_16x16x32_bf16 v[154:157], v[46:49], v[42:45], v[30:33]
	s_waitcnt lgkmcnt(0)
	v_mfma_f32_16x16x32_bf16 v[150:153], v[46:49], v[86:89], v[18:21]
	v_mov_b32_e32 v136, s0
	v_mov_b32_e32 v171, v176
; #define LAS __attribute__((address_space(3)))
; DEV void s5_phase(LAS char* shm, const bf16_t* Uin, bf16_t* Yout, const char* tab, const float* dskip) {
;     ...
;         const float2 al = AL[g * NP + lane];
;         const float4 dsk = *(const float4*)(dskip + g * GC + 4 * fq);
;         const bf16_t* vvp = VV + (size_t)g * V_G + ((size_t)(wid * 4) * 64 + lane) * 8; asm volatile("" : "+v"(vvp));
;         bf16x8 va[4][4];
; #pragma unroll
;         for (int q = 0; q < 4; ++q)
; #pragma unroll
;             for (int ks = 0; ks < 4; ++ks) va[q][ks] = *(const bf16x8*)(vvp + ((size_t)((8 * q) * 4 + ks) * 64) * 8);
; #pragma unroll
;         for (int nt = 0; nt < 4; ++nt) *(LAS f32x4*)(shm + SL + (16 * nt + fr) * SRS + (16 * wid + 4 * fq) * 4) = sac[nt];
;         __syncthreads();
;         {
;             float hr = 0.f, hi = 0.f, lr[8], li[8];
; #pragma unroll
;             for (int n = 0; n < 8; ++n) {
;                 lr[n] = hr; li[n] = hi;
;                 const float sr = *(const LAS float*)(shm + SL + (8 * wid + n) * SRS + lane * 4), si = *(const LAS float*)(shm + SL + (8 * wid + n) * SRS + (64 + lane) * 4);
;                 const float nr = al.x * hr - al.y * hi + sr, ni = al.x * hi + al.y * hr + si; hr = nr; hi = ni;
;             }
;             *(LAS float*)(shm + TSEG + (wid * 128 + lane) * 4) = hr; *(LAS float*)(shm + TSEG + (wid * 128 + 64 + lane) * 4) = hi;
;             float pr = al.x, pi = al.y;
; #pragma unroll
;             for (int e = 0; e < 3; ++e) { const float nr = pr * pr - pi * pi, ni = 2.f * pr * pi; pr = nr; pi = ni; }
;             __syncthreads();
;             float cr = 0.f, ci = 0.f;
;             for (int w2 = 0; w2 < wid; ++w2) {
;                 const float tr = *(const LAS float*)(shm + TSEG + (w2 * 128 + lane) * 4), ti = *(const LAS float*)(shm + TSEG + (w2 * 128 + 64 + lane) * 4);
;                 const float nr = pr * cr - pi * ci + tr, ni = pr * ci + pi * cr + ti; cr = nr; ci = ni;
;             }
.LBB0_300:
	s_lshl_b32 s0, s47, 6
	v_or_b32_e32 v0, s0, v173
	v_lshlrev_b32_e32 v0, 3, v0
	global_load_dwordx2 v[134:135], v0, s[4:5]
	s_add_u32 s0, s15, s0
	v_lshlrev_b32_e32 v168, 2, v173
	s_addc_u32 s1, s16, 0
	s_lshl_b32 s7, s7, 1
	v_and_b32_e32 v0, 48, v173
	s_mul_i32 s10, s45, 0x1080
	v_add_u32_e32 v1, s42, v168
	s_add_u32 s7, s25, s7
	v_add_u32_e32 v138, s10, v1
	global_load_dwordx4 v[18:21], v0, s[0:1]
	s_addc_u32 s10, s26, 0
	s_lshl_b32 s0, s45, 2
	s_ashr_i32 s1, s0, 31
	v_lshrrev_b32_e32 v143, 4, v173
	s_lshl_b64 s[0:1], s[0:1], 10
	v_lshlrev_b32_e32 v144, 2, v143
	s_add_u32 s0, s7, s0
	v_or_b32_e32 v22, s6, v144
	s_addc_u32 s1, s10, s1
	v_lshl_add_u32 v0, v22, 2, s42
	v_lshl_add_u64 v[22:23], s[0:1], 0, v[166:167]
	global_load_dwordx4 v[118:121], v[22:23], off
	global_load_dwordx4 v[86:89], v[22:23], off offset:1024
	global_load_dwordx4 v[46:49], v[22:23], off offset:2048
	global_load_dwordx4 v[34:37], v[22:23], off offset:3072
	v_add_co_u32_e32 v24, vcc, s39, v22
	s_lshl_b32 s7, s45, 3
	s_nop 0
	v_addc_co_u32_e32 v25, vcc, 0, v23, vcc
	v_add_co_u32_e32 v26, vcc, s40, v22
	s_or_b32 s0, s7, 1
	s_nop 0
	v_addc_co_u32_e32 v27, vcc, 0, v23, vcc
	v_add_co_u32_e32 v28, vcc, s41, v22
	v_or_b32_e32 v142, 16, v175
	s_nop 0
	v_addc_co_u32_e32 v29, vcc, 0, v23, vcc
	global_load_dwordx4 v[122:125], v[24:25], off
	global_load_dwordx4 v[90:93], v[24:25], off offset:1024
	s_waitcnt vmcnt(0)
	global_load_dwordx4 v[82:85], v[24:25], off offset:2048
	global_load_dwordx4 v[30:33], v[24:25], off offset:3072
	global_load_dwordx4 v[126:129], v[26:27], off
	global_load_dwordx4 v[94:97], v[26:27], off offset:1024
	global_load_dwordx4 v[42:45], v[26:27], off offset:2048
	s_nop 0
	global_load_dwordx4 v[22:25], v[26:27], off offset:3072
	global_load_dwordx4 v[130:133], v[28:29], off
	global_load_dwordx4 v[98:101], v[28:29], off offset:1024
	global_load_dwordx4 v[38:41], v[28:29], off offset:2048
	s_nop 0
	global_load_dwordx4 v[26:29], v[28:29], off offset:3072
	v_add_u32_e32 v139, v0, v171
	s_mul_i32 s1, s0, 0x210
	v_mad_u32_u24 v0, v142, s29, v0
	v_add_u32_e32 v1, s1, v1
	ds_write_b128 v139, v[162:165]
	ds_write_b128 v0, v[158:161]
	ds_write_b128 v0, v[154:157] offset:8448
	ds_write_b128 v0, v[150:153] offset:16896
	s_waitcnt lgkmcnt(0)
	s_barrier
	ds_read2st64_b32 v[138:139], v138 offset1:1
	ds_read2st64_b32 v[140:141], v1 offset1:1
	ds_read2_b32 v[146:147], v1 offset0:132 offset1:196
	v_add_u32_e32 v0, 32, v1
	ds_read2st64_b32 v[148:149], v0 offset0:4 offset1:5
	v_add_u32_e32 v136, 0, v136
	v_add_u32_e32 v136, v136, v168
	v_add_u32_e32 v136, 0x21200, v136
	v_mov_b32_e32 v137, 0
	s_cmp_lt_i32 s45, 1
	v_mul_f32_e32 v159, 0, v135
	v_fma_f32 v145, 0, v134, v159
	v_fma_f32 v0, v134, 0, -v159
	s_waitcnt lgkmcnt(0)
	v_add_f32_e32 v157, v145, v139
	v_add_f32_e32 v158, v0, v138
	v_mul_f32_e32 v0, v135, v157
	v_mul_f32_e32 v138, v134, v157
	v_fma_f32 v0, v134, v158, -v0
	v_fmac_f32_e32 v138, v135, v158
	v_add_f32_e32 v156, v140, v0
	v_add_f32_e32 v155, v141, v138
	v_mul_f32_e32 v138, v135, v156
	v_mul_f32_e32 v0, v135, v155
	v_fmac_f32_e32 v138, v134, v155
	v_fma_f32 v0, v134, v156, -v0
	v_add_f32_e32 v153, v147, v138
	v_add_f32_e32 v154, v146, v0
	v_mul_f32_e32 v0, v135, v153
	v_fma_f32 v0, v134, v154, -v0
	v_add_f32_e32 v151, v148, v0
	v_add_u32_e32 v0, 48, v1
	v_mul_f32_e32 v140, v135, v154
	ds_read2st64_b32 v[138:139], v0 offset0:6 offset1:7
	v_fmac_f32_e32 v140, v134, v153
	v_add_f32_e32 v152, v149, v140
	v_mul_f32_e32 v0, v135, v152
	v_fma_f32 v0, v134, v151, -v0
	s_waitcnt lgkmcnt(0)
	v_add_f32_e32 v149, v138, v0
	v_add_u32_e32 v138, 64, v1
	v_mul_f32_e32 v0, v135, v151
	ds_read2st64_b32 v[140:141], v138 offset0:8 offset1:9
	v_fmac_f32_e32 v0, v134, v152
	v_add_f32_e32 v150, v139, v0
	v_mul_f32_e32 v0, v135, v150
	v_fma_f32 v0, v134, v149, -v0
	v_add_u32_e32 v138, 0x50, v1
	s_waitcnt lgkmcnt(0)
	v_add_f32_e32 v147, v140, v0
	v_mul_f32_e32 v0, v135, v149
	ds_read2st64_b32 v[138:139], v138 offset0:10 offset1:11
	v_fmac_f32_e32 v0, v134, v150
	v_add_f32_e32 v148, v141, v0
	v_mul_f32_e32 v0, v135, v148
	v_fma_f32 v0, v134, v147, -v0
	v_add_u32_e32 v1, 0x60, v1
	s_waitcnt lgkmcnt(0)
	v_add_f32_e32 v145, v138, v0
	v_mul_f32_e32 v0, v135, v147
	ds_read2st64_b32 v[140:141], v1 offset0:12 offset1:13
	v_fmac_f32_e32 v0, v134, v148
	v_add_f32_e32 v146, v139, v0
	v_mul_f32_e32 v0, v135, v146
	v_mul_f32_e32 v1, v135, v145
	v_fma_f32 v0, v134, v145, -v0
	v_fmac_f32_e32 v1, v134, v146
	s_waitcnt lgkmcnt(0)
	v_add_f32_e32 v0, v140, v0
	v_add_f32_e32 v1, v141, v1
	ds_write2st64_b32 v136, v0, v1 offset1:1
	v_mov_b32_e32 v136, 0
	s_waitcnt lgkmcnt(0)
	s_barrier
	s_cbranch_scc1 .LBB0_287
	v_mul_f32_e32 v1, v135, v135
	v_add_f32_e32 v0, v134, v134
	v_fma_f32 v1, v134, v134, -v1
	v_mul_f32_e32 v0, v0, v135
	v_add_f32_e32 v136, v1, v1
	v_mul_f32_e32 v136, v0, v136
	v_mul_f32_e32 v0, v0, v0
	v_fma_f32 v0, v1, v1, -v0
	v_add_f32_e32 v1, v0, v0
	v_mul_f32_e32 v138, v136, v1
	v_mul_f32_e32 v1, v136, v136
	v_fma_f32 v140, v0, v0, -v1
	s_cmp_lt_u32 s45, 8
	v_mov_b32_e32 v141, v140
	s_cbranch_scc1 .LBB0_305
	s_add_i32 s7, 0, 0x21200
	v_mov_b32_e32 v136, 0
	s_and_b32 s1, s45, 0x7ffffff8
	v_mov_b32_e32 v139, v138
	v_add_u32_e32 v160, s7, v168
	s_mov_b32 s7, 0
	v_mov_b32_e32 v137, v136

; #define LAS __attribute__((address_space(3)))
; template <int H2>
; DEV void s5_p1_all(LAS char* shm, int wid, int fr, int fq, bf16x8 (&wfr)[8], const bf16_t* wsp, f32x4 (&acc)[4][4], f32x4 (&sac)[4]) {
;     ...
;     for (int sp = 0; sp < 16; ++sp) {
;         bf16x8 bn[4], kf[4];
; #pragma unroll
;         for (int q = 0; q < 4; ++q) if (q >= S5_Q0(sp)) kf[q] = *(const LAS bf16x8*)(kb + (8 * q - 2 * sp + 30) * 512);
; #pragma unroll
;         for (int nt = 0; nt < 4; ++nt) bn[nt] = bu[nt];
;         if (sp < 15) {
; #pragma unroll
;             for (int nt = 0; nt < 4; ++nt) bn[nt] = *(const LAS bf16x8*)(ub + nt * 16 * 528 + (sp + 1) * 32);
;         }
; #pragma unroll
;         for (int nt = 0; nt < 4; ++nt) sac[nt] = __builtin_amdgcn_mfma_f32_16x16x32_bf16(wfr[sp & 7], bu[nt], sac[nt], 0, 0, 0);
;         if (sp < 8) wfr[sp & 7] = *(const bf16x8*)(wsp + (size_t)(sp + 8) * 64 * 8);
; #pragma unroll
;         for (int q = 0; q < 4; ++q) {
;             if (q >= S5_Q0(sp)) {
; #pragma unroll
;                 for (int nt = 0; nt < 4; ++nt) acc[q][nt] = __builtin_amdgcn_mfma_f32_16x16x32_bf16(kf[q], bu[nt], acc[q][nt], 0, 0, 0);
;             }
;         }
; #pragma unroll
;         for (int nt = 0; nt < 4; ++nt) bu[nt] = bn[nt];
;         __builtin_amdgcn_sched_barrier(0);
;     }
.LBB0_308:
	s_cmp_eq_u32 s51, 2
	s_mov_b64 s[12:13], -1
	s_cbranch_scc0 .LBB0_310
	s_waitcnt lgkmcnt(0)
	v_mfma_f32_16x16x32_bf16 v[2:5], v[46:49], v[118:121], 0
	v_mfma_f32_16x16x32_bf16 v[6:9], v[46:49], v[126:129], 0
	v_mfma_f32_16x16x32_bf16 v[10:13], v[46:49], v[134:137], 0
	v_mfma_f32_16x16x32_bf16 v[14:17], v[46:49], v[138:141], 0
	v_mfma_f32_16x16x32_bf16 v[50:53], v[146:149], v[118:121], 0
	v_mfma_f32_16x16x32_bf16 v[54:57], v[146:149], v[126:129], 0
	v_mfma_f32_16x16x32_bf16 v[58:61], v[146:149], v[134:137], 0
	v_mfma_f32_16x16x32_bf16 v[62:65], v[146:149], v[138:141], 0
	v_mfma_f32_16x16x32_bf16 v[66:69], v[142:145], v[118:121], 0
	v_mfma_f32_16x16x32_bf16 v[70:73], v[142:145], v[126:129], 0
	v_mfma_f32_16x16x32_bf16 v[74:77], v[142:145], v[134:137], 0
	v_mfma_f32_16x16x32_bf16 v[78:81], v[142:145], v[138:141], 0
	v_mfma_f32_16x16x32_bf16 v[102:105], v[130:133], v[118:121], 0
	v_mfma_f32_16x16x32_bf16 v[106:109], v[130:133], v[126:129], 0
	v_mfma_f32_16x16x32_bf16 v[110:113], v[130:133], v[134:137], 0
	v_mfma_f32_16x16x32_bf16 v[114:117], v[130:133], v[138:141], 0
	v_mfma_f32_16x16x32_bf16 v[150:153], v[122:125], v[118:121], 0
	v_mfma_f32_16x16x32_bf16 v[154:157], v[122:125], v[126:129], 0
	v_mfma_f32_16x16x32_bf16 v[158:161], v[122:125], v[134:137], 0
	v_mfma_f32_16x16x32_bf16 v[162:165], v[122:125], v[138:141], 0
	v_add_u32_e32 v0, 0xfffffc00, v182
	ds_read_b128 v[184:187], v0
	ds_read_b128 v[188:191], v182 offset:11264
	v_add_co_u32_e32 v220, vcc, s34, v168
	v_mfma_f32_16x16x32_bf16 v[2:5], v[42:45], v[86:89], v[2:5]
	s_nop 0
	v_addc_co_u32_e32 v221, vcc, 0, v169, vcc
	s_waitcnt lgkmcnt(0)
	v_mfma_f32_16x16x32_bf16 v[50:53], v[184:187], v[86:89], v[50:53]
	v_mfma_f32_16x16x32_bf16 v[54:57], v[184:187], v[94:97], v[54:57]
	v_mfma_f32_16x16x32_bf16 v[58:61], v[184:187], v[98:101], v[58:61]
	v_mfma_f32_16x16x32_bf16 v[62:65], v[184:187], v[90:93], v[62:65]
	ds_read_b128 v[184:187], v182 offset:3072
	ds_read_b128 v[192:195], v182 offset:7168
	s_waitcnt lgkmcnt(0)
	v_mfma_f32_16x16x32_bf16 v[66:69], v[184:187], v[86:89], v[66:69]
	v_mfma_f32_16x16x32_bf16 v[70:73], v[184:187], v[94:97], v[70:73]
	v_mfma_f32_16x16x32_bf16 v[74:77], v[184:187], v[98:101], v[74:77]
	v_mfma_f32_16x16x32_bf16 v[78:81], v[184:187], v[90:93], v[78:81]
	global_load_dwordx4 v[184:187], v[220:221], off offset:1024
	v_mfma_f32_16x16x32_bf16 v[102:105], v[192:195], v[86:89], v[102:105]
	v_mfma_f32_16x16x32_bf16 v[106:109], v[192:195], v[94:97], v[106:109]
	v_mfma_f32_16x16x32_bf16 v[110:113], v[192:195], v[98:101], v[110:113]
	v_mfma_f32_16x16x32_bf16 v[114:117], v[192:195], v[90:93], v[114:117]
	ds_read_b128 v[192:195], v181 offset:64
	ds_read_b128 v[196:199], v181 offset:8512
	ds_read_b128 v[200:203], v181 offset:16960
	ds_read_b128 v[204:207], v181 offset:25408
	v_mfma_f32_16x16x32_bf16 v[6:9], v[42:45], v[94:97], v[6:9]
	v_mfma_f32_16x16x32_bf16 v[10:13], v[42:45], v[98:101], v[10:13]
	v_mfma_f32_16x16x32_bf16 v[14:17], v[42:45], v[90:93], v[14:17]
	v_mfma_f32_16x16x32_bf16 v[150:153], v[188:191], v[86:89], v[150:153]
	v_mfma_f32_16x16x32_bf16 v[154:157], v[188:191], v[94:97], v[154:157]
	v_mfma_f32_16x16x32_bf16 v[158:161], v[188:191], v[98:101], v[158:161]
	v_mfma_f32_16x16x32_bf16 v[162:165], v[188:191], v[90:93], v[162:165]
	v_add_u32_e32 v1, 0xfffff800, v182
	s_waitcnt lgkmcnt(0)
	v_mfma_f32_16x16x32_bf16 v[188:191], v[38:41], v[192:195], v[2:5]
	s_nop 2
	ds_read_b128 v[2:5], v1
	v_mfma_f32_16x16x32_bf16 v[212:215], v[38:41], v[200:203], v[10:13]
	v_mfma_f32_16x16x32_bf16 v[216:219], v[38:41], v[204:207], v[14:17]
	s_waitcnt lgkmcnt(0)
	v_mfma_f32_16x16x32_bf16 v[14:17], v[2:5], v[192:195], v[50:53]
	v_mfma_f32_16x16x32_bf16 v[10:13], v[2:5], v[196:199], v[54:57]
	s_nop 1
	ds_read_b128 v[50:53], v182 offset:2048
	ds_read_b128 v[54:57], v182 offset:6144
	v_mfma_f32_16x16x32_bf16 v[208:211], v[38:41], v[196:199], v[6:9]
	v_mfma_f32_16x16x32_bf16 v[6:9], v[2:5], v[200:203], v[58:61]
	v_mfma_f32_16x16x32_bf16 v[2:5], v[2:5], v[204:207], v[62:65]
	s_waitcnt lgkmcnt(0)
	v_mfma_f32_16x16x32_bf16 v[58:61], v[50:53], v[192:195], v[66:69]
	v_mfma_f32_16x16x32_bf16 v[62:65], v[50:53], v[196:199], v[70:73]
	v_mfma_f32_16x16x32_bf16 v[66:69], v[50:53], v[200:203], v[74:77]
	v_mfma_f32_16x16x32_bf16 v[50:53], v[50:53], v[204:207], v[78:81]
	v_mfma_f32_16x16x32_bf16 v[70:73], v[54:57], v[192:195], v[102:105]
	v_mfma_f32_16x16x32_bf16 v[74:77], v[54:57], v[196:199], v[106:109]
	s_nop 1
	ds_read_b128 v[102:105], v182 offset:10240
	v_mfma_f32_16x16x32_bf16 v[78:81], v[54:57], v[200:203], v[110:113]
	v_mfma_f32_16x16x32_bf16 v[54:57], v[54:57], v[204:207], v[114:117]
	s_nop 2
	global_load_dwordx4 v[114:117], v[220:221], off offset:2048
	s_waitcnt lgkmcnt(0)
	v_mfma_f32_16x16x32_bf16 v[106:109], v[102:105], v[192:195], v[150:153]
	v_mfma_f32_16x16x32_bf16 v[110:113], v[102:105], v[196:199], v[154:157]
	v_mfma_f32_16x16x32_bf16 v[150:153], v[102:105], v[200:203], v[158:161]
	s_nop 1
	ds_read_b128 v[154:157], v181 offset:96
	ds_read_b128 v[158:161], v181 offset:8544
	ds_read_b128 v[192:195], v181 offset:16992
	ds_read_b128 v[196:199], v181 offset:25440
	v_mfma_f32_16x16x32_bf16 v[102:105], v[102:105], v[204:207], v[162:165]
	s_waitcnt lgkmcnt(0)
	v_mfma_f32_16x16x32_bf16 v[162:165], v[34:37], v[154:157], v[188:191]
	v_mfma_f32_16x16x32_bf16 v[188:191], v[34:37], v[158:161], v[208:211]
	v_mfma_f32_16x16x32_bf16 v[200:203], v[34:37], v[192:195], v[212:215]
	s_nop 1
	ds_read_b128 v[208:211], v182 offset:1024
	ds_read_b128 v[212:215], v182 offset:5120
	s_waitcnt lgkmcnt(0)
; #define LAS __attribute__((address_space(3)))
; template <int H2>
; DEV void s5_p1_all(LAS char* shm, int wid, int fr, int fq, bf16x8 (&wfr)[8], const bf16_t* wsp, f32x4 (&acc)[4][4], f32x4 (&sac)[4]) {
;     ...
;     for (int sp = 0; sp < 16; ++sp) {
;         bf16x8 bn[4], kf[4];
; #pragma unroll
;         for (int q = 0; q < 4; ++q) if (q >= S5_Q0(sp)) kf[q] = *(const LAS bf16x8*)(kb + (8 * q - 2 * sp + 30) * 512);
; #pragma unroll
;         for (int nt = 0; nt < 4; ++nt) bn[nt] = bu[nt];
;         if (sp < 15) {
; #pragma unroll
;             for (int nt = 0; nt < 4; ++nt) bn[nt] = *(const LAS bf16x8*)(ub + nt * 16 * 528 + (sp + 1) * 32);
;         }
; #pragma unroll
;         for (int nt = 0; nt < 4; ++nt) sac[nt] = __builtin_amdgcn_mfma_f32_16x16x32_bf16(wfr[sp & 7], bu[nt], sac[nt], 0, 0, 0);
;         if (sp < 8) wfr[sp & 7] = *(const bf16x8*)(wsp + (size_t)(sp + 8) * 64 * 8);
; #pragma unroll
;         for (int q = 0; q < 4; ++q) {
;             if (q >= S5_Q0(sp)) {
; #pragma unroll
;                 for (int nt = 0; nt < 4; ++nt) acc[q][nt] = __builtin_amdgcn_mfma_f32_16x16x32_bf16(kf[q], bu[nt], acc[q][nt], 0, 0, 0);
;             }
;         }
; #pragma unroll
;         for (int nt = 0; nt < 4; ++nt) bu[nt] = bn[nt];
;         __builtin_amdgcn_sched_barrier(0);
;     }
	v_mfma_f32_16x16x32_bf16 v[58:61], v[208:211], v[154:157], v[58:61]
	v_mfma_f32_16x16x32_bf16 v[62:65], v[208:211], v[158:161], v[62:65]
	v_mfma_f32_16x16x32_bf16 v[66:69], v[208:211], v[192:195], v[66:69]
	v_mfma_f32_16x16x32_bf16 v[50:53], v[208:211], v[196:199], v[50:53]
	ds_read_b128 v[208:211], v182 offset:9216
	v_mfma_f32_16x16x32_bf16 v[70:73], v[212:215], v[154:157], v[70:73]
	s_waitcnt lgkmcnt(0)
	v_mfma_f32_16x16x32_bf16 v[106:109], v[208:211], v[154:157], v[106:109]
	global_load_dwordx4 v[154:157], v[220:221], off offset:3072
	v_mfma_f32_16x16x32_bf16 v[204:207], v[34:37], v[196:199], v[216:219]
	v_mfma_f32_16x16x32_bf16 v[74:77], v[212:215], v[158:161], v[74:77]
	v_mfma_f32_16x16x32_bf16 v[78:81], v[212:215], v[192:195], v[78:81]
	v_mfma_f32_16x16x32_bf16 v[54:57], v[212:215], v[196:199], v[54:57]
	v_mfma_f32_16x16x32_bf16 v[110:113], v[208:211], v[158:161], v[110:113]
	v_mfma_f32_16x16x32_bf16 v[150:153], v[208:211], v[192:195], v[150:153]
	ds_read_b128 v[158:161], v181 offset:128
	ds_read_b128 v[192:195], v181 offset:8576
	ds_read_b128 v[212:215], v181 offset:17024
	ds_read_b128 v[216:219], v181 offset:25472
	v_mfma_f32_16x16x32_bf16 v[102:105], v[208:211], v[196:199], v[102:105]
	s_waitcnt lgkmcnt(0)
	v_mfma_f32_16x16x32_bf16 v[196:199], v[30:33], v[212:215], v[200:203]
	v_add_co_u32_e32 v236, vcc, s38, v168
	v_mfma_f32_16x16x32_bf16 v[200:203], v[30:33], v[216:219], v[204:207]
	s_nop 2
	ds_read_b128 v[204:207], v182
	ds_read_b128 v[208:211], v182 offset:4096
	v_addc_co_u32_e32 v237, vcc, 0, v169, vcc
	s_waitcnt lgkmcnt(0)
	v_mfma_f32_16x16x32_bf16 v[58:61], v[204:207], v[158:161], v[58:61]
	v_mfma_f32_16x16x32_bf16 v[62:65], v[204:207], v[192:195], v[62:65]
	v_mfma_f32_16x16x32_bf16 v[66:69], v[204:207], v[212:215], v[66:69]
	v_mfma_f32_16x16x32_bf16 v[50:53], v[204:207], v[216:219], v[50:53]
	ds_read_b128 v[204:207], v182 offset:8192
	v_mfma_f32_16x16x32_bf16 v[162:165], v[30:33], v[158:161], v[162:165]
	v_mfma_f32_16x16x32_bf16 v[70:73], v[208:211], v[158:161], v[70:73]
	s_waitcnt lgkmcnt(0)
	v_mfma_f32_16x16x32_bf16 v[106:109], v[204:207], v[158:161], v[106:109]
	global_load_dwordx4 v[158:161], v[236:237], off
	v_mfma_f32_16x16x32_bf16 v[188:191], v[30:33], v[192:195], v[188:191]
	v_mfma_f32_16x16x32_bf16 v[74:77], v[208:211], v[192:195], v[74:77]
	v_mfma_f32_16x16x32_bf16 v[78:81], v[208:211], v[212:215], v[78:81]
	v_mfma_f32_16x16x32_bf16 v[54:57], v[208:211], v[216:219], v[54:57]
	v_mfma_f32_16x16x32_bf16 v[110:113], v[204:207], v[192:195], v[110:113]
	v_mfma_f32_16x16x32_bf16 v[150:153], v[204:207], v[212:215], v[150:153]
	ds_read_b128 v[192:195], v181 offset:160
	ds_read_b128 v[208:211], v181 offset:8608
	ds_read_b128 v[212:215], v181 offset:17056
	ds_read_b128 v[220:223], v181 offset:25504
	v_mfma_f32_16x16x32_bf16 v[102:105], v[204:207], v[216:219], v[102:105]
	ds_read_b128 v[204:207], v0
	s_waitcnt lgkmcnt(0)
	v_mfma_f32_16x16x32_bf16 v[162:165], v[26:29], v[192:195], v[162:165]
	v_mfma_f32_16x16x32_bf16 v[188:191], v[26:29], v[208:211], v[188:191]
	v_mfma_f32_16x16x32_bf16 v[58:61], v[204:207], v[192:195], v[58:61]
	v_mfma_f32_16x16x32_bf16 v[216:219], v[204:207], v[208:211], v[62:65]
	v_mfma_f32_16x16x32_bf16 v[66:69], v[204:207], v[212:215], v[66:69]
	v_mfma_f32_16x16x32_bf16 v[50:53], v[204:207], v[220:223], v[50:53]
	s_nop 0
	ds_read_b128 v[62:65], v182 offset:3072
	ds_read_b128 v[204:207], v182 offset:7168
	s_waitcnt lgkmcnt(0)
	v_mfma_f32_16x16x32_bf16 v[70:73], v[62:65], v[192:195], v[70:73]
	v_mfma_f32_16x16x32_bf16 v[106:109], v[204:207], v[192:195], v[106:109]
	global_load_dwordx4 v[192:195], v[236:237], off offset:1024
	v_mfma_f32_16x16x32_bf16 v[196:199], v[26:29], v[212:215], v[196:199]
	v_mfma_f32_16x16x32_bf16 v[74:77], v[62:65], v[208:211], v[74:77]
	v_mfma_f32_16x16x32_bf16 v[78:81], v[62:65], v[212:215], v[78:81]
	v_mfma_f32_16x16x32_bf16 v[110:113], v[204:207], v[208:211], v[110:113]
	v_mfma_f32_16x16x32_bf16 v[150:153], v[204:207], v[212:215], v[150:153]
	ds_read_b128 v[208:211], v181 offset:192
	ds_read_b128 v[212:215], v181 offset:8640
	ds_read_b128 v[228:231], v181 offset:17088
	ds_read_b128 v[232:235], v181 offset:25536
	v_mfma_f32_16x16x32_bf16 v[102:105], v[204:207], v[220:223], v[102:105]
	v_mfma_f32_16x16x32_bf16 v[200:203], v[26:29], v[220:223], v[200:203]
	v_mfma_f32_16x16x32_bf16 v[224:227], v[62:65], v[220:223], v[54:57]
	ds_read_b128 v[204:207], v1
	s_waitcnt lgkmcnt(0)
	v_mfma_f32_16x16x32_bf16 v[162:165], v[22:25], v[208:211], v[162:165]
	v_mfma_f32_16x16x32_bf16 v[188:191], v[22:25], v[212:215], v[188:191]
	v_mfma_f32_16x16x32_bf16 v[62:65], v[204:207], v[208:211], v[58:61]
	v_mfma_f32_16x16x32_bf16 v[58:61], v[204:207], v[212:215], v[216:219]
	v_mfma_f32_16x16x32_bf16 v[54:57], v[204:207], v[228:231], v[66:69]
	v_mfma_f32_16x16x32_bf16 v[50:53], v[204:207], v[232:235], v[50:53]
	s_nop 1
	ds_read_b128 v[66:69], v182 offset:2048
	ds_read_b128 v[204:207], v182 offset:6144
	s_waitcnt lgkmcnt(0)
	v_mfma_f32_16x16x32_bf16 v[70:73], v[66:69], v[208:211], v[70:73]
	v_mfma_f32_16x16x32_bf16 v[106:109], v[204:207], v[208:211], v[106:109]
	global_load_dwordx4 v[208:211], v[236:237], off offset:2048
	v_mfma_f32_16x16x32_bf16 v[74:77], v[66:69], v[212:215], v[74:77]
	v_mfma_f32_16x16x32_bf16 v[78:81], v[66:69], v[228:231], v[78:81]
	v_mfma_f32_16x16x32_bf16 v[66:69], v[66:69], v[232:235], v[224:227]
	v_mfma_f32_16x16x32_bf16 v[110:113], v[204:207], v[212:215], v[110:113]
	ds_read_b128 v[212:215], v181 offset:224
	ds_read_b128 v[216:219], v181 offset:8672
	ds_read_b128 v[220:223], v181 offset:17120
	ds_read_b128 v[224:227], v181 offset:25568
	v_mfma_f32_16x16x32_bf16 v[150:153], v[204:207], v[228:231], v[150:153]
	v_mfma_f32_16x16x32_bf16 v[102:105], v[204:207], v[232:235], v[102:105]
	v_mfma_f32_16x16x32_bf16 v[196:199], v[22:25], v[228:231], v[196:199]
	v_mfma_f32_16x16x32_bf16 v[200:203], v[22:25], v[232:235], v[200:203]
	ds_read_b128 v[204:207], v182 offset:1024
	ds_read_b128 v[228:231], v182 offset:5120
	s_waitcnt lgkmcnt(0)
; #define LAS __attribute__((address_space(3)))
; template <int H2>
; DEV void s5_p1_all(LAS char* shm, int wid, int fr, int fq, bf16x8 (&wfr)[8], const bf16_t* wsp, f32x4 (&acc)[4][4], f32x4 (&sac)[4]) {
;     ...
;     for (int sp = 0; sp < 16; ++sp) {
;         bf16x8 bn[4], kf[4];
; #pragma unroll
;         for (int q = 0; q < 4; ++q) if (q >= S5_Q0(sp)) kf[q] = *(const LAS bf16x8*)(kb + (8 * q - 2 * sp + 30) * 512);
; #pragma unroll
;         for (int nt = 0; nt < 4; ++nt) bn[nt] = bu[nt];
;         if (sp < 15) {
; #pragma unroll
;             for (int nt = 0; nt < 4; ++nt) bn[nt] = *(const LAS bf16x8*)(ub + nt * 16 * 528 + (sp + 1) * 32);
;         }
; #pragma unroll
;         for (int nt = 0; nt < 4; ++nt) sac[nt] = __builtin_amdgcn_mfma_f32_16x16x32_bf16(wfr[sp & 7], bu[nt], sac[nt], 0, 0, 0);
;         if (sp < 8) wfr[sp & 7] = *(const bf16x8*)(wsp + (size_t)(sp + 8) * 64 * 8);
; #pragma unroll
;         for (int q = 0; q < 4; ++q) {
;             if (q >= S5_Q0(sp)) {
; #pragma unroll
;                 for (int nt = 0; nt < 4; ++nt) acc[q][nt] = __builtin_amdgcn_mfma_f32_16x16x32_bf16(kf[q], bu[nt], acc[q][nt], 0, 0, 0);
;             }
;         }
; #pragma unroll
;         for (int nt = 0; nt < 4; ++nt) bu[nt] = bn[nt];
;         __builtin_amdgcn_sched_barrier(0);
;     }
	v_mfma_f32_16x16x32_bf16 v[162:165], v[18:21], v[212:215], v[162:165]
	v_mfma_f32_16x16x32_bf16 v[70:73], v[204:207], v[212:215], v[70:73]
	v_mfma_f32_16x16x32_bf16 v[74:77], v[204:207], v[216:219], v[74:77]
	v_mfma_f32_16x16x32_bf16 v[78:81], v[204:207], v[220:223], v[78:81]
	v_mfma_f32_16x16x32_bf16 v[66:69], v[204:207], v[224:227], v[66:69]
	global_load_dwordx4 v[204:207], v[236:237], off offset:3072
	v_mfma_f32_16x16x32_bf16 v[188:191], v[18:21], v[216:219], v[188:191]
	v_mfma_f32_16x16x32_bf16 v[196:199], v[18:21], v[220:223], v[196:199]
	v_mfma_f32_16x16x32_bf16 v[106:109], v[228:231], v[212:215], v[106:109]
	v_mfma_f32_16x16x32_bf16 v[110:113], v[228:231], v[216:219], v[110:113]
	v_mfma_f32_16x16x32_bf16 v[150:153], v[228:231], v[220:223], v[150:153]
	ds_read_b128 v[212:215], v181 offset:256
	ds_read_b128 v[216:219], v181 offset:8704
	ds_read_b128 v[220:223], v181 offset:17152
	ds_read_b128 v[232:235], v181 offset:25600
	v_mfma_f32_16x16x32_bf16 v[102:105], v[228:231], v[224:227], v[102:105]
	v_mfma_f32_16x16x32_bf16 v[200:203], v[18:21], v[224:227], v[200:203]
	ds_read_b128 v[224:227], v182
	ds_read_b128 v[228:231], v182 offset:4096
	s_waitcnt vmcnt(0) lgkmcnt(0)
	v_mfma_f32_16x16x32_bf16 v[162:165], v[82:85], v[212:215], v[162:165]
	v_mfma_f32_16x16x32_bf16 v[188:191], v[82:85], v[216:219], v[188:191]
	v_mfma_f32_16x16x32_bf16 v[196:199], v[82:85], v[220:223], v[196:199]
	v_mfma_f32_16x16x32_bf16 v[70:73], v[224:227], v[212:215], v[70:73]
	v_mfma_f32_16x16x32_bf16 v[74:77], v[224:227], v[216:219], v[74:77]
	v_mfma_f32_16x16x32_bf16 v[78:81], v[224:227], v[220:223], v[78:81]
	v_mfma_f32_16x16x32_bf16 v[66:69], v[224:227], v[232:235], v[66:69]
	v_mfma_f32_16x16x32_bf16 v[106:109], v[228:231], v[212:215], v[106:109]
	v_mfma_f32_16x16x32_bf16 v[110:113], v[228:231], v[216:219], v[110:113]
	v_mfma_f32_16x16x32_bf16 v[150:153], v[228:231], v[220:223], v[150:153]
	ds_read_b128 v[212:215], v181 offset:288
	ds_read_b128 v[216:219], v181 offset:8736
	ds_read_b128 v[220:223], v181 offset:17184
	ds_read_b128 v[224:227], v181 offset:25632
	v_mfma_f32_16x16x32_bf16 v[102:105], v[228:231], v[232:235], v[102:105]
	v_mfma_f32_16x16x32_bf16 v[200:203], v[82:85], v[232:235], v[200:203]
	s_waitcnt lgkmcnt(3)
	v_mfma_f32_16x16x32_bf16 v[162:165], v[184:187], v[212:215], v[162:165]
	s_waitcnt lgkmcnt(2)
	v_mfma_f32_16x16x32_bf16 v[188:191], v[184:187], v[216:219], v[188:191]
	s_waitcnt lgkmcnt(1)
	v_mfma_f32_16x16x32_bf16 v[196:199], v[184:187], v[220:223], v[196:199]
	s_waitcnt lgkmcnt(0)
	v_mfma_f32_16x16x32_bf16 v[184:187], v[184:187], v[224:227], v[200:203]
	s_nop 2
	ds_read_b128 v[200:203], v0
	ds_read_b128 v[228:231], v182 offset:3072
	s_waitcnt lgkmcnt(1)
	v_mfma_f32_16x16x32_bf16 v[70:73], v[200:203], v[212:215], v[70:73]
	v_mfma_f32_16x16x32_bf16 v[74:77], v[200:203], v[216:219], v[74:77]
	v_mfma_f32_16x16x32_bf16 v[232:235], v[200:203], v[220:223], v[78:81]
	v_mfma_f32_16x16x32_bf16 v[66:69], v[200:203], v[224:227], v[66:69]
	s_waitcnt lgkmcnt(0)
	v_mfma_f32_16x16x32_bf16 v[106:109], v[228:231], v[212:215], v[106:109]
	v_mfma_f32_16x16x32_bf16 v[110:113], v[228:231], v[216:219], v[110:113]
	v_mfma_f32_16x16x32_bf16 v[150:153], v[228:231], v[220:223], v[150:153]
	ds_read_b128 v[200:203], v181 offset:320
	ds_read_b128 v[212:215], v181 offset:8768
	ds_read_b128 v[216:219], v181 offset:17216
	ds_read_b128 v[220:223], v181 offset:25664
	v_mfma_f32_16x16x32_bf16 v[102:105], v[228:231], v[224:227], v[102:105]
	s_waitcnt lgkmcnt(3)
	v_mfma_f32_16x16x32_bf16 v[162:165], v[114:117], v[200:203], v[162:165]
	s_waitcnt lgkmcnt(2)
	v_mfma_f32_16x16x32_bf16 v[188:191], v[114:117], v[212:215], v[188:191]
	s_waitcnt lgkmcnt(1)
	v_mfma_f32_16x16x32_bf16 v[196:199], v[114:117], v[216:219], v[196:199]
	s_waitcnt lgkmcnt(0)
	v_mfma_f32_16x16x32_bf16 v[114:117], v[114:117], v[220:223], v[184:187]
	s_nop 2
	ds_read_b128 v[184:187], v1
	ds_read_b128 v[224:227], v182 offset:2048
	s_waitcnt lgkmcnt(1)
	v_mfma_f32_16x16x32_bf16 v[78:81], v[184:187], v[200:203], v[70:73]
	v_mfma_f32_16x16x32_bf16 v[74:77], v[184:187], v[212:215], v[74:77]
	v_mfma_f32_16x16x32_bf16 v[70:73], v[184:187], v[216:219], v[232:235]
	v_mfma_f32_16x16x32_bf16 v[66:69], v[184:187], v[220:223], v[66:69]
	s_waitcnt lgkmcnt(0)
; #define LAS __attribute__((address_space(3)))
; template <int H2>
; DEV void s5_p1_all(LAS char* shm, int wid, int fr, int fq, bf16x8 (&wfr)[8], const bf16_t* wsp, f32x4 (&acc)[4][4], f32x4 (&sac)[4]) {
;     ...
;     for (int sp = 0; sp < 16; ++sp) {
;         bf16x8 bn[4], kf[4];
; #pragma unroll
;         for (int q = 0; q < 4; ++q) if (q >= S5_Q0(sp)) kf[q] = *(const LAS bf16x8*)(kb + (8 * q - 2 * sp + 30) * 512);
; #pragma unroll
;         for (int nt = 0; nt < 4; ++nt) bn[nt] = bu[nt];
;         if (sp < 15) {
; #pragma unroll
;             for (int nt = 0; nt < 4; ++nt) bn[nt] = *(const LAS bf16x8*)(ub + nt * 16 * 528 + (sp + 1) * 32);
;         }
; #pragma unroll
;         for (int nt = 0; nt < 4; ++nt) sac[nt] = __builtin_amdgcn_mfma_f32_16x16x32_bf16(wfr[sp & 7], bu[nt], sac[nt], 0, 0, 0);
;         if (sp < 8) wfr[sp & 7] = *(const bf16x8*)(wsp + (size_t)(sp + 8) * 64 * 8);
; #pragma unroll
;         for (int q = 0; q < 4; ++q) {
;             if (q >= S5_Q0(sp)) {
; #pragma unroll
;                 for (int nt = 0; nt < 4; ++nt) acc[q][nt] = __builtin_amdgcn_mfma_f32_16x16x32_bf16(kf[q], bu[nt], acc[q][nt], 0, 0, 0);
;             }
;         }
; #pragma unroll
;         for (int nt = 0; nt < 4; ++nt) bu[nt] = bn[nt];
;         __builtin_amdgcn_sched_barrier(0);
;     }
	v_mfma_f32_16x16x32_bf16 v[106:109], v[224:227], v[200:203], v[106:109]
	v_mfma_f32_16x16x32_bf16 v[110:113], v[224:227], v[212:215], v[110:113]
	v_mfma_f32_16x16x32_bf16 v[150:153], v[224:227], v[216:219], v[150:153]
	ds_read_b128 v[184:187], v181 offset:352
	ds_read_b128 v[200:203], v181 offset:8800
	ds_read_b128 v[212:215], v181 offset:17248
	ds_read_b128 v[216:219], v181 offset:25696
	v_mfma_f32_16x16x32_bf16 v[102:105], v[224:227], v[220:223], v[102:105]
	s_waitcnt lgkmcnt(3)
	v_mfma_f32_16x16x32_bf16 v[162:165], v[154:157], v[184:187], v[162:165]
	s_waitcnt lgkmcnt(2)
	v_mfma_f32_16x16x32_bf16 v[188:191], v[154:157], v[200:203], v[188:191]
	s_waitcnt lgkmcnt(1)
	v_mfma_f32_16x16x32_bf16 v[196:199], v[154:157], v[212:215], v[196:199]
	s_waitcnt lgkmcnt(0)
	v_mfma_f32_16x16x32_bf16 v[114:117], v[154:157], v[216:219], v[114:117]
	ds_read_b128 v[154:157], v182 offset:1024
	s_waitcnt lgkmcnt(0)
	v_mfma_f32_16x16x32_bf16 v[106:109], v[154:157], v[184:187], v[106:109]
	v_mfma_f32_16x16x32_bf16 v[110:113], v[154:157], v[200:203], v[110:113]
	v_mfma_f32_16x16x32_bf16 v[150:153], v[154:157], v[212:215], v[150:153]
	ds_read_b128 v[184:187], v181 offset:384
	ds_read_b128 v[200:203], v181 offset:8832
	ds_read_b128 v[212:215], v181 offset:17280
	ds_read_b128 v[220:223], v181 offset:25728
	v_mfma_f32_16x16x32_bf16 v[102:105], v[154:157], v[216:219], v[102:105]
	s_waitcnt lgkmcnt(3)
	v_mfma_f32_16x16x32_bf16 v[154:157], v[158:161], v[184:187], v[162:165]
	s_waitcnt lgkmcnt(2)
	v_mfma_f32_16x16x32_bf16 v[162:165], v[158:161], v[200:203], v[188:191]
	s_waitcnt lgkmcnt(1)
	v_mfma_f32_16x16x32_bf16 v[188:191], v[158:161], v[212:215], v[196:199]
	s_waitcnt lgkmcnt(0)
	v_mfma_f32_16x16x32_bf16 v[114:117], v[158:161], v[220:223], v[114:117]
	ds_read_b128 v[158:161], v182
	s_waitcnt lgkmcnt(0)
	v_mfma_f32_16x16x32_bf16 v[106:109], v[158:161], v[184:187], v[106:109]
	v_mfma_f32_16x16x32_bf16 v[110:113], v[158:161], v[200:203], v[110:113]
	v_mfma_f32_16x16x32_bf16 v[150:153], v[158:161], v[212:215], v[150:153]
	ds_read_b128 v[184:187], v181 offset:416
	ds_read_b128 v[196:199], v181 offset:8864
	ds_read_b128 v[200:203], v181 offset:17312
	ds_read_b128 v[212:215], v181 offset:25760
	v_mfma_f32_16x16x32_bf16 v[102:105], v[158:161], v[220:223], v[102:105]
	s_waitcnt lgkmcnt(2)
	v_mfma_f32_16x16x32_bf16 v[158:161], v[192:195], v[196:199], v[162:165]
	s_waitcnt lgkmcnt(1)
	v_mfma_f32_16x16x32_bf16 v[162:165], v[192:195], v[200:203], v[188:191]
	s_nop 2
	ds_read_b128 v[188:191], v0
	v_mfma_f32_16x16x32_bf16 v[154:157], v[192:195], v[184:187], v[154:157]
	s_waitcnt lgkmcnt(1)
	v_mfma_f32_16x16x32_bf16 v[114:117], v[192:195], v[212:215], v[114:117]
	s_waitcnt lgkmcnt(0)
	v_mfma_f32_16x16x32_bf16 v[106:109], v[188:191], v[184:187], v[106:109]
	v_mfma_f32_16x16x32_bf16 v[184:187], v[188:191], v[196:199], v[110:113]
	v_mfma_f32_16x16x32_bf16 v[150:153], v[188:191], v[200:203], v[150:153]
	s_nop 1
	ds_read_b128 v[110:113], v181 offset:448
	ds_read_b128 v[192:195], v181 offset:8896
	ds_read_b128 v[196:199], v181 offset:17344
	ds_read_b128 v[200:203], v181 offset:25792
	v_mfma_f32_16x16x32_bf16 v[188:191], v[188:191], v[212:215], v[102:105]
	s_waitcnt lgkmcnt(3)
	v_mfma_f32_16x16x32_bf16 v[154:157], v[208:211], v[110:113], v[154:157]
	s_waitcnt lgkmcnt(2)
	v_mfma_f32_16x16x32_bf16 v[158:161], v[208:211], v[192:195], v[158:161]
	s_waitcnt lgkmcnt(1)
	v_mfma_f32_16x16x32_bf16 v[212:215], v[208:211], v[196:199], v[162:165]
	s_waitcnt lgkmcnt(0)
	v_mfma_f32_16x16x32_bf16 v[208:211], v[208:211], v[200:203], v[114:117]
	s_nop 2
	ds_read_b128 v[114:117], v1
	s_waitcnt lgkmcnt(0)
	v_mfma_f32_16x16x32_bf16 v[110:113], v[114:117], v[110:113], v[106:109]
	v_mfma_f32_16x16x32_bf16 v[106:109], v[114:117], v[192:195], v[184:187]
	v_mfma_f32_16x16x32_bf16 v[102:105], v[114:117], v[196:199], v[150:153]
	s_nop 2
	ds_read_b128 v[150:153], v181 offset:480
	ds_read_b128 v[184:187], v181 offset:8928
	ds_read_b128 v[192:195], v181 offset:17376
	ds_read_b128 v[196:199], v181 offset:25824
	v_mfma_f32_16x16x32_bf16 v[114:117], v[114:117], v[200:203], v[188:191]
	s_waitcnt lgkmcnt(3)
	v_mfma_f32_16x16x32_bf16 v[162:165], v[204:207], v[150:153], v[154:157]
	s_waitcnt lgkmcnt(2)
	v_mfma_f32_16x16x32_bf16 v[158:161], v[204:207], v[184:187], v[158:161]
	s_waitcnt lgkmcnt(1)
	v_mfma_f32_16x16x32_bf16 v[154:157], v[204:207], v[192:195], v[212:215]
	s_waitcnt lgkmcnt(0)
	v_mfma_f32_16x16x32_bf16 v[150:153], v[204:207], v[196:199], v[208:211]
	s_mov_b64 s[12:13], 0

; #define LAS __attribute__((address_space(3)))
; template <int H2>
; DEV void s5_p1_all(LAS char* shm, int wid, int fr, int fq, bf16x8 (&wfr)[8], const bf16_t* wsp, f32x4 (&acc)[4][4], f32x4 (&sac)[4]) {
;     ...
;     for (int sp = 0; sp < 16; ++sp) {
;         bf16x8 bn[4], kf[4];
; #pragma unroll
;         for (int q = 0; q < 4; ++q) if (q >= S5_Q0(sp)) kf[q] = *(const LAS bf16x8*)(kb + (8 * q - 2 * sp + 30) * 512);
; #pragma unroll
;         for (int nt = 0; nt < 4; ++nt) bn[nt] = bu[nt];
;         if (sp < 15) {
; #pragma unroll
;             for (int nt = 0; nt < 4; ++nt) bn[nt] = *(const LAS bf16x8*)(ub + nt * 16 * 528 + (sp + 1) * 32);
;         }
; #pragma unroll
;         for (int nt = 0; nt < 4; ++nt) sac[nt] = __builtin_amdgcn_mfma_f32_16x16x32_bf16(wfr[sp & 7], bu[nt], sac[nt], 0, 0, 0);
;         if (sp < 8) wfr[sp & 7] = *(const bf16x8*)(wsp + (size_t)(sp + 8) * 64 * 8);
; #pragma unroll
;         for (int q = 0; q < 4; ++q) {
;             if (q >= S5_Q0(sp)) {
; #pragma unroll
;                 for (int nt = 0; nt < 4; ++nt) acc[q][nt] = __builtin_amdgcn_mfma_f32_16x16x32_bf16(kf[q], bu[nt], acc[q][nt], 0, 0, 0);
;             }
;         }
; #pragma unroll
;         for (int nt = 0; nt < 4; ++nt) bu[nt] = bn[nt];
;         __builtin_amdgcn_sched_barrier(0);
;     }
.LBB0_312:
	s_waitcnt lgkmcnt(0)
	v_mfma_f32_16x16x32_bf16 v[2:5], v[46:49], v[118:121], 0
	v_mfma_f32_16x16x32_bf16 v[6:9], v[46:49], v[126:129], 0
	v_mfma_f32_16x16x32_bf16 v[10:13], v[46:49], v[134:137], 0
	v_mfma_f32_16x16x32_bf16 v[14:17], v[46:49], v[138:141], 0
	v_mfma_f32_16x16x32_bf16 v[50:53], v[146:149], v[118:121], 0
	v_mfma_f32_16x16x32_bf16 v[54:57], v[146:149], v[126:129], 0
	v_mfma_f32_16x16x32_bf16 v[58:61], v[146:149], v[134:137], 0
	v_mfma_f32_16x16x32_bf16 v[62:65], v[146:149], v[138:141], 0
	v_mfma_f32_16x16x32_bf16 v[66:69], v[142:145], v[118:121], 0
	v_mfma_f32_16x16x32_bf16 v[70:73], v[142:145], v[126:129], 0
	v_mfma_f32_16x16x32_bf16 v[74:77], v[142:145], v[134:137], 0
	v_mfma_f32_16x16x32_bf16 v[78:81], v[142:145], v[138:141], 0
	v_mfma_f32_16x16x32_bf16 v[102:105], v[130:133], v[118:121], 0
	v_mfma_f32_16x16x32_bf16 v[106:109], v[130:133], v[126:129], 0
	v_mfma_f32_16x16x32_bf16 v[110:113], v[130:133], v[134:137], 0
	v_mfma_f32_16x16x32_bf16 v[114:117], v[130:133], v[138:141], 0
	v_mfma_f32_16x16x32_bf16 v[150:153], v[122:125], v[118:121], 0
	v_mfma_f32_16x16x32_bf16 v[154:157], v[122:125], v[126:129], 0
	v_mfma_f32_16x16x32_bf16 v[158:161], v[122:125], v[134:137], 0
	v_mfma_f32_16x16x32_bf16 v[162:165], v[122:125], v[138:141], 0
	ds_read_b128 v[184:187], v183
	v_add_co_u32_e32 v224, vcc, s34, v168
	v_mfma_f32_16x16x32_bf16 v[2:5], v[42:45], v[86:89], v[2:5]
	s_nop 0
	v_addc_co_u32_e32 v225, vcc, 0, v169, vcc
	v_mfma_f32_16x16x32_bf16 v[6:9], v[42:45], v[94:97], v[6:9]
	s_waitcnt lgkmcnt(0)
	v_mfma_f32_16x16x32_bf16 v[50:53], v[184:187], v[86:89], v[50:53]
	v_mfma_f32_16x16x32_bf16 v[54:57], v[184:187], v[94:97], v[54:57]
	v_mfma_f32_16x16x32_bf16 v[58:61], v[184:187], v[98:101], v[58:61]
	v_mfma_f32_16x16x32_bf16 v[62:65], v[184:187], v[90:93], v[62:65]
	ds_read_b128 v[184:187], v182 offset:3072
	ds_read_b128 v[188:191], v182 offset:7168
	s_waitcnt lgkmcnt(0)
	v_mfma_f32_16x16x32_bf16 v[192:195], v[184:187], v[86:89], v[66:69]
	s_nop 2
	global_load_dwordx4 v[66:69], v[224:225], off offset:1024
	v_mfma_f32_16x16x32_bf16 v[70:73], v[184:187], v[94:97], v[70:73]
	v_mfma_f32_16x16x32_bf16 v[74:77], v[184:187], v[98:101], v[74:77]
	v_mfma_f32_16x16x32_bf16 v[78:81], v[184:187], v[90:93], v[78:81]
	ds_read_b128 v[184:187], v182 offset:11264
	v_mfma_f32_16x16x32_bf16 v[102:105], v[188:191], v[86:89], v[102:105]
	v_mfma_f32_16x16x32_bf16 v[106:109], v[188:191], v[94:97], v[106:109]
	v_mfma_f32_16x16x32_bf16 v[110:113], v[188:191], v[98:101], v[110:113]
	v_mfma_f32_16x16x32_bf16 v[114:117], v[188:191], v[90:93], v[114:117]
	ds_read_b128 v[188:191], v181 offset:64
	ds_read_b128 v[196:199], v181 offset:8512
	ds_read_b128 v[200:203], v181 offset:16960
	ds_read_b128 v[204:207], v181 offset:25408
	v_mfma_f32_16x16x32_bf16 v[10:13], v[42:45], v[98:101], v[10:13]
	v_mfma_f32_16x16x32_bf16 v[14:17], v[42:45], v[90:93], v[14:17]
	s_waitcnt lgkmcnt(0)
	v_mfma_f32_16x16x32_bf16 v[150:153], v[184:187], v[86:89], v[150:153]
	v_mfma_f32_16x16x32_bf16 v[154:157], v[184:187], v[94:97], v[154:157]
	v_mfma_f32_16x16x32_bf16 v[158:161], v[184:187], v[98:101], v[158:161]
	v_mfma_f32_16x16x32_bf16 v[162:165], v[184:187], v[90:93], v[162:165]
	v_add_u32_e32 v0, 0xfffff800, v182
	ds_read_b128 v[184:187], v0
	v_mfma_f32_16x16x32_bf16 v[2:5], v[38:41], v[188:191], v[2:5]
	v_mfma_f32_16x16x32_bf16 v[6:9], v[38:41], v[196:199], v[6:9]
	s_waitcnt lgkmcnt(0)
	v_mfma_f32_16x16x32_bf16 v[50:53], v[184:187], v[188:191], v[50:53]
	v_mfma_f32_16x16x32_bf16 v[54:57], v[184:187], v[196:199], v[54:57]
	v_mfma_f32_16x16x32_bf16 v[58:61], v[184:187], v[200:203], v[58:61]
	v_mfma_f32_16x16x32_bf16 v[62:65], v[184:187], v[204:207], v[62:65]
	ds_read_b128 v[184:187], v182 offset:2048
	ds_read_b128 v[208:211], v182 offset:6144
	s_waitcnt lgkmcnt(0)
	v_mfma_f32_16x16x32_bf16 v[192:195], v[184:187], v[188:191], v[192:195]
	v_mfma_f32_16x16x32_bf16 v[70:73], v[184:187], v[196:199], v[70:73]
	v_mfma_f32_16x16x32_bf16 v[74:77], v[184:187], v[200:203], v[74:77]
	v_mfma_f32_16x16x32_bf16 v[78:81], v[184:187], v[204:207], v[78:81]
	ds_read_b128 v[184:187], v182 offset:10240
	v_mfma_f32_16x16x32_bf16 v[102:105], v[208:211], v[188:191], v[102:105]
	s_waitcnt lgkmcnt(0)
	v_mfma_f32_16x16x32_bf16 v[150:153], v[184:187], v[188:191], v[150:153]
	global_load_dwordx4 v[188:191], v[224:225], off offset:2048
	v_mfma_f32_16x16x32_bf16 v[10:13], v[38:41], v[200:203], v[10:13]
	v_mfma_f32_16x16x32_bf16 v[106:109], v[208:211], v[196:199], v[106:109]
	v_mfma_f32_16x16x32_bf16 v[110:113], v[208:211], v[200:203], v[110:113]
	v_mfma_f32_16x16x32_bf16 v[114:117], v[208:211], v[204:207], v[114:117]
	v_mfma_f32_16x16x32_bf16 v[154:157], v[184:187], v[196:199], v[154:157]
	v_mfma_f32_16x16x32_bf16 v[158:161], v[184:187], v[200:203], v[158:161]
	ds_read_b128 v[196:199], v181 offset:96
	ds_read_b128 v[200:203], v181 offset:8544
	ds_read_b128 v[208:211], v181 offset:16992
	ds_read_b128 v[212:215], v181 offset:25440
	v_mfma_f32_16x16x32_bf16 v[14:17], v[38:41], v[204:207], v[14:17]
	v_mfma_f32_16x16x32_bf16 v[162:165], v[184:187], v[204:207], v[162:165]
	v_add_u32_e32 v1, 0xfffff400, v182
	s_waitcnt lgkmcnt(0)
	v_mfma_f32_16x16x32_bf16 v[184:187], v[34:37], v[196:199], v[2:5]
	s_nop 2
	ds_read_b128 v[2:5], v1
	v_mfma_f32_16x16x32_bf16 v[216:219], v[34:37], v[208:211], v[10:13]
	v_mfma_f32_16x16x32_bf16 v[220:223], v[34:37], v[212:215], v[14:17]
	s_waitcnt lgkmcnt(0)
	v_mfma_f32_16x16x32_bf16 v[14:17], v[2:5], v[196:199], v[50:53]
	v_mfma_f32_16x16x32_bf16 v[10:13], v[2:5], v[200:203], v[54:57]
	s_nop 1
	ds_read_b128 v[50:53], v182 offset:1024
	ds_read_b128 v[54:57], v182 offset:5120
	v_mfma_f32_16x16x32_bf16 v[204:207], v[34:37], v[200:203], v[6:9]
	v_mfma_f32_16x16x32_bf16 v[6:9], v[2:5], v[208:211], v[58:61]
	v_mfma_f32_16x16x32_bf16 v[2:5], v[2:5], v[212:215], v[62:65]
	s_waitcnt lgkmcnt(0)
; #define LAS __attribute__((address_space(3)))
; template <int H2>
; DEV void s5_p1_all(LAS char* shm, int wid, int fr, int fq, bf16x8 (&wfr)[8], const bf16_t* wsp, f32x4 (&acc)[4][4], f32x4 (&sac)[4]) {
;     ...
;     for (int sp = 0; sp < 16; ++sp) {
;         bf16x8 bn[4], kf[4];
; #pragma unroll
;         for (int q = 0; q < 4; ++q) if (q >= S5_Q0(sp)) kf[q] = *(const LAS bf16x8*)(kb + (8 * q - 2 * sp + 30) * 512);
; #pragma unroll
;         for (int nt = 0; nt < 4; ++nt) bn[nt] = bu[nt];
;         if (sp < 15) {
; #pragma unroll
;             for (int nt = 0; nt < 4; ++nt) bn[nt] = *(const LAS bf16x8*)(ub + nt * 16 * 528 + (sp + 1) * 32);
;         }
; #pragma unroll
;         for (int nt = 0; nt < 4; ++nt) sac[nt] = __builtin_amdgcn_mfma_f32_16x16x32_bf16(wfr[sp & 7], bu[nt], sac[nt], 0, 0, 0);
;         if (sp < 8) wfr[sp & 7] = *(const bf16x8*)(wsp + (size_t)(sp + 8) * 64 * 8);
; #pragma unroll
;         for (int q = 0; q < 4; ++q) {
;             if (q >= S5_Q0(sp)) {
; #pragma unroll
;                 for (int nt = 0; nt < 4; ++nt) acc[q][nt] = __builtin_amdgcn_mfma_f32_16x16x32_bf16(kf[q], bu[nt], acc[q][nt], 0, 0, 0);
;             }
;         }
; #pragma unroll
;         for (int nt = 0; nt < 4; ++nt) bu[nt] = bn[nt];
;         __builtin_amdgcn_sched_barrier(0);
;     }
	v_mfma_f32_16x16x32_bf16 v[58:61], v[50:53], v[196:199], v[192:195]
	v_mfma_f32_16x16x32_bf16 v[62:65], v[50:53], v[200:203], v[70:73]
	v_mfma_f32_16x16x32_bf16 v[70:73], v[50:53], v[208:211], v[74:77]
	v_mfma_f32_16x16x32_bf16 v[50:53], v[50:53], v[212:215], v[78:81]
	v_mfma_f32_16x16x32_bf16 v[78:81], v[54:57], v[200:203], v[106:109]
	s_nop 2
	ds_read_b128 v[106:109], v182 offset:9216
	v_mfma_f32_16x16x32_bf16 v[74:77], v[54:57], v[196:199], v[102:105]
	v_mfma_f32_16x16x32_bf16 v[102:105], v[54:57], v[208:211], v[110:113]
	s_waitcnt lgkmcnt(0)
	v_mfma_f32_16x16x32_bf16 v[110:113], v[106:109], v[196:199], v[150:153]
	s_nop 2
	global_load_dwordx4 v[150:153], v[224:225], off offset:3072
	v_mfma_f32_16x16x32_bf16 v[54:57], v[54:57], v[212:215], v[114:117]
	v_mfma_f32_16x16x32_bf16 v[114:117], v[106:109], v[200:203], v[154:157]
	v_mfma_f32_16x16x32_bf16 v[154:157], v[106:109], v[208:211], v[158:161]
	s_nop 2
	ds_read_b128 v[158:161], v181 offset:128
	ds_read_b128 v[192:195], v181 offset:8576
	ds_read_b128 v[196:199], v181 offset:17024
	ds_read_b128 v[200:203], v181 offset:25472
	v_mfma_f32_16x16x32_bf16 v[106:109], v[106:109], v[212:215], v[162:165]
	s_waitcnt lgkmcnt(0)
	v_mfma_f32_16x16x32_bf16 v[162:165], v[30:33], v[158:161], v[184:187]
	v_add_co_u32_e32 v240, vcc, s38, v168
	v_mfma_f32_16x16x32_bf16 v[184:187], v[30:33], v[192:195], v[204:207]
	s_nop 0
	v_addc_co_u32_e32 v241, vcc, 0, v169, vcc
	v_mfma_f32_16x16x32_bf16 v[204:207], v[30:33], v[196:199], v[216:219]
	ds_read_b128 v[212:215], v182
	s_nop 1
	ds_read_b128 v[216:219], v182 offset:4096
	s_waitcnt lgkmcnt(0)
	v_mfma_f32_16x16x32_bf16 v[58:61], v[212:215], v[158:161], v[58:61]
	v_mfma_f32_16x16x32_bf16 v[62:65], v[212:215], v[192:195], v[62:65]
	v_mfma_f32_16x16x32_bf16 v[70:73], v[212:215], v[196:199], v[70:73]
	v_mfma_f32_16x16x32_bf16 v[50:53], v[212:215], v[200:203], v[50:53]
	ds_read_b128 v[212:215], v182 offset:8192
	v_mfma_f32_16x16x32_bf16 v[74:77], v[216:219], v[158:161], v[74:77]
	s_waitcnt lgkmcnt(0)
	v_mfma_f32_16x16x32_bf16 v[110:113], v[212:215], v[158:161], v[110:113]
	global_load_dwordx4 v[158:161], v[240:241], off
	v_mfma_f32_16x16x32_bf16 v[208:211], v[30:33], v[200:203], v[220:223]
	v_mfma_f32_16x16x32_bf16 v[78:81], v[216:219], v[192:195], v[78:81]
	v_mfma_f32_16x16x32_bf16 v[102:105], v[216:219], v[196:199], v[102:105]
	v_mfma_f32_16x16x32_bf16 v[54:57], v[216:219], v[200:203], v[54:57]
	v_mfma_f32_16x16x32_bf16 v[114:117], v[212:215], v[192:195], v[114:117]
	v_mfma_f32_16x16x32_bf16 v[154:157], v[212:215], v[196:199], v[154:157]
	ds_read_b128 v[192:195], v181 offset:160
	ds_read_b128 v[196:199], v181 offset:8608
	ds_read_b128 v[216:219], v181 offset:17056
	ds_read_b128 v[220:223], v181 offset:25504
	v_mfma_f32_16x16x32_bf16 v[106:109], v[212:215], v[200:203], v[106:109]
	s_waitcnt lgkmcnt(0)
	v_mfma_f32_16x16x32_bf16 v[200:203], v[26:29], v[216:219], v[204:207]
	v_mfma_f32_16x16x32_bf16 v[204:207], v[26:29], v[220:223], v[208:211]
	s_nop 2
	ds_read_b128 v[208:211], v183
	s_waitcnt lgkmcnt(0)
	v_mfma_f32_16x16x32_bf16 v[58:61], v[208:211], v[192:195], v[58:61]
	v_mfma_f32_16x16x32_bf16 v[62:65], v[208:211], v[196:199], v[62:65]
	v_mfma_f32_16x16x32_bf16 v[70:73], v[208:211], v[216:219], v[70:73]
	v_mfma_f32_16x16x32_bf16 v[50:53], v[208:211], v[220:223], v[50:53]
	ds_read_b128 v[208:211], v182 offset:3072
	ds_read_b128 v[212:215], v182 offset:7168
	v_mfma_f32_16x16x32_bf16 v[162:165], v[26:29], v[192:195], v[162:165]
	s_waitcnt lgkmcnt(0)
	v_mfma_f32_16x16x32_bf16 v[74:77], v[208:211], v[192:195], v[74:77]
	v_mfma_f32_16x16x32_bf16 v[110:113], v[212:215], v[192:195], v[110:113]
	global_load_dwordx4 v[192:195], v[240:241], off offset:1024
	v_mfma_f32_16x16x32_bf16 v[184:187], v[26:29], v[196:199], v[184:187]
	v_mfma_f32_16x16x32_bf16 v[78:81], v[208:211], v[196:199], v[78:81]
	v_mfma_f32_16x16x32_bf16 v[102:105], v[208:211], v[216:219], v[102:105]
	v_mfma_f32_16x16x32_bf16 v[54:57], v[208:211], v[220:223], v[54:57]
	v_mfma_f32_16x16x32_bf16 v[114:117], v[212:215], v[196:199], v[114:117]
	v_mfma_f32_16x16x32_bf16 v[154:157], v[212:215], v[216:219], v[154:157]
	ds_read_b128 v[196:199], v181 offset:192
	ds_read_b128 v[208:211], v181 offset:8640
	ds_read_b128 v[216:219], v181 offset:17088
	ds_read_b128 v[224:227], v181 offset:25536
	v_mfma_f32_16x16x32_bf16 v[106:109], v[212:215], v[220:223], v[106:109]
	ds_read_b128 v[212:215], v0
	s_waitcnt lgkmcnt(0)
	v_mfma_f32_16x16x32_bf16 v[162:165], v[22:25], v[196:199], v[162:165]
	v_mfma_f32_16x16x32_bf16 v[184:187], v[22:25], v[208:211], v[184:187]
	v_mfma_f32_16x16x32_bf16 v[58:61], v[212:215], v[196:199], v[58:61]
	v_mfma_f32_16x16x32_bf16 v[220:223], v[212:215], v[208:211], v[62:65]
	v_mfma_f32_16x16x32_bf16 v[70:73], v[212:215], v[216:219], v[70:73]
	v_mfma_f32_16x16x32_bf16 v[50:53], v[212:215], v[224:227], v[50:53]
	s_nop 0
	ds_read_b128 v[62:65], v182 offset:2048
	ds_read_b128 v[212:215], v182 offset:6144
	s_waitcnt lgkmcnt(0)
	v_mfma_f32_16x16x32_bf16 v[74:77], v[62:65], v[196:199], v[74:77]
	v_mfma_f32_16x16x32_bf16 v[110:113], v[212:215], v[196:199], v[110:113]
	global_load_dwordx4 v[196:199], v[240:241], off offset:2048
	v_mfma_f32_16x16x32_bf16 v[200:203], v[22:25], v[216:219], v[200:203]
	v_mfma_f32_16x16x32_bf16 v[78:81], v[62:65], v[208:211], v[78:81]
	v_mfma_f32_16x16x32_bf16 v[102:105], v[62:65], v[216:219], v[102:105]
	v_mfma_f32_16x16x32_bf16 v[114:117], v[212:215], v[208:211], v[114:117]
	v_mfma_f32_16x16x32_bf16 v[154:157], v[212:215], v[216:219], v[154:157]
	ds_read_b128 v[208:211], v181 offset:224
	ds_read_b128 v[216:219], v181 offset:8672
	ds_read_b128 v[232:235], v181 offset:17120
	ds_read_b128 v[236:239], v181 offset:25568
	v_mfma_f32_16x16x32_bf16 v[106:109], v[212:215], v[224:227], v[106:109]
	v_mfma_f32_16x16x32_bf16 v[204:207], v[22:25], v[224:227], v[204:207]
	v_mfma_f32_16x16x32_bf16 v[228:231], v[62:65], v[224:227], v[54:57]
	ds_read_b128 v[212:215], v1
	s_waitcnt lgkmcnt(0)
; #define LAS __attribute__((address_space(3)))
; template <int H2>
; DEV void s5_p1_all(LAS char* shm, int wid, int fr, int fq, bf16x8 (&wfr)[8], const bf16_t* wsp, f32x4 (&acc)[4][4], f32x4 (&sac)[4]) {
;     ...
;     for (int sp = 0; sp < 16; ++sp) {
;         bf16x8 bn[4], kf[4];
; #pragma unroll
;         for (int q = 0; q < 4; ++q) if (q >= S5_Q0(sp)) kf[q] = *(const LAS bf16x8*)(kb + (8 * q - 2 * sp + 30) * 512);
; #pragma unroll
;         for (int nt = 0; nt < 4; ++nt) bn[nt] = bu[nt];
;         if (sp < 15) {
; #pragma unroll
;             for (int nt = 0; nt < 4; ++nt) bn[nt] = *(const LAS bf16x8*)(ub + nt * 16 * 528 + (sp + 1) * 32);
;         }
; #pragma unroll
;         for (int nt = 0; nt < 4; ++nt) sac[nt] = __builtin_amdgcn_mfma_f32_16x16x32_bf16(wfr[sp & 7], bu[nt], sac[nt], 0, 0, 0);
;         if (sp < 8) wfr[sp & 7] = *(const bf16x8*)(wsp + (size_t)(sp + 8) * 64 * 8);
; #pragma unroll
;         for (int q = 0; q < 4; ++q) {
;             if (q >= S5_Q0(sp)) {
; #pragma unroll
;                 for (int nt = 0; nt < 4; ++nt) acc[q][nt] = __builtin_amdgcn_mfma_f32_16x16x32_bf16(kf[q], bu[nt], acc[q][nt], 0, 0, 0);
;             }
;         }
; #pragma unroll
;         for (int nt = 0; nt < 4; ++nt) bu[nt] = bn[nt];
;         __builtin_amdgcn_sched_barrier(0);
;     }
	v_mfma_f32_16x16x32_bf16 v[162:165], v[18:21], v[208:211], v[162:165]
	v_mfma_f32_16x16x32_bf16 v[184:187], v[18:21], v[216:219], v[184:187]
	v_mfma_f32_16x16x32_bf16 v[62:65], v[212:215], v[208:211], v[58:61]
	v_mfma_f32_16x16x32_bf16 v[58:61], v[212:215], v[216:219], v[220:223]
	v_mfma_f32_16x16x32_bf16 v[54:57], v[212:215], v[232:235], v[70:73]
	v_mfma_f32_16x16x32_bf16 v[50:53], v[212:215], v[236:239], v[50:53]
	s_nop 1
	ds_read_b128 v[70:73], v182 offset:1024
	ds_read_b128 v[212:215], v182 offset:5120
	s_waitcnt lgkmcnt(0)
	v_mfma_f32_16x16x32_bf16 v[74:77], v[70:73], v[208:211], v[74:77]
	v_mfma_f32_16x16x32_bf16 v[110:113], v[212:215], v[208:211], v[110:113]
	global_load_dwordx4 v[208:211], v[240:241], off offset:3072
	v_mfma_f32_16x16x32_bf16 v[78:81], v[70:73], v[216:219], v[78:81]
	v_mfma_f32_16x16x32_bf16 v[102:105], v[70:73], v[232:235], v[102:105]
	v_mfma_f32_16x16x32_bf16 v[70:73], v[70:73], v[236:239], v[228:231]
	v_mfma_f32_16x16x32_bf16 v[114:117], v[212:215], v[216:219], v[114:117]
	ds_read_b128 v[216:219], v181 offset:256
	ds_read_b128 v[220:223], v181 offset:8704
	ds_read_b128 v[224:227], v181 offset:17152
	ds_read_b128 v[228:231], v181 offset:25600
	v_mfma_f32_16x16x32_bf16 v[154:157], v[212:215], v[232:235], v[154:157]
	v_mfma_f32_16x16x32_bf16 v[106:109], v[212:215], v[236:239], v[106:109]
	v_mfma_f32_16x16x32_bf16 v[200:203], v[18:21], v[232:235], v[200:203]
	v_mfma_f32_16x16x32_bf16 v[204:207], v[18:21], v[236:239], v[204:207]
	ds_read_b128 v[212:215], v182
	ds_read_b128 v[232:235], v182 offset:4096
	s_waitcnt vmcnt(0) lgkmcnt(0)
	v_mfma_f32_16x16x32_bf16 v[162:165], v[82:85], v[216:219], v[162:165]
	v_mfma_f32_16x16x32_bf16 v[184:187], v[82:85], v[220:223], v[184:187]
	v_mfma_f32_16x16x32_bf16 v[200:203], v[82:85], v[224:227], v[200:203]
	v_mfma_f32_16x16x32_bf16 v[74:77], v[212:215], v[216:219], v[74:77]
	v_mfma_f32_16x16x32_bf16 v[78:81], v[212:215], v[220:223], v[78:81]
	v_mfma_f32_16x16x32_bf16 v[102:105], v[212:215], v[224:227], v[102:105]
	v_mfma_f32_16x16x32_bf16 v[70:73], v[212:215], v[228:231], v[70:73]
	v_mfma_f32_16x16x32_bf16 v[110:113], v[232:235], v[216:219], v[110:113]
	v_mfma_f32_16x16x32_bf16 v[114:117], v[232:235], v[220:223], v[114:117]
	v_mfma_f32_16x16x32_bf16 v[154:157], v[232:235], v[224:227], v[154:157]
	ds_read_b128 v[212:215], v181 offset:288
	ds_read_b128 v[216:219], v181 offset:8736
	ds_read_b128 v[220:223], v181 offset:17184
	ds_read_b128 v[224:227], v181 offset:25632
	v_mfma_f32_16x16x32_bf16 v[106:109], v[232:235], v[228:231], v[106:109]
	v_mfma_f32_16x16x32_bf16 v[204:207], v[82:85], v[228:231], v[204:207]
	s_waitcnt lgkmcnt(3)
	v_mfma_f32_16x16x32_bf16 v[162:165], v[66:69], v[212:215], v[162:165]
	s_waitcnt lgkmcnt(2)
	v_mfma_f32_16x16x32_bf16 v[184:187], v[66:69], v[216:219], v[184:187]
	s_waitcnt lgkmcnt(1)
	v_mfma_f32_16x16x32_bf16 v[200:203], v[66:69], v[220:223], v[200:203]
	s_waitcnt lgkmcnt(0)
	v_mfma_f32_16x16x32_bf16 v[66:69], v[66:69], v[224:227], v[204:207]
	s_nop 2
	ds_read_b128 v[204:207], v183
	ds_read_b128 v[228:231], v182 offset:3072
	s_waitcnt lgkmcnt(1)
	v_mfma_f32_16x16x32_bf16 v[74:77], v[204:207], v[212:215], v[74:77]
	v_mfma_f32_16x16x32_bf16 v[78:81], v[204:207], v[216:219], v[78:81]
	v_mfma_f32_16x16x32_bf16 v[102:105], v[204:207], v[220:223], v[102:105]
	v_mfma_f32_16x16x32_bf16 v[70:73], v[204:207], v[224:227], v[70:73]
	s_waitcnt lgkmcnt(0)
	v_mfma_f32_16x16x32_bf16 v[110:113], v[228:231], v[212:215], v[110:113]
	v_mfma_f32_16x16x32_bf16 v[114:117], v[228:231], v[216:219], v[114:117]
	v_mfma_f32_16x16x32_bf16 v[154:157], v[228:231], v[220:223], v[154:157]
	ds_read_b128 v[204:207], v181 offset:320
	ds_read_b128 v[212:215], v181 offset:8768
	ds_read_b128 v[216:219], v181 offset:17216
	ds_read_b128 v[220:223], v181 offset:25664
	v_mfma_f32_16x16x32_bf16 v[106:109], v[228:231], v[224:227], v[106:109]
	s_waitcnt lgkmcnt(3)
	v_mfma_f32_16x16x32_bf16 v[162:165], v[188:191], v[204:207], v[162:165]
	s_waitcnt lgkmcnt(2)
	v_mfma_f32_16x16x32_bf16 v[184:187], v[188:191], v[212:215], v[184:187]
	s_waitcnt lgkmcnt(1)
	v_mfma_f32_16x16x32_bf16 v[200:203], v[188:191], v[216:219], v[200:203]
	s_waitcnt lgkmcnt(0)
	v_mfma_f32_16x16x32_bf16 v[66:69], v[188:191], v[220:223], v[66:69]
	ds_read_b128 v[188:191], v0
	ds_read_b128 v[224:227], v182 offset:2048
	s_waitcnt lgkmcnt(1)
	v_mfma_f32_16x16x32_bf16 v[74:77], v[188:191], v[204:207], v[74:77]
	v_mfma_f32_16x16x32_bf16 v[228:231], v[188:191], v[212:215], v[78:81]
	v_mfma_f32_16x16x32_bf16 v[102:105], v[188:191], v[216:219], v[102:105]
	s_waitcnt lgkmcnt(0)
	v_mfma_f32_16x16x32_bf16 v[110:113], v[224:227], v[204:207], v[110:113]
	v_mfma_f32_16x16x32_bf16 v[114:117], v[224:227], v[212:215], v[114:117]
	v_mfma_f32_16x16x32_bf16 v[154:157], v[224:227], v[216:219], v[154:157]
	ds_read_b128 v[204:207], v181 offset:352
	ds_read_b128 v[212:215], v181 offset:8800
	ds_read_b128 v[216:219], v181 offset:17248
	ds_read_b128 v[232:235], v181 offset:25696
	v_mfma_f32_16x16x32_bf16 v[106:109], v[224:227], v[220:223], v[106:109]
	v_mfma_f32_16x16x32_bf16 v[188:191], v[188:191], v[220:223], v[70:73]
	s_waitcnt lgkmcnt(3)
; #define LAS __attribute__((address_space(3)))
; template <int H2>
; DEV void s5_p1_all(LAS char* shm, int wid, int fr, int fq, bf16x8 (&wfr)[8], const bf16_t* wsp, f32x4 (&acc)[4][4], f32x4 (&sac)[4]) {
;     constexpr int PLANE = 64 * 528, KTL = 2 * PLANE;
;     const LAS char* ub = shm + (fq & 1) * PLANE + fr * 528 + (fq >> 1) * 16;
;     const LAS char* kb = shm + KTL + (1 - (fq >> 1)) * 512 + fr * 32 + (fq & 1) * 16 + (wid - 30) * 512;
;     ...
;     bf16x8 bu[4];
; #pragma unroll
;     for (int nt = 0; nt < 4; ++nt) bu[nt] = *(const LAS bf16x8*)(ub + nt * 16 * 528);
; #pragma unroll
;     for (int sp = 0; sp < 16; ++sp) {
;         bf16x8 bn[4], kf[4];
; #pragma unroll
;         for (int q = 0; q < 4; ++q) if (q >= S5_Q0(sp)) kf[q] = *(const LAS bf16x8*)(kb + (8 * q - 2 * sp + 30) * 512);
; #pragma unroll
;         for (int nt = 0; nt < 4; ++nt) bn[nt] = bu[nt];
;         if (sp < 15) {
; #pragma unroll
;             for (int nt = 0; nt < 4; ++nt) bn[nt] = *(const LAS bf16x8*)(ub + nt * 16 * 528 + (sp + 1) * 32);
;         }
; #pragma unroll
;         for (int nt = 0; nt < 4; ++nt) sac[nt] = __builtin_amdgcn_mfma_f32_16x16x32_bf16(wfr[sp & 7], bu[nt], sac[nt], 0, 0, 0);
;         if (sp < 8) wfr[sp & 7] = *(const bf16x8*)(wsp + (size_t)(sp + 8) * 64 * 8);
; #pragma unroll
;         for (int q = 0; q < 4; ++q) {
;             if (q >= S5_Q0(sp)) {
; #pragma unroll
;                 for (int nt = 0; nt < 4; ++nt) acc[q][nt] = __builtin_amdgcn_mfma_f32_16x16x32_bf16(kf[q], bu[nt], acc[q][nt], 0, 0, 0);
;             }
;         }
; #pragma unroll
;         for (int nt = 0; nt < 4; ++nt) bu[nt] = bn[nt];
;         __builtin_amdgcn_sched_barrier(0);
;     }
;     ...
; }
	v_mfma_f32_16x16x32_bf16 v[162:165], v[150:153], v[204:207], v[162:165]
	s_waitcnt lgkmcnt(2)
	v_mfma_f32_16x16x32_bf16 v[184:187], v[150:153], v[212:215], v[184:187]
	s_waitcnt lgkmcnt(1)
	v_mfma_f32_16x16x32_bf16 v[200:203], v[150:153], v[216:219], v[200:203]
	s_waitcnt lgkmcnt(0)
	v_mfma_f32_16x16x32_bf16 v[150:153], v[150:153], v[232:235], v[66:69]
	s_nop 2
	ds_read_b128 v[66:69], v1
	ds_read_b128 v[220:223], v182 offset:1024
	s_waitcnt lgkmcnt(1)
	v_mfma_f32_16x16x32_bf16 v[78:81], v[66:69], v[204:207], v[74:77]
	v_mfma_f32_16x16x32_bf16 v[74:77], v[66:69], v[212:215], v[228:231]
	v_mfma_f32_16x16x32_bf16 v[70:73], v[66:69], v[216:219], v[102:105]
	v_mfma_f32_16x16x32_bf16 v[66:69], v[66:69], v[232:235], v[188:191]
	s_waitcnt lgkmcnt(0)
	v_mfma_f32_16x16x32_bf16 v[102:105], v[220:223], v[204:207], v[110:113]
	v_mfma_f32_16x16x32_bf16 v[110:113], v[220:223], v[212:215], v[114:117]
	v_mfma_f32_16x16x32_bf16 v[114:117], v[220:223], v[216:219], v[154:157]
	s_nop 2
	ds_read_b128 v[154:157], v181 offset:384
	ds_read_b128 v[188:191], v181 offset:8832
	ds_read_b128 v[204:207], v181 offset:17280
	ds_read_b128 v[212:215], v181 offset:25728
	v_mfma_f32_16x16x32_bf16 v[106:109], v[220:223], v[232:235], v[106:109]
	s_waitcnt lgkmcnt(3)
	v_mfma_f32_16x16x32_bf16 v[162:165], v[158:161], v[154:157], v[162:165]
	s_waitcnt lgkmcnt(2)
	v_mfma_f32_16x16x32_bf16 v[184:187], v[158:161], v[188:191], v[184:187]
	s_waitcnt lgkmcnt(1)
	v_mfma_f32_16x16x32_bf16 v[200:203], v[158:161], v[204:207], v[200:203]
	s_waitcnt lgkmcnt(0)
	v_mfma_f32_16x16x32_bf16 v[150:153], v[158:161], v[212:215], v[150:153]
	ds_read_b128 v[158:161], v182
	s_waitcnt lgkmcnt(0)
	v_mfma_f32_16x16x32_bf16 v[102:105], v[158:161], v[154:157], v[102:105]
	v_mfma_f32_16x16x32_bf16 v[110:113], v[158:161], v[188:191], v[110:113]
	v_mfma_f32_16x16x32_bf16 v[114:117], v[158:161], v[204:207], v[114:117]
	ds_read_b128 v[154:157], v181 offset:416
	ds_read_b128 v[188:191], v181 offset:8864
	ds_read_b128 v[204:207], v181 offset:17312
	ds_read_b128 v[216:219], v181 offset:25760
	v_mfma_f32_16x16x32_bf16 v[106:109], v[158:161], v[212:215], v[106:109]
	s_waitcnt lgkmcnt(3)
	v_mfma_f32_16x16x32_bf16 v[158:161], v[192:195], v[154:157], v[162:165]
	s_waitcnt lgkmcnt(2)
	v_mfma_f32_16x16x32_bf16 v[162:165], v[192:195], v[188:191], v[184:187]
	s_waitcnt lgkmcnt(1)
	v_mfma_f32_16x16x32_bf16 v[184:187], v[192:195], v[204:207], v[200:203]
	s_waitcnt lgkmcnt(0)
	v_mfma_f32_16x16x32_bf16 v[150:153], v[192:195], v[216:219], v[150:153]
	ds_read_b128 v[192:195], v183
	s_waitcnt lgkmcnt(0)
	v_mfma_f32_16x16x32_bf16 v[102:105], v[192:195], v[154:157], v[102:105]
	v_mfma_f32_16x16x32_bf16 v[110:113], v[192:195], v[188:191], v[110:113]
	v_mfma_f32_16x16x32_bf16 v[114:117], v[192:195], v[204:207], v[114:117]
	ds_read_b128 v[154:157], v181 offset:448
	ds_read_b128 v[188:191], v181 offset:8896
	ds_read_b128 v[200:203], v181 offset:17344
	ds_read_b128 v[204:207], v181 offset:25792
	v_mfma_f32_16x16x32_bf16 v[106:109], v[192:195], v[216:219], v[106:109]
	s_waitcnt lgkmcnt(2)
	v_mfma_f32_16x16x32_bf16 v[192:195], v[196:199], v[188:191], v[162:165]
	s_nop 2
	ds_read_b128 v[162:165], v0
	v_mfma_f32_16x16x32_bf16 v[158:161], v[196:199], v[154:157], v[158:161]
	s_waitcnt lgkmcnt(2)
	v_mfma_f32_16x16x32_bf16 v[184:187], v[196:199], v[200:203], v[184:187]
	s_waitcnt lgkmcnt(1)
	v_mfma_f32_16x16x32_bf16 v[150:153], v[196:199], v[204:207], v[150:153]
	s_waitcnt lgkmcnt(0)
	v_mfma_f32_16x16x32_bf16 v[188:191], v[162:165], v[188:191], v[110:113]
	v_mfma_f32_16x16x32_bf16 v[114:117], v[162:165], v[200:203], v[114:117]
	s_nop 1
	ds_read_b128 v[110:113], v181 offset:480
	ds_read_b128 v[196:199], v181 offset:8928
	ds_read_b128 v[200:203], v181 offset:17376
	ds_read_b128 v[212:215], v181 offset:25824
	v_mfma_f32_16x16x32_bf16 v[102:105], v[162:165], v[154:157], v[102:105]
	v_mfma_f32_16x16x32_bf16 v[204:207], v[162:165], v[204:207], v[106:109]
	s_waitcnt lgkmcnt(1)
	v_mfma_f32_16x16x32_bf16 v[154:157], v[208:211], v[200:203], v[184:187]
	s_nop 2
	ds_read_b128 v[184:187], v1
	v_mfma_f32_16x16x32_bf16 v[162:165], v[208:211], v[110:113], v[158:161]
	v_mfma_f32_16x16x32_bf16 v[158:161], v[208:211], v[196:199], v[192:195]
	s_waitcnt lgkmcnt(1)
	v_mfma_f32_16x16x32_bf16 v[150:153], v[208:211], v[212:215], v[150:153]
	s_waitcnt lgkmcnt(0)
	v_mfma_f32_16x16x32_bf16 v[110:113], v[184:187], v[110:113], v[102:105]
	v_mfma_f32_16x16x32_bf16 v[106:109], v[184:187], v[196:199], v[188:191]
	v_mfma_f32_16x16x32_bf16 v[102:105], v[184:187], v[200:203], v[114:117]
	v_mfma_f32_16x16x32_bf16 v[114:117], v[184:187], v[212:215], v[204:207]
	s_cbranch_execz .LBB0_296
	s_branch .LBB0_297

.LBB0_894:
	s_or_b64 exec, exec, s[40:41]
	s_barrier
	s_and_saveexec_b64 s[0:1], s[4:5]
	s_cbranch_execz .LBB0_896
	v_lshl_add_u64 v[0:1], v[182:183], 4, s[18:19]
	global_load_dword v182, v[0:1], off sc1
	global_load_dword v183, v[0:1], off offset:4 sc1
	global_load_dword v221, v[0:1], off offset:8 sc1
	global_load_dword v222, v[0:1], off offset:12 sc1
	s_mov_b32 s12, 0x800000
	s_waitcnt vmcnt(0)
	v_add_f32_e32 v182, v183, v182
	s_nop 0
	s_nop 0
	v_add_f32_e32 v182, v182, v221
	s_nop 0
	s_nop 0
	v_add_f32_e32 v0, v182, v222
	v_fmamk_f32 v0, v0, 0x3a800000, v219
	v_cmp_gt_f32_e32 vcc, s12, v0
	v_mul_f32_e32 v1, 0x4b800000, v0
	s_nop 0
	v_cndmask_b32_e32 v0, v0, v1, vcc
	v_rsq_f32_e32 v0, v0
	s_nop 0
	v_mul_f32_e32 v1, 0x45800000, v0
	v_cndmask_b32_e32 v0, v0, v1, vcc
	ds_write_b32 v215, v0

; DEV int opaque_tid() { int t = threadIdx.x; asm volatile("" : "+v"(t)); return t; }
; #define LAS __attribute__((address_space(3)))
; DEV void s5_phase(LAS char* shm, const bf16_t* Uin, bf16_t* Yout, const char* tab, const float* dskip) {
;     ...
;     for (int item = blockIdx.x; item < BATCH * NG; item += gridDim.x) {
;         const int tid = opaque_tid(), wid = __builtin_amdgcn_readfirstlane(tid >> 6), lane = tid & 63, fr = lane & 15, fq = lane >> 4;
;         const int xcd_ = item & 7, j_ = (item >> 3) & 31, g = xcd_ * 8 + (j_ & 7), b = (j_ >> 3) + 4 * (item >> 8);
;         const bf16_t* Ub = Uin + ((size_t)g * MTOK + (size_t)b * SEQ) * 16;
;         bf16_t* Yb = Yout + ((size_t)g * MTOK + (size_t)b * SEQ) * 16;
;         bf16x8 wfr[8];
;         const bf16_t* wsp = WS + (size_t)g * WS_G + ((size_t)(wid * 16) * 64 + lane) * 8; asm volatile("" : "+v"(wsp));
; #pragma unroll
;         for (int sp = 0; sp < 8; ++sp) wfr[sp] = *(const bf16x8*)(wsp + (size_t)sp * 64 * 8);
;         __syncthreads();
; #pragma unroll
;         for (int i = 0; i < 8; ++i) {
;             const int idx = tid + 512 * i, tok = idx >> 1, hf = idx & 1;
;             const uint4 uv = *(const uint4*)(Ub + (size_t)tok * 16 + hf * 8);
;             *(LAS u32x4*)(shm + hf * PLANE + (tok >> 5) * 528 + (tok & 31) * 16) = (u32x4){uv.x, uv.y, uv.z, uv.w};
;         }
;         for (int idx = tid; idx < 33 * 32; idx += 512) {
;             const uint4 kv = *(const uint4*)(KT + (size_t)g * KT_G + idx * 8);
;             *(LAS u32x4*)(shm + KTL + idx * 16) = (u32x4){kv.x, kv.y, kv.z, kv.w};
;         }
.LBB0_1143:
	s_lshl_b32 s0, s42, 3
	s_and_b32 s0, s0, 56
	s_bfe_u32 s1, s42, 0x30003
	s_or_b32 s45, s0, s1
	s_ashr_i32 s1, s42, 6
	s_bfe_u32 s0, s42, 0x20006
	s_and_b32 s1, s1, -4
	v_mov_b32_e32 v172, v254
	s_or_b32 s0, s0, s1
	s_ashr_i32 s1, s0, 31
	v_readfirstlane_b32 s44, v172
	s_ashr_i32 s43, s44, 6
	s_lshl_b64 s[0:1], s[0:1], 15
	s_lshl_b32 s6, s45, 18
	s_add_u32 s0, s6, s0
	s_addc_u32 s1, 0, s1
	s_lshl_b64 s[8:9], s[0:1], 1
	s_add_u32 s0, s15, s8
	s_addc_u32 s1, s16, s9
	s_lshl_b32 s6, s45, 17
	s_add_u32 s12, s23, s6
	s_addc_u32 s13, s24, 0
	s_lshl_b32 s6, s43, 4
	s_ashr_i32 s7, s6, 31
	s_lshl_b64 s[10:11], s[6:7], 10
	v_and_b32_e32 v173, 63, v172
	s_add_u32 s10, s12, s10
	s_addc_u32 s11, s13, s11
	v_lshlrev_b32_e32 v166, 4, v173
	v_lshl_add_u64 v[168:169], s[10:11], 0, v[166:167]
	v_and_b32_e32 v82, 1, v172
	v_add_co_u32_e32 v0, vcc, s27, v168
	v_ashrrev_i32_e32 v66, 1, v172
	s_nop 0
	v_addc_co_u32_e32 v1, vcc, 0, v169, vcc
	global_load_dwordx4 v[46:49], v[168:169], off
	global_load_dwordx4 v[42:45], v[168:169], off offset:1024
	global_load_dwordx4 v[38:41], v[168:169], off offset:2048
	global_load_dwordx4 v[34:37], v[168:169], off offset:3072
	global_load_dwordx4 v[30:33], v[0:1], off
	global_load_dwordx4 v[26:29], v[0:1], off offset:1024
	global_load_dwordx4 v[22:25], v[0:1], off offset:2048
	global_load_dwordx4 v[18:21], v[0:1], off offset:3072
	v_lshlrev_b32_e32 v0, 4, v82
	v_mov_b32_e32 v1, v167
	v_ashrrev_i32_e32 v67, 31, v66
	v_lshl_add_u64 v[0:1], s[0:1], 0, v[0:1]
	v_lshlrev_b64 v[2:3], 5, v[66:67]
	v_add_u32_e32 v67, 0x200, v172
	v_lshl_add_u64 v[2:3], v[0:1], 0, v[2:3]
	v_ashrrev_i32_e32 v68, 1, v67
	s_waitcnt lgkmcnt(0)
	s_barrier
	global_load_dwordx4 v[2:5], v[2:3], off
	v_ashrrev_i32_e32 v69, 31, v68
	v_lshlrev_b64 v[6:7], 5, v[68:69]
	v_add_u32_e32 v69, 0x400, v172
	v_lshl_add_u64 v[6:7], v[0:1], 0, v[6:7]
	v_ashrrev_i32_e32 v70, 1, v69
	global_load_dwordx4 v[6:9], v[6:7], off
	v_ashrrev_i32_e32 v71, 31, v70
	v_lshlrev_b64 v[10:11], 5, v[70:71]
	v_add_u32_e32 v71, 0x600, v172
	v_lshl_add_u64 v[10:11], v[0:1], 0, v[10:11]
	v_ashrrev_i32_e32 v72, 1, v71
	global_load_dwordx4 v[10:13], v[10:11], off
	v_ashrrev_i32_e32 v73, 31, v72
	v_lshlrev_b64 v[14:15], 5, v[72:73]
	v_add_u32_e32 v73, 0x800, v172
	v_lshl_add_u64 v[14:15], v[0:1], 0, v[14:15]
	v_ashrrev_i32_e32 v74, 1, v73
	global_load_dwordx4 v[14:17], v[14:15], off
	v_ashrrev_i32_e32 v75, 31, v74
	v_lshlrev_b64 v[50:51], 5, v[74:75]
	v_add_u32_e32 v75, 0xa00, v172
	v_lshl_add_u64 v[50:51], v[0:1], 0, v[50:51]
	v_ashrrev_i32_e32 v76, 1, v75
	global_load_dwordx4 v[50:53], v[50:51], off
	v_ashrrev_i32_e32 v77, 31, v76
	v_lshlrev_b64 v[54:55], 5, v[76:77]
	v_add_u32_e32 v77, 0xc00, v172
	v_lshl_add_u64 v[54:55], v[0:1], 0, v[54:55]
	v_ashrrev_i32_e32 v78, 1, v77
	global_load_dwordx4 v[54:57], v[54:55], off
	v_ashrrev_i32_e32 v79, 31, v78
	v_lshlrev_b64 v[58:59], 5, v[78:79]
	v_add_u32_e32 v79, 0xe00, v172
	v_lshl_add_u64 v[58:59], v[0:1], 0, v[58:59]
	v_ashrrev_i32_e32 v80, 1, v79
	global_load_dwordx4 v[58:61], v[58:59], off
	v_ashrrev_i32_e32 v81, 31, v80
	v_lshlrev_b64 v[62:63], 5, v[80:81]
	v_lshl_add_u64 v[0:1], v[0:1], 0, v[62:63]
	global_load_dwordx4 v[62:65], v[0:1], off
	v_ashrrev_i32_e32 v1, 6, v172
	v_lshlrev_b32_e32 v66, 4, v66
	v_mad_u32_u24 v0, v82, s28, 0
	v_mul_lo_u32 v1, v1, s29
	v_and_b32_e32 v66, 0x1f0, v66
	v_add3_u32 v1, v0, v1, v66
	v_cmp_gt_i32_e32 vcc, s30, v172
	s_waitcnt vmcnt(0)
	ds_write_b128 v1, v[2:5]
	v_ashrrev_i32_e32 v1, 6, v67
	v_lshlrev_b32_e32 v2, 4, v68
	v_mul_lo_u32 v1, v1, s29
	v_and_b32_e32 v2, 0x1f0, v2
	v_add3_u32 v1, v0, v1, v2
	ds_write_b128 v1, v[6:9]
	v_ashrrev_i32_e32 v1, 6, v69
	v_lshlrev_b32_e32 v2, 4, v70
	v_mul_lo_u32 v1, v1, s29
	v_and_b32_e32 v2, 0x1f0, v2
	v_add3_u32 v1, v0, v1, v2
	ds_write_b128 v1, v[10:13]
	v_ashrrev_i32_e32 v1, 6, v71
	v_lshlrev_b32_e32 v2, 4, v72
	v_mul_lo_u32 v1, v1, s29
	v_and_b32_e32 v2, 0x1f0, v2
	v_add3_u32 v1, v0, v1, v2
	ds_write_b128 v1, v[14:17]
	v_ashrrev_i32_e32 v1, 6, v73
	v_lshlrev_b32_e32 v2, 4, v74
	v_mul_lo_u32 v1, v1, s29
	v_and_b32_e32 v2, 0x1f0, v2
	v_add3_u32 v1, v0, v1, v2
	ds_write_b128 v1, v[50:53]
	v_ashrrev_i32_e32 v1, 6, v75
	v_lshlrev_b32_e32 v2, 4, v76
	v_mul_lo_u32 v1, v1, s29
	v_and_b32_e32 v2, 0x1f0, v2
	v_add3_u32 v1, v0, v1, v2
	ds_write_b128 v1, v[54:57]
	v_ashrrev_i32_e32 v1, 6, v77
	v_lshlrev_b32_e32 v2, 4, v78
	v_mul_lo_u32 v1, v1, s29
	v_and_b32_e32 v2, 0x1f0, v2
	v_add3_u32 v1, v0, v1, v2
	ds_write_b128 v1, v[58:61]
	v_ashrrev_i32_e32 v1, 6, v79
	v_lshlrev_b32_e32 v2, 4, v80
	v_mul_lo_u32 v1, v1, s29
	v_and_b32_e32 v2, 0x1f0, v2
	v_add3_u32 v0, v0, v1, v2
	ds_write_b128 v0, v[62:65]
	s_and_saveexec_b64 s[0:1], vcc
	s_cbranch_execz .LBB0_1146
	s_mul_i32 s7, s45, 0x4200
	s_add_u32 s10, s19, s7
	s_addc_u32 s11, s20, 0
	v_add_u32_e32 v4, 0xfffffe00, v172
	v_lshl_add_u32 v5, v172, 4, s31
	v_lshlrev_b32_e32 v2, 3, v172
	s_mov_b64 s[12:13], 0

; #define LAS __attribute__((address_space(3)))
; template <int H2>
; DEV void s5_p1_all(LAS char* shm, int wid, int fr, int fq, bf16x8 (&wfr)[8], const bf16_t* wsp, f32x4 (&acc)[4][4], f32x4 (&sac)[4]) {
;     constexpr int PLANE = 64 * 528, KTL = 2 * PLANE;
;     const LAS char* ub = shm + (fq & 1) * PLANE + fr * 528 + (fq >> 1) * 16;
;     const LAS char* kb = shm + KTL + (1 - (fq >> 1)) * 512 + fr * 32 + (fq & 1) * 16 + (wid - 30) * 512;
;     ...
;     bf16x8 bu[4];
; #pragma unroll
;     for (int nt = 0; nt < 4; ++nt) bu[nt] = *(const LAS bf16x8*)(ub + nt * 16 * 528);
; #pragma unroll
;     for (int sp = 0; sp < 16; ++sp) {
;         bf16x8 bn[4], kf[4];
; #pragma unroll
;         for (int q = 0; q < 4; ++q) if (q >= S5_Q0(sp)) kf[q] = *(const LAS bf16x8*)(kb + (8 * q - 2 * sp + 30) * 512);
; #pragma unroll
;         for (int nt = 0; nt < 4; ++nt) bn[nt] = bu[nt];
;         if (sp < 15) {
; #pragma unroll
;             for (int nt = 0; nt < 4; ++nt) bn[nt] = *(const LAS bf16x8*)(ub + nt * 16 * 528 + (sp + 1) * 32);
; DEV void s5_phase(LAS char* shm, const bf16_t* Uin, bf16_t* Yout, const char* tab, const float* dskip) {
;     ...
;         {
;             const int h2 = wid >> 1;
;             if (h2 == 0) s5_p1_all<0>(shm, wid, fr, fq, wfr, wsp, acc, sac);
;             else if (h2 == 1) s5_p1_all<1>(shm, wid, fr, fq, wfr, wsp, acc, sac);
;             else if (h2 == 2) s5_p1_all<2>(shm, wid, fr, fq, wfr, wsp, acc, sac);
;             else s5_p1_all<3>(shm, wid, fr, fq, wfr, wsp, acc, sac);
;         }
.LBB0_1146:
	s_or_b64 exec, exec, s[0:1]
	s_lshl_b32 s7, s45, 16
	v_and_b32_e32 v175, 15, v172
	v_bfe_u32 v0, v173, 4, 1
	v_lshrrev_b32_e32 v174, 5, v173
	s_mov_b64 s[0:1], -1
	s_cmpk_gt_u32 s44, 0x7f
	v_lshlrev_b32_e32 v170, 5, v175
	v_mad_u32_u24 v179, v0, s28, 0
	v_mul_u32_u24_e32 v176, 0x210, v175
	v_lshlrev_b32_e32 v180, 4, v174
	v_lshlrev_b32_e32 v178, 9, v174
	v_lshlrev_b32_e32 v177, 4, v0
	s_waitcnt lgkmcnt(0)
	s_barrier
	s_cbranch_scc0 .LBB0_1153
	v_add_co_u32_e32 v0, vcc, 0x2000, v168
	v_mul_u32_u24_e32 v171, 0x210, v175
	s_nop 0
	v_addc_co_u32_e32 v1, vcc, 0, v169, vcc
	global_load_dwordx4 v[82:85], v[0:1], off
	v_xor_b32_e32 v0, 0x200, v178
	s_lshl_b32 s46, s43, 9
	v_add3_u32 v0, s31, v0, v170
	v_add3_u32 v181, v179, v171, v180
	v_add3_u32 v182, v0, v177, s46
	ds_read_b128 v[118:121], v181
	ds_read_b128 v[86:89], v181 offset:32
	ds_read_b128 v[146:149], v182
	ds_read_b128 v[142:145], v182 offset:4096
	ds_read_b128 v[130:133], v182 offset:8192
	ds_read_b128 v[122:125], v182 offset:12288
	ds_read_b128 v[126:129], v181 offset:8448
	ds_read_b128 v[94:97], v181 offset:8480
	ds_read_b128 v[134:137], v181 offset:16896
	ds_read_b128 v[98:101], v181 offset:16928
	ds_read_b128 v[138:141], v181 offset:25344
	ds_read_b128 v[90:93], v181 offset:25376
	s_ashr_i32 s47, s44, 7
	s_mov_b64 s[10:11], 0
	s_cmp_lt_i32 s47, 2
	s_mov_b64 s[12:13], 0
	s_cbranch_scc0 .LBB0_1163
	s_and_b64 vcc, exec, s[0:1]
	s_cbranch_vccnz .LBB0_1166

; #define LAS __attribute__((address_space(3)))
; template <int H2>
; DEV void s5_p1_all(LAS char* shm, int wid, int fr, int fq, bf16x8 (&wfr)[8], const bf16_t* wsp, f32x4 (&acc)[4][4], f32x4 (&sac)[4]) {
;     ...
;     for (int sp = 0; sp < 16; ++sp) {
;         bf16x8 bn[4], kf[4];
; #pragma unroll
;         for (int q = 0; q < 4; ++q) if (q >= S5_Q0(sp)) kf[q] = *(const LAS bf16x8*)(kb + (8 * q - 2 * sp + 30) * 512);
; #pragma unroll
;         for (int nt = 0; nt < 4; ++nt) bn[nt] = bu[nt];
;         if (sp < 15) {
; #pragma unroll
;             for (int nt = 0; nt < 4; ++nt) bn[nt] = *(const LAS bf16x8*)(ub + nt * 16 * 528 + (sp + 1) * 32);
;         }
; #pragma unroll
;         for (int nt = 0; nt < 4; ++nt) sac[nt] = __builtin_amdgcn_mfma_f32_16x16x32_bf16(wfr[sp & 7], bu[nt], sac[nt], 0, 0, 0);
;         if (sp < 8) wfr[sp & 7] = *(const bf16x8*)(wsp + (size_t)(sp + 8) * 64 * 8);
; #pragma unroll
;         for (int q = 0; q < 4; ++q) {
;             if (q >= S5_Q0(sp)) {
; #pragma unroll
;                 for (int nt = 0; nt < 4; ++nt) acc[q][nt] = __builtin_amdgcn_mfma_f32_16x16x32_bf16(kf[q], bu[nt], acc[q][nt], 0, 0, 0);
;             }
;         }
; #pragma unroll
;         for (int nt = 0; nt < 4; ++nt) bu[nt] = bn[nt];
;         __builtin_amdgcn_sched_barrier(0);
;     }
.LBB0_1151:
	s_waitcnt lgkmcnt(0)
	v_mfma_f32_16x16x32_bf16 v[2:5], v[46:49], v[118:121], 0
	v_mfma_f32_16x16x32_bf16 v[6:9], v[46:49], v[126:129], 0
	v_mfma_f32_16x16x32_bf16 v[10:13], v[46:49], v[134:137], 0
	v_mfma_f32_16x16x32_bf16 v[14:17], v[46:49], v[138:141], 0
	v_mfma_f32_16x16x32_bf16 v[50:53], v[146:149], v[118:121], 0
	v_mfma_f32_16x16x32_bf16 v[54:57], v[146:149], v[126:129], 0
	v_mfma_f32_16x16x32_bf16 v[58:61], v[146:149], v[134:137], 0
	v_mfma_f32_16x16x32_bf16 v[62:65], v[146:149], v[138:141], 0
	v_mfma_f32_16x16x32_bf16 v[66:69], v[142:145], v[118:121], 0
	v_mfma_f32_16x16x32_bf16 v[70:73], v[142:145], v[126:129], 0
	v_mfma_f32_16x16x32_bf16 v[74:77], v[142:145], v[134:137], 0
	v_mfma_f32_16x16x32_bf16 v[78:81], v[142:145], v[138:141], 0
	v_mfma_f32_16x16x32_bf16 v[102:105], v[130:133], v[118:121], 0
	v_mfma_f32_16x16x32_bf16 v[106:109], v[130:133], v[126:129], 0
	v_mfma_f32_16x16x32_bf16 v[110:113], v[130:133], v[134:137], 0
	v_mfma_f32_16x16x32_bf16 v[114:117], v[130:133], v[138:141], 0
	v_mfma_f32_16x16x32_bf16 v[118:121], v[122:125], v[118:121], 0
	v_mfma_f32_16x16x32_bf16 v[126:129], v[122:125], v[126:129], 0
	v_mfma_f32_16x16x32_bf16 v[130:133], v[122:125], v[134:137], 0
	v_mfma_f32_16x16x32_bf16 v[122:125], v[122:125], v[138:141], 0
	v_mfma_f32_16x16x32_bf16 v[134:137], v[42:45], v[86:89], v[2:5]
	v_add_co_u32_e32 v0, vcc, s34, v168
	s_nop 1
	ds_read_b128 v[2:5], v183
	v_mfma_f32_16x16x32_bf16 v[142:145], v[42:45], v[98:101], v[10:13]
	v_addc_co_u32_e32 v1, vcc, 0, v169, vcc
	v_mfma_f32_16x16x32_bf16 v[146:149], v[42:45], v[90:93], v[14:17]
	s_waitcnt lgkmcnt(0)
	v_mfma_f32_16x16x32_bf16 v[14:17], v[2:5], v[86:89], v[50:53]
	v_mfma_f32_16x16x32_bf16 v[10:13], v[2:5], v[94:97], v[54:57]
	s_nop 1
	ds_read_b128 v[50:53], v182 offset:3072
	ds_read_b128 v[54:57], v182 offset:7168
	v_mfma_f32_16x16x32_bf16 v[138:141], v[42:45], v[94:97], v[6:9]
	v_mfma_f32_16x16x32_bf16 v[6:9], v[2:5], v[98:101], v[58:61]
	s_waitcnt lgkmcnt(0)
	v_mfma_f32_16x16x32_bf16 v[58:61], v[50:53], v[86:89], v[66:69]
	v_mfma_f32_16x16x32_bf16 v[66:69], v[50:53], v[98:101], v[74:77]
	v_mfma_f32_16x16x32_bf16 v[74:77], v[54:57], v[94:97], v[106:109]
	s_nop 2
	global_load_dwordx4 v[106:109], v[0:1], off offset:1024
	v_mfma_f32_16x16x32_bf16 v[2:5], v[2:5], v[90:93], v[62:65]
	v_mfma_f32_16x16x32_bf16 v[62:65], v[50:53], v[94:97], v[70:73]
	v_mfma_f32_16x16x32_bf16 v[70:73], v[54:57], v[86:89], v[102:105]
	s_nop 2
	ds_read_b128 v[102:105], v182 offset:11264
	v_mfma_f32_16x16x32_bf16 v[50:53], v[50:53], v[90:93], v[78:81]
	v_mfma_f32_16x16x32_bf16 v[78:81], v[54:57], v[98:101], v[110:113]
	v_mfma_f32_16x16x32_bf16 v[54:57], v[54:57], v[90:93], v[114:117]
	s_waitcnt lgkmcnt(0)
	v_mfma_f32_16x16x32_bf16 v[86:89], v[102:105], v[86:89], v[118:121]
	v_mfma_f32_16x16x32_bf16 v[94:97], v[102:105], v[94:97], v[126:129]
	ds_read_b128 v[110:113], v181 offset:64
	ds_read_b128 v[114:117], v181 offset:8512
	ds_read_b128 v[118:121], v181 offset:16960
	ds_read_b128 v[126:129], v181 offset:25408
	v_mfma_f32_16x16x32_bf16 v[98:101], v[102:105], v[98:101], v[130:133]
	v_mfma_f32_16x16x32_bf16 v[90:93], v[102:105], v[90:93], v[122:125]
	s_waitcnt lgkmcnt(0)
	v_mfma_f32_16x16x32_bf16 v[122:125], v[38:41], v[114:117], v[138:141]
	v_mfma_f32_16x16x32_bf16 v[130:133], v[38:41], v[118:121], v[142:145]
	s_nop 1
	ds_read_b128 v[138:141], v182 offset:2048
	ds_read_b128 v[142:145], v182 offset:6144
	s_waitcnt lgkmcnt(0)
	v_mfma_f32_16x16x32_bf16 v[58:61], v[138:141], v[110:113], v[58:61]
	v_mfma_f32_16x16x32_bf16 v[62:65], v[138:141], v[114:117], v[62:65]
	v_mfma_f32_16x16x32_bf16 v[66:69], v[138:141], v[118:121], v[66:69]
	v_mfma_f32_16x16x32_bf16 v[50:53], v[138:141], v[126:129], v[50:53]
	ds_read_b128 v[138:141], v182 offset:10240
	v_mfma_f32_16x16x32_bf16 v[102:105], v[38:41], v[110:113], v[134:137]
	v_mfma_f32_16x16x32_bf16 v[70:73], v[142:145], v[110:113], v[70:73]
	s_waitcnt lgkmcnt(0)
	v_mfma_f32_16x16x32_bf16 v[86:89], v[138:141], v[110:113], v[86:89]
	global_load_dwordx4 v[110:113], v[0:1], off offset:2048
	v_mfma_f32_16x16x32_bf16 v[134:137], v[38:41], v[126:129], v[146:149]
	v_mfma_f32_16x16x32_bf16 v[74:77], v[142:145], v[114:117], v[74:77]
	v_mfma_f32_16x16x32_bf16 v[78:81], v[142:145], v[118:121], v[78:81]
	v_mfma_f32_16x16x32_bf16 v[54:57], v[142:145], v[126:129], v[54:57]
	v_mfma_f32_16x16x32_bf16 v[94:97], v[138:141], v[114:117], v[94:97]
	v_mfma_f32_16x16x32_bf16 v[98:101], v[138:141], v[118:121], v[98:101]
	ds_read_b128 v[114:117], v181 offset:96
	ds_read_b128 v[118:121], v181 offset:8544
	ds_read_b128 v[142:145], v181 offset:16992
	ds_read_b128 v[146:149], v181 offset:25440
	v_mfma_f32_16x16x32_bf16 v[90:93], v[138:141], v[126:129], v[90:93]
	s_waitcnt lgkmcnt(0)
	v_mfma_f32_16x16x32_bf16 v[126:129], v[34:37], v[142:145], v[130:133]
	v_mfma_f32_16x16x32_bf16 v[130:133], v[34:37], v[146:149], v[134:137]
	s_nop 2
	ds_read_b128 v[134:137], v182 offset:1024
	ds_read_b128 v[138:141], v182 offset:5120
	s_waitcnt lgkmcnt(0)
	v_mfma_f32_16x16x32_bf16 v[58:61], v[134:137], v[114:117], v[58:61]
	v_mfma_f32_16x16x32_bf16 v[62:65], v[134:137], v[118:121], v[62:65]
	v_mfma_f32_16x16x32_bf16 v[66:69], v[134:137], v[142:145], v[66:69]
	v_mfma_f32_16x16x32_bf16 v[50:53], v[134:137], v[146:149], v[50:53]
	ds_read_b128 v[134:137], v182 offset:9216
	v_mfma_f32_16x16x32_bf16 v[102:105], v[34:37], v[114:117], v[102:105]
	v_mfma_f32_16x16x32_bf16 v[70:73], v[138:141], v[114:117], v[70:73]
	s_waitcnt lgkmcnt(0)
; #define LAS __attribute__((address_space(3)))
; template <int H2>
; DEV void s5_p1_all(LAS char* shm, int wid, int fr, int fq, bf16x8 (&wfr)[8], const bf16_t* wsp, f32x4 (&acc)[4][4], f32x4 (&sac)[4]) {
;     ...
;     for (int sp = 0; sp < 16; ++sp) {
;         bf16x8 bn[4], kf[4];
; #pragma unroll
;         for (int q = 0; q < 4; ++q) if (q >= S5_Q0(sp)) kf[q] = *(const LAS bf16x8*)(kb + (8 * q - 2 * sp + 30) * 512);
; #pragma unroll
;         for (int nt = 0; nt < 4; ++nt) bn[nt] = bu[nt];
;         if (sp < 15) {
; #pragma unroll
;             for (int nt = 0; nt < 4; ++nt) bn[nt] = *(const LAS bf16x8*)(ub + nt * 16 * 528 + (sp + 1) * 32);
;         }
; #pragma unroll
;         for (int nt = 0; nt < 4; ++nt) sac[nt] = __builtin_amdgcn_mfma_f32_16x16x32_bf16(wfr[sp & 7], bu[nt], sac[nt], 0, 0, 0);
;         if (sp < 8) wfr[sp & 7] = *(const bf16x8*)(wsp + (size_t)(sp + 8) * 64 * 8);
; #pragma unroll
;         for (int q = 0; q < 4; ++q) {
;             if (q >= S5_Q0(sp)) {
; #pragma unroll
;                 for (int nt = 0; nt < 4; ++nt) acc[q][nt] = __builtin_amdgcn_mfma_f32_16x16x32_bf16(kf[q], bu[nt], acc[q][nt], 0, 0, 0);
;             }
;         }
; #pragma unroll
;         for (int nt = 0; nt < 4; ++nt) bu[nt] = bn[nt];
;         __builtin_amdgcn_sched_barrier(0);
;     }
	v_mfma_f32_16x16x32_bf16 v[86:89], v[134:137], v[114:117], v[86:89]
	global_load_dwordx4 v[114:117], v[0:1], off offset:3072
	v_mfma_f32_16x16x32_bf16 v[122:125], v[34:37], v[118:121], v[122:125]
	v_mfma_f32_16x16x32_bf16 v[74:77], v[138:141], v[118:121], v[74:77]
	v_mfma_f32_16x16x32_bf16 v[78:81], v[138:141], v[142:145], v[78:81]
	v_mfma_f32_16x16x32_bf16 v[54:57], v[138:141], v[146:149], v[54:57]
	v_mfma_f32_16x16x32_bf16 v[94:97], v[134:137], v[118:121], v[94:97]
	v_mfma_f32_16x16x32_bf16 v[98:101], v[134:137], v[142:145], v[98:101]
	ds_read_b128 v[118:121], v181 offset:128
	ds_read_b128 v[138:141], v181 offset:8576
	ds_read_b128 v[142:145], v181 offset:17024
	ds_read_b128 v[150:153], v181 offset:25472
	v_mfma_f32_16x16x32_bf16 v[90:93], v[134:137], v[146:149], v[90:93]
	ds_read_b128 v[134:137], v182
	ds_read_b128 v[146:149], v182 offset:4096
	v_add_co_u32_e32 v0, vcc, s36, v168
	s_waitcnt lgkmcnt(0)
	v_mfma_f32_16x16x32_bf16 v[102:105], v[30:33], v[118:121], v[102:105]
	v_addc_co_u32_e32 v1, vcc, 0, v169, vcc
	v_mfma_f32_16x16x32_bf16 v[58:61], v[134:137], v[118:121], v[58:61]
	v_mfma_f32_16x16x32_bf16 v[154:157], v[134:137], v[138:141], v[62:65]
	v_mfma_f32_16x16x32_bf16 v[66:69], v[134:137], v[142:145], v[66:69]
	v_mfma_f32_16x16x32_bf16 v[50:53], v[134:137], v[150:153], v[50:53]
	v_mfma_f32_16x16x32_bf16 v[134:137], v[146:149], v[150:153], v[54:57]
	s_nop 2
	ds_read_b128 v[54:57], v182 offset:8192
	v_mfma_f32_16x16x32_bf16 v[70:73], v[146:149], v[118:121], v[70:73]
	s_waitcnt lgkmcnt(0)
	v_mfma_f32_16x16x32_bf16 v[86:89], v[54:57], v[118:121], v[86:89]
	global_load_dwordx4 v[118:121], v[0:1], off
	v_mfma_f32_16x16x32_bf16 v[122:125], v[30:33], v[138:141], v[122:125]
	v_mfma_f32_16x16x32_bf16 v[126:129], v[30:33], v[142:145], v[126:129]
	v_mfma_f32_16x16x32_bf16 v[74:77], v[146:149], v[138:141], v[74:77]
	v_mfma_f32_16x16x32_bf16 v[78:81], v[146:149], v[142:145], v[78:81]
	v_mfma_f32_16x16x32_bf16 v[94:97], v[54:57], v[138:141], v[94:97]
	v_mfma_f32_16x16x32_bf16 v[98:101], v[54:57], v[142:145], v[98:101]
	ds_read_b128 v[138:141], v181 offset:160
	ds_read_b128 v[142:145], v181 offset:8608
	ds_read_b128 v[146:149], v181 offset:17056
	ds_read_b128 v[158:161], v181 offset:25504
	v_mfma_f32_16x16x32_bf16 v[130:133], v[30:33], v[150:153], v[130:133]
	v_mfma_f32_16x16x32_bf16 v[90:93], v[54:57], v[150:153], v[90:93]
	ds_read_b128 v[150:153], v183
	s_waitcnt lgkmcnt(0)
	v_mfma_f32_16x16x32_bf16 v[102:105], v[26:29], v[138:141], v[102:105]
	v_mfma_f32_16x16x32_bf16 v[122:125], v[26:29], v[142:145], v[122:125]
	v_mfma_f32_16x16x32_bf16 v[62:65], v[150:153], v[138:141], v[58:61]
	v_mfma_f32_16x16x32_bf16 v[58:61], v[150:153], v[142:145], v[154:157]
	v_mfma_f32_16x16x32_bf16 v[54:57], v[150:153], v[146:149], v[66:69]
	v_mfma_f32_16x16x32_bf16 v[50:53], v[150:153], v[158:161], v[50:53]
	s_nop 1
	ds_read_b128 v[66:69], v182 offset:3072
	ds_read_b128 v[150:153], v182 offset:7168
	s_waitcnt lgkmcnt(0)
	v_mfma_f32_16x16x32_bf16 v[70:73], v[66:69], v[138:141], v[70:73]
	v_mfma_f32_16x16x32_bf16 v[74:77], v[66:69], v[142:145], v[74:77]
	v_mfma_f32_16x16x32_bf16 v[78:81], v[66:69], v[146:149], v[78:81]
	v_mfma_f32_16x16x32_bf16 v[66:69], v[66:69], v[158:161], v[134:137]
	s_nop 2
	global_load_dwordx4 v[134:137], v[0:1], off offset:1024
	v_mfma_f32_16x16x32_bf16 v[126:129], v[26:29], v[146:149], v[126:129]
	v_mfma_f32_16x16x32_bf16 v[86:89], v[150:153], v[138:141], v[86:89]
	v_mfma_f32_16x16x32_bf16 v[94:97], v[150:153], v[142:145], v[94:97]
	v_mfma_f32_16x16x32_bf16 v[98:101], v[150:153], v[146:149], v[98:101]
	ds_read_b128 v[138:141], v181 offset:192
	ds_read_b128 v[142:145], v181 offset:8640
	ds_read_b128 v[146:149], v181 offset:17088
	ds_read_b128 v[154:157], v181 offset:25536
	v_mfma_f32_16x16x32_bf16 v[130:133], v[26:29], v[158:161], v[130:133]
	v_mfma_f32_16x16x32_bf16 v[90:93], v[150:153], v[158:161], v[90:93]
	ds_read_b128 v[150:153], v182 offset:2048
	ds_read_b128 v[158:161], v182 offset:6144
	s_waitcnt lgkmcnt(0)
	v_mfma_f32_16x16x32_bf16 v[102:105], v[22:25], v[138:141], v[102:105]
	v_mfma_f32_16x16x32_bf16 v[70:73], v[150:153], v[138:141], v[70:73]
	v_mfma_f32_16x16x32_bf16 v[86:89], v[158:161], v[138:141], v[86:89]
	global_load_dwordx4 v[138:141], v[0:1], off offset:2048
	v_mfma_f32_16x16x32_bf16 v[122:125], v[22:25], v[142:145], v[122:125]
	v_mfma_f32_16x16x32_bf16 v[126:129], v[22:25], v[146:149], v[126:129]
	v_mfma_f32_16x16x32_bf16 v[74:77], v[150:153], v[142:145], v[74:77]
	v_mfma_f32_16x16x32_bf16 v[78:81], v[150:153], v[146:149], v[78:81]
	v_mfma_f32_16x16x32_bf16 v[66:69], v[150:153], v[154:157], v[66:69]
	v_mfma_f32_16x16x32_bf16 v[94:97], v[158:161], v[142:145], v[94:97]
	v_mfma_f32_16x16x32_bf16 v[98:101], v[158:161], v[146:149], v[98:101]
	ds_read_b128 v[142:145], v181 offset:224
	ds_read_b128 v[146:149], v181 offset:8672
	ds_read_b128 v[150:153], v181 offset:17120
	ds_read_b128 v[162:165], v181 offset:25568
	v_mfma_f32_16x16x32_bf16 v[130:133], v[22:25], v[154:157], v[130:133]
	v_mfma_f32_16x16x32_bf16 v[90:93], v[158:161], v[154:157], v[90:93]
	ds_read_b128 v[154:157], v182 offset:1024
	ds_read_b128 v[158:161], v182 offset:5120
	s_waitcnt lgkmcnt(0)
; #define LAS __attribute__((address_space(3)))
; template <int H2>
; DEV void s5_p1_all(LAS char* shm, int wid, int fr, int fq, bf16x8 (&wfr)[8], const bf16_t* wsp, f32x4 (&acc)[4][4], f32x4 (&sac)[4]) {
;     ...
;     for (int sp = 0; sp < 16; ++sp) {
;         bf16x8 bn[4], kf[4];
; #pragma unroll
;         for (int q = 0; q < 4; ++q) if (q >= S5_Q0(sp)) kf[q] = *(const LAS bf16x8*)(kb + (8 * q - 2 * sp + 30) * 512);
; #pragma unroll
;         for (int nt = 0; nt < 4; ++nt) bn[nt] = bu[nt];
;         if (sp < 15) {
; #pragma unroll
;             for (int nt = 0; nt < 4; ++nt) bn[nt] = *(const LAS bf16x8*)(ub + nt * 16 * 528 + (sp + 1) * 32);
;         }
; #pragma unroll
;         for (int nt = 0; nt < 4; ++nt) sac[nt] = __builtin_amdgcn_mfma_f32_16x16x32_bf16(wfr[sp & 7], bu[nt], sac[nt], 0, 0, 0);
;         if (sp < 8) wfr[sp & 7] = *(const bf16x8*)(wsp + (size_t)(sp + 8) * 64 * 8);
; #pragma unroll
;         for (int q = 0; q < 4; ++q) {
;             if (q >= S5_Q0(sp)) {
; #pragma unroll
;                 for (int nt = 0; nt < 4; ++nt) acc[q][nt] = __builtin_amdgcn_mfma_f32_16x16x32_bf16(kf[q], bu[nt], acc[q][nt], 0, 0, 0);
;             }
;         }
; #pragma unroll
;         for (int nt = 0; nt < 4; ++nt) bu[nt] = bn[nt];
;         __builtin_amdgcn_sched_barrier(0);
;     }
	v_mfma_f32_16x16x32_bf16 v[102:105], v[18:21], v[142:145], v[102:105]
	v_mfma_f32_16x16x32_bf16 v[70:73], v[154:157], v[142:145], v[70:73]
	v_mfma_f32_16x16x32_bf16 v[86:89], v[158:161], v[142:145], v[86:89]
	global_load_dwordx4 v[142:145], v[0:1], off offset:3072
	v_mfma_f32_16x16x32_bf16 v[122:125], v[18:21], v[146:149], v[122:125]
	v_mfma_f32_16x16x32_bf16 v[126:129], v[18:21], v[150:153], v[126:129]
	v_mfma_f32_16x16x32_bf16 v[74:77], v[154:157], v[146:149], v[74:77]
	v_mfma_f32_16x16x32_bf16 v[78:81], v[154:157], v[150:153], v[78:81]
	v_mfma_f32_16x16x32_bf16 v[66:69], v[154:157], v[162:165], v[66:69]
	v_mfma_f32_16x16x32_bf16 v[94:97], v[158:161], v[146:149], v[94:97]
	v_mfma_f32_16x16x32_bf16 v[98:101], v[158:161], v[150:153], v[98:101]
	ds_read_b128 v[146:149], v181 offset:256
	ds_read_b128 v[150:153], v181 offset:8704
	ds_read_b128 v[154:157], v181 offset:17152
	ds_read_b128 v[184:187], v181 offset:25600
	v_mfma_f32_16x16x32_bf16 v[130:133], v[18:21], v[162:165], v[130:133]
	v_mfma_f32_16x16x32_bf16 v[90:93], v[158:161], v[162:165], v[90:93]
	s_waitcnt vmcnt(0) lgkmcnt(0)
	v_mfma_f32_16x16x32_bf16 v[102:105], v[82:85], v[146:149], v[102:105]
	v_mfma_f32_16x16x32_bf16 v[122:125], v[82:85], v[150:153], v[122:125]
	v_mfma_f32_16x16x32_bf16 v[126:129], v[82:85], v[154:157], v[126:129]
	v_mfma_f32_16x16x32_bf16 v[82:85], v[82:85], v[184:187], v[130:133]
	s_nop 2
	ds_read_b128 v[130:133], v182
	ds_read_b128 v[158:161], v182 offset:4096
	s_waitcnt lgkmcnt(1)
	v_mfma_f32_16x16x32_bf16 v[70:73], v[130:133], v[146:149], v[70:73]
	v_mfma_f32_16x16x32_bf16 v[74:77], v[130:133], v[150:153], v[74:77]
	v_mfma_f32_16x16x32_bf16 v[162:165], v[130:133], v[154:157], v[78:81]
	v_mfma_f32_16x16x32_bf16 v[66:69], v[130:133], v[184:187], v[66:69]
	s_waitcnt lgkmcnt(0)
	v_mfma_f32_16x16x32_bf16 v[86:89], v[158:161], v[146:149], v[86:89]
	v_mfma_f32_16x16x32_bf16 v[94:97], v[158:161], v[150:153], v[94:97]
	v_mfma_f32_16x16x32_bf16 v[98:101], v[158:161], v[154:157], v[98:101]
	ds_read_b128 v[130:133], v181 offset:288
	ds_read_b128 v[146:149], v181 offset:8736
	ds_read_b128 v[150:153], v181 offset:17184
	ds_read_b128 v[154:157], v181 offset:25632
	v_mfma_f32_16x16x32_bf16 v[90:93], v[158:161], v[184:187], v[90:93]
	s_waitcnt lgkmcnt(3)
	v_mfma_f32_16x16x32_bf16 v[102:105], v[106:109], v[130:133], v[102:105]
	s_waitcnt lgkmcnt(2)
	v_mfma_f32_16x16x32_bf16 v[122:125], v[106:109], v[146:149], v[122:125]
	s_waitcnt lgkmcnt(1)
	v_mfma_f32_16x16x32_bf16 v[126:129], v[106:109], v[150:153], v[126:129]
	s_waitcnt lgkmcnt(0)
	v_mfma_f32_16x16x32_bf16 v[82:85], v[106:109], v[154:157], v[82:85]
	ds_read_b128 v[106:109], v183
	ds_read_b128 v[158:161], v182 offset:3072
	s_waitcnt lgkmcnt(1)
	v_mfma_f32_16x16x32_bf16 v[78:81], v[106:109], v[130:133], v[70:73]
	v_mfma_f32_16x16x32_bf16 v[74:77], v[106:109], v[146:149], v[74:77]
	v_mfma_f32_16x16x32_bf16 v[70:73], v[106:109], v[150:153], v[162:165]
	v_mfma_f32_16x16x32_bf16 v[66:69], v[106:109], v[154:157], v[66:69]
	s_waitcnt lgkmcnt(0)
	v_mfma_f32_16x16x32_bf16 v[86:89], v[158:161], v[130:133], v[86:89]
	v_mfma_f32_16x16x32_bf16 v[94:97], v[158:161], v[146:149], v[94:97]
	v_mfma_f32_16x16x32_bf16 v[98:101], v[158:161], v[150:153], v[98:101]
	ds_read_b128 v[106:109], v181 offset:320
	ds_read_b128 v[130:133], v181 offset:8768
	ds_read_b128 v[146:149], v181 offset:17216
	ds_read_b128 v[150:153], v181 offset:25664
	v_mfma_f32_16x16x32_bf16 v[90:93], v[158:161], v[154:157], v[90:93]
	s_waitcnt lgkmcnt(3)
	v_mfma_f32_16x16x32_bf16 v[102:105], v[110:113], v[106:109], v[102:105]
	s_waitcnt lgkmcnt(2)
	v_mfma_f32_16x16x32_bf16 v[122:125], v[110:113], v[130:133], v[122:125]
	s_waitcnt lgkmcnt(1)
	v_mfma_f32_16x16x32_bf16 v[126:129], v[110:113], v[146:149], v[126:129]
	s_waitcnt lgkmcnt(0)
	v_mfma_f32_16x16x32_bf16 v[82:85], v[110:113], v[150:153], v[82:85]
	ds_read_b128 v[110:113], v182 offset:2048
	s_waitcnt lgkmcnt(0)
; #define LAS __attribute__((address_space(3)))
; template <int H2>
; DEV void s5_p1_all(LAS char* shm, int wid, int fr, int fq, bf16x8 (&wfr)[8], const bf16_t* wsp, f32x4 (&acc)[4][4], f32x4 (&sac)[4]) {
;     ...
;     for (int sp = 0; sp < 16; ++sp) {
;         bf16x8 bn[4], kf[4];
; #pragma unroll
;         for (int q = 0; q < 4; ++q) if (q >= S5_Q0(sp)) kf[q] = *(const LAS bf16x8*)(kb + (8 * q - 2 * sp + 30) * 512);
; #pragma unroll
;         for (int nt = 0; nt < 4; ++nt) bn[nt] = bu[nt];
;         if (sp < 15) {
; #pragma unroll
;             for (int nt = 0; nt < 4; ++nt) bn[nt] = *(const LAS bf16x8*)(ub + nt * 16 * 528 + (sp + 1) * 32);
;         }
; #pragma unroll
;         for (int nt = 0; nt < 4; ++nt) sac[nt] = __builtin_amdgcn_mfma_f32_16x16x32_bf16(wfr[sp & 7], bu[nt], sac[nt], 0, 0, 0);
;         if (sp < 8) wfr[sp & 7] = *(const bf16x8*)(wsp + (size_t)(sp + 8) * 64 * 8);
; #pragma unroll
;         for (int q = 0; q < 4; ++q) {
;             if (q >= S5_Q0(sp)) {
; #pragma unroll
;                 for (int nt = 0; nt < 4; ++nt) acc[q][nt] = __builtin_amdgcn_mfma_f32_16x16x32_bf16(kf[q], bu[nt], acc[q][nt], 0, 0, 0);
;             }
;         }
; #pragma unroll
;         for (int nt = 0; nt < 4; ++nt) bu[nt] = bn[nt];
;         __builtin_amdgcn_sched_barrier(0);
;     }
	v_mfma_f32_16x16x32_bf16 v[86:89], v[110:113], v[106:109], v[86:89]
	v_mfma_f32_16x16x32_bf16 v[94:97], v[110:113], v[130:133], v[94:97]
	v_mfma_f32_16x16x32_bf16 v[98:101], v[110:113], v[146:149], v[98:101]
	ds_read_b128 v[106:109], v181 offset:352
	ds_read_b128 v[130:133], v181 offset:8800
	ds_read_b128 v[146:149], v181 offset:17248
	ds_read_b128 v[154:157], v181 offset:25696
	v_mfma_f32_16x16x32_bf16 v[90:93], v[110:113], v[150:153], v[90:93]
	s_waitcnt lgkmcnt(3)
	v_mfma_f32_16x16x32_bf16 v[102:105], v[114:117], v[106:109], v[102:105]
	s_waitcnt lgkmcnt(2)
	v_mfma_f32_16x16x32_bf16 v[110:113], v[114:117], v[130:133], v[122:125]
	s_waitcnt lgkmcnt(1)
	v_mfma_f32_16x16x32_bf16 v[122:125], v[114:117], v[146:149], v[126:129]
	s_waitcnt lgkmcnt(0)
	v_mfma_f32_16x16x32_bf16 v[82:85], v[114:117], v[154:157], v[82:85]
	ds_read_b128 v[114:117], v182 offset:1024
	s_waitcnt lgkmcnt(0)
	v_mfma_f32_16x16x32_bf16 v[86:89], v[114:117], v[106:109], v[86:89]
	v_mfma_f32_16x16x32_bf16 v[94:97], v[114:117], v[130:133], v[94:97]
	v_mfma_f32_16x16x32_bf16 v[98:101], v[114:117], v[146:149], v[98:101]
	ds_read_b128 v[106:109], v181 offset:384
	ds_read_b128 v[126:129], v181 offset:8832
	ds_read_b128 v[130:133], v181 offset:17280
	ds_read_b128 v[146:149], v181 offset:25728
	v_mfma_f32_16x16x32_bf16 v[90:93], v[114:117], v[154:157], v[90:93]
	s_waitcnt lgkmcnt(3)
	v_mfma_f32_16x16x32_bf16 v[102:105], v[118:121], v[106:109], v[102:105]
	s_waitcnt lgkmcnt(2)
	v_mfma_f32_16x16x32_bf16 v[110:113], v[118:121], v[126:129], v[110:113]
	s_waitcnt lgkmcnt(1)
	v_mfma_f32_16x16x32_bf16 v[114:117], v[118:121], v[130:133], v[122:125]
	s_waitcnt lgkmcnt(0)
	v_mfma_f32_16x16x32_bf16 v[82:85], v[118:121], v[146:149], v[82:85]
	ds_read_b128 v[118:121], v182
	s_waitcnt lgkmcnt(0)
	v_mfma_f32_16x16x32_bf16 v[86:89], v[118:121], v[106:109], v[86:89]
	v_mfma_f32_16x16x32_bf16 v[94:97], v[118:121], v[126:129], v[94:97]
	v_mfma_f32_16x16x32_bf16 v[98:101], v[118:121], v[130:133], v[98:101]
	ds_read_b128 v[106:109], v181 offset:416
	ds_read_b128 v[122:125], v181 offset:8864
	ds_read_b128 v[126:129], v181 offset:17312
	ds_read_b128 v[130:133], v181 offset:25760
	v_mfma_f32_16x16x32_bf16 v[90:93], v[118:121], v[146:149], v[90:93]
	s_waitcnt lgkmcnt(1)
	v_mfma_f32_16x16x32_bf16 v[150:153], v[134:137], v[126:129], v[114:117]
	s_nop 2
	ds_read_b128 v[114:117], v183
	v_mfma_f32_16x16x32_bf16 v[118:121], v[134:137], v[106:109], v[102:105]
	v_mfma_f32_16x16x32_bf16 v[146:149], v[134:137], v[122:125], v[110:113]
	s_waitcnt lgkmcnt(0)
	v_mfma_f32_16x16x32_bf16 v[110:113], v[114:117], v[106:109], v[86:89]
	v_mfma_f32_16x16x32_bf16 v[106:109], v[114:117], v[122:125], v[94:97]
	v_mfma_f32_16x16x32_bf16 v[102:105], v[114:117], v[126:129], v[98:101]
	s_nop 0
	ds_read_b128 v[86:89], v181 offset:448
	ds_read_b128 v[94:97], v181 offset:8896
	ds_read_b128 v[98:101], v181 offset:17344
	ds_read_b128 v[122:125], v181 offset:25792
	v_mfma_f32_16x16x32_bf16 v[114:117], v[114:117], v[130:133], v[90:93]
	v_mfma_f32_16x16x32_bf16 v[82:85], v[134:137], v[130:133], v[82:85]
	s_waitcnt lgkmcnt(3)
	v_mfma_f32_16x16x32_bf16 v[86:89], v[138:141], v[86:89], v[118:121]
	s_waitcnt lgkmcnt(2)
	v_mfma_f32_16x16x32_bf16 v[90:93], v[138:141], v[94:97], v[146:149]
	s_waitcnt lgkmcnt(1)
	v_mfma_f32_16x16x32_bf16 v[94:97], v[138:141], v[98:101], v[150:153]
	ds_read_b128 v[98:101], v181 offset:480
	ds_read_b128 v[118:121], v181 offset:8928
	ds_read_b128 v[126:129], v181 offset:17376
	ds_read_b128 v[130:133], v181 offset:25824
	s_waitcnt lgkmcnt(4)
	v_mfma_f32_16x16x32_bf16 v[82:85], v[138:141], v[122:125], v[82:85]
	s_waitcnt lgkmcnt(3)
	v_mfma_f32_16x16x32_bf16 v[162:165], v[142:145], v[98:101], v[86:89]
	s_waitcnt lgkmcnt(2)
	v_mfma_f32_16x16x32_bf16 v[158:161], v[142:145], v[118:121], v[90:93]
	s_waitcnt lgkmcnt(1)
	v_mfma_f32_16x16x32_bf16 v[154:157], v[142:145], v[126:129], v[94:97]
	s_waitcnt lgkmcnt(0)
	v_mfma_f32_16x16x32_bf16 v[150:153], v[142:145], v[130:133], v[82:85]

; #define LAS __attribute__((address_space(3)))
; template <int H2>
; DEV void s5_p1_all(LAS char* shm, int wid, int fr, int fq, bf16x8 (&wfr)[8], const bf16_t* wsp, f32x4 (&acc)[4][4], f32x4 (&sac)[4]) {
;     ...
;     for (int sp = 0; sp < 16; ++sp) {
;         bf16x8 bn[4], kf[4];
; #pragma unroll
;         for (int q = 0; q < 4; ++q) if (q >= S5_Q0(sp)) kf[q] = *(const LAS bf16x8*)(kb + (8 * q - 2 * sp + 30) * 512);
; #pragma unroll
;         for (int nt = 0; nt < 4; ++nt) bn[nt] = bu[nt];
;         if (sp < 15) {
; #pragma unroll
;             for (int nt = 0; nt < 4; ++nt) bn[nt] = *(const LAS bf16x8*)(ub + nt * 16 * 528 + (sp + 1) * 32);
;         }
; #pragma unroll
;         for (int nt = 0; nt < 4; ++nt) sac[nt] = __builtin_amdgcn_mfma_f32_16x16x32_bf16(wfr[sp & 7], bu[nt], sac[nt], 0, 0, 0);
;         if (sp < 8) wfr[sp & 7] = *(const bf16x8*)(wsp + (size_t)(sp + 8) * 64 * 8);
; #pragma unroll
;         for (int q = 0; q < 4; ++q) {
;             if (q >= S5_Q0(sp)) {
; #pragma unroll
;                 for (int nt = 0; nt < 4; ++nt) acc[q][nt] = __builtin_amdgcn_mfma_f32_16x16x32_bf16(kf[q], bu[nt], acc[q][nt], 0, 0, 0);
;             }
;         }
; #pragma unroll
;         for (int nt = 0; nt < 4; ++nt) bu[nt] = bn[nt];
;         __builtin_amdgcn_sched_barrier(0);
;     }
.LBB0_1153:
	s_and_b64 vcc, exec, s[0:1]
	s_cbranch_vccz .LBB0_1155
	v_xor_b32_e32 v0, 0x200, v178
	s_lshl_b32 s0, s43, 9
	v_add3_u32 v0, s31, v0, v170
	v_add3_u32 v151, v0, v177, s0
	v_add_co_u32_e32 v0, vcc, s34, v168
	v_add3_u32 v150, v179, v176, v180
	s_nop 0
	v_addc_co_u32_e32 v1, vcc, 0, v169, vcc
	ds_read_b128 v[50:53], v150
	ds_read_b128 v[54:57], v150 offset:8448
	ds_read_b128 v[58:61], v150 offset:32
	ds_read_b128 v[66:69], v150 offset:16896
	ds_read_b128 v[70:73], v150 offset:8480
	ds_read_b128 v[78:81], v150 offset:25344
	s_waitcnt vmcnt(0)
	ds_read_b128 v[82:85], v150 offset:16928
	ds_read_b128 v[90:93], v150 offset:25376
	ds_read_b128 v[2:5], v151
	ds_read_b128 v[94:97], v151 offset:4096
	ds_read_b128 v[110:113], v151 offset:8192
	ds_read_b128 v[114:117], v151 offset:12288
	global_load_dwordx4 v[130:133], v[0:1], off
	s_waitcnt lgkmcnt(0)
	v_mfma_f32_16x16x32_bf16 v[62:65], v[46:49], v[50:53], 0
	v_mfma_f32_16x16x32_bf16 v[74:77], v[46:49], v[54:57], 0
	v_mfma_f32_16x16x32_bf16 v[86:89], v[46:49], v[66:69], 0
	v_mfma_f32_16x16x32_bf16 v[46:49], v[46:49], v[78:81], 0
	v_mfma_f32_16x16x32_bf16 v[14:17], v[2:5], v[50:53], 0
	v_mfma_f32_16x16x32_bf16 v[10:13], v[2:5], v[54:57], 0
	v_mfma_f32_16x16x32_bf16 v[6:9], v[2:5], v[66:69], 0
	v_mfma_f32_16x16x32_bf16 v[2:5], v[2:5], v[78:81], 0
	v_mfma_f32_16x16x32_bf16 v[98:101], v[94:97], v[50:53], 0
	v_mfma_f32_16x16x32_bf16 v[102:105], v[94:97], v[54:57], 0
	v_mfma_f32_16x16x32_bf16 v[106:109], v[94:97], v[66:69], 0
	v_mfma_f32_16x16x32_bf16 v[94:97], v[94:97], v[78:81], 0
	v_mfma_f32_16x16x32_bf16 v[118:121], v[110:113], v[50:53], 0
	v_mfma_f32_16x16x32_bf16 v[122:125], v[110:113], v[54:57], 0
	v_mfma_f32_16x16x32_bf16 v[126:129], v[110:113], v[66:69], 0
	v_mfma_f32_16x16x32_bf16 v[110:113], v[110:113], v[78:81], 0
	v_mfma_f32_16x16x32_bf16 v[50:53], v[114:117], v[50:53], 0
	v_mfma_f32_16x16x32_bf16 v[54:57], v[114:117], v[54:57], 0
	v_mfma_f32_16x16x32_bf16 v[66:69], v[114:117], v[66:69], 0
	v_mfma_f32_16x16x32_bf16 v[78:81], v[114:117], v[78:81], 0
	v_mfma_f32_16x16x32_bf16 v[62:65], v[42:45], v[58:61], v[62:65]
	v_mfma_f32_16x16x32_bf16 v[74:77], v[42:45], v[70:73], v[74:77]
	v_mfma_f32_16x16x32_bf16 v[86:89], v[42:45], v[82:85], v[86:89]
	v_mfma_f32_16x16x32_bf16 v[42:45], v[42:45], v[90:93], v[46:49]
	s_nop 2
	ds_read_b128 v[46:49], v151 offset:3072
	ds_read_b128 v[114:117], v151 offset:7168
	s_waitcnt lgkmcnt(0)
	v_mfma_f32_16x16x32_bf16 v[98:101], v[46:49], v[58:61], v[98:101]
	v_mfma_f32_16x16x32_bf16 v[102:105], v[46:49], v[70:73], v[102:105]
	v_mfma_f32_16x16x32_bf16 v[106:109], v[46:49], v[82:85], v[106:109]
	v_mfma_f32_16x16x32_bf16 v[46:49], v[46:49], v[90:93], v[94:97]
	v_mfma_f32_16x16x32_bf16 v[94:97], v[114:117], v[58:61], v[118:121]
	v_mfma_f32_16x16x32_bf16 v[118:121], v[114:117], v[70:73], v[122:125]
	v_mfma_f32_16x16x32_bf16 v[122:125], v[114:117], v[82:85], v[126:129]
	s_nop 2
	global_load_dwordx4 v[126:129], v[0:1], off offset:1024
	v_mfma_f32_16x16x32_bf16 v[110:113], v[114:117], v[90:93], v[110:113]
	ds_read_b128 v[114:117], v151 offset:11264
	s_waitcnt lgkmcnt(0)
	v_mfma_f32_16x16x32_bf16 v[50:53], v[114:117], v[58:61], v[50:53]
	v_mfma_f32_16x16x32_bf16 v[54:57], v[114:117], v[70:73], v[54:57]
	v_mfma_f32_16x16x32_bf16 v[58:61], v[114:117], v[82:85], v[66:69]
	s_nop 2
	ds_read_b128 v[66:69], v150 offset:64
	ds_read_b128 v[70:73], v150 offset:8512
	ds_read_b128 v[82:85], v150 offset:16960
	ds_read_b128 v[134:137], v150 offset:25408
	v_mfma_f32_16x16x32_bf16 v[78:81], v[114:117], v[90:93], v[78:81]
	s_waitcnt lgkmcnt(0)
	v_mfma_f32_16x16x32_bf16 v[62:65], v[38:41], v[66:69], v[62:65]
	v_mfma_f32_16x16x32_bf16 v[74:77], v[38:41], v[70:73], v[74:77]
	v_mfma_f32_16x16x32_bf16 v[86:89], v[38:41], v[82:85], v[86:89]
	v_mfma_f32_16x16x32_bf16 v[38:41], v[38:41], v[134:137], v[42:45]
	s_nop 2
	ds_read_b128 v[42:45], v151 offset:2048
	ds_read_b128 v[90:93], v151 offset:6144
	s_waitcnt lgkmcnt(0)
	v_mfma_f32_16x16x32_bf16 v[98:101], v[42:45], v[66:69], v[98:101]
	v_mfma_f32_16x16x32_bf16 v[102:105], v[42:45], v[70:73], v[102:105]
	v_mfma_f32_16x16x32_bf16 v[106:109], v[42:45], v[82:85], v[106:109]
	v_mfma_f32_16x16x32_bf16 v[42:45], v[42:45], v[134:137], v[46:49]
	v_mfma_f32_16x16x32_bf16 v[46:49], v[90:93], v[66:69], v[94:97]
	v_mfma_f32_16x16x32_bf16 v[94:97], v[90:93], v[70:73], v[118:121]
	s_nop 2
	global_load_dwordx4 v[118:121], v[0:1], off offset:2048
	v_mfma_f32_16x16x32_bf16 v[114:117], v[90:93], v[82:85], v[122:125]
	v_mfma_f32_16x16x32_bf16 v[90:93], v[90:93], v[134:137], v[110:113]
	s_nop 2
	ds_read_b128 v[110:113], v151 offset:10240
	s_waitcnt lgkmcnt(0)
	v_mfma_f32_16x16x32_bf16 v[50:53], v[110:113], v[66:69], v[50:53]
	v_mfma_f32_16x16x32_bf16 v[54:57], v[110:113], v[70:73], v[54:57]
	v_mfma_f32_16x16x32_bf16 v[58:61], v[110:113], v[82:85], v[58:61]
	ds_read_b128 v[66:69], v150 offset:96
	ds_read_b128 v[70:73], v150 offset:8544
	ds_read_b128 v[82:85], v150 offset:16992
	ds_read_b128 v[122:125], v150 offset:25440
	v_mfma_f32_16x16x32_bf16 v[78:81], v[110:113], v[134:137], v[78:81]
	s_waitcnt lgkmcnt(0)
	v_mfma_f32_16x16x32_bf16 v[62:65], v[34:37], v[66:69], v[62:65]
	v_mfma_f32_16x16x32_bf16 v[74:77], v[34:37], v[70:73], v[74:77]
	v_mfma_f32_16x16x32_bf16 v[86:89], v[34:37], v[82:85], v[86:89]
	v_mfma_f32_16x16x32_bf16 v[34:37], v[34:37], v[122:125], v[38:41]
	s_nop 2
	ds_read_b128 v[38:41], v151 offset:1024
	ds_read_b128 v[110:113], v151 offset:5120
	s_waitcnt lgkmcnt(0)
; #define LAS __attribute__((address_space(3)))
; template <int H2>
; DEV void s5_p1_all(LAS char* shm, int wid, int fr, int fq, bf16x8 (&wfr)[8], const bf16_t* wsp, f32x4 (&acc)[4][4], f32x4 (&sac)[4]) {
;     ...
;     for (int sp = 0; sp < 16; ++sp) {
;         bf16x8 bn[4], kf[4];
; #pragma unroll
;         for (int q = 0; q < 4; ++q) if (q >= S5_Q0(sp)) kf[q] = *(const LAS bf16x8*)(kb + (8 * q - 2 * sp + 30) * 512);
; #pragma unroll
;         for (int nt = 0; nt < 4; ++nt) bn[nt] = bu[nt];
;         if (sp < 15) {
; #pragma unroll
;             for (int nt = 0; nt < 4; ++nt) bn[nt] = *(const LAS bf16x8*)(ub + nt * 16 * 528 + (sp + 1) * 32);
;         }
; #pragma unroll
;         for (int nt = 0; nt < 4; ++nt) sac[nt] = __builtin_amdgcn_mfma_f32_16x16x32_bf16(wfr[sp & 7], bu[nt], sac[nt], 0, 0, 0);
;         if (sp < 8) wfr[sp & 7] = *(const bf16x8*)(wsp + (size_t)(sp + 8) * 64 * 8);
; #pragma unroll
;         for (int q = 0; q < 4; ++q) {
;             if (q >= S5_Q0(sp)) {
; #pragma unroll
;                 for (int nt = 0; nt < 4; ++nt) acc[q][nt] = __builtin_amdgcn_mfma_f32_16x16x32_bf16(kf[q], bu[nt], acc[q][nt], 0, 0, 0);
;             }
;         }
; #pragma unroll
;         for (int nt = 0; nt < 4; ++nt) bu[nt] = bn[nt];
;         __builtin_amdgcn_sched_barrier(0);
;     }
	v_mfma_f32_16x16x32_bf16 v[98:101], v[38:41], v[66:69], v[98:101]
	v_mfma_f32_16x16x32_bf16 v[102:105], v[38:41], v[70:73], v[102:105]
	v_mfma_f32_16x16x32_bf16 v[106:109], v[38:41], v[82:85], v[106:109]
	v_mfma_f32_16x16x32_bf16 v[38:41], v[38:41], v[122:125], v[42:45]
	v_mfma_f32_16x16x32_bf16 v[42:45], v[110:113], v[66:69], v[46:49]
	v_mfma_f32_16x16x32_bf16 v[46:49], v[110:113], v[70:73], v[94:97]
	v_mfma_f32_16x16x32_bf16 v[94:97], v[110:113], v[82:85], v[114:117]
	s_nop 2
	global_load_dwordx4 v[114:117], v[0:1], off offset:3072
	v_mfma_f32_16x16x32_bf16 v[90:93], v[110:113], v[122:125], v[90:93]
	ds_read_b128 v[110:113], v151 offset:9216
	ds_read_b128 v[134:137], v150 offset:128
	ds_read_b128 v[138:141], v150 offset:8576
	ds_read_b128 v[142:145], v150 offset:17024
	ds_read_b128 v[146:149], v150 offset:25472
	s_waitcnt lgkmcnt(0)
	v_mfma_f32_16x16x32_bf16 v[66:69], v[110:113], v[66:69], v[50:53]
	v_mfma_f32_16x16x32_bf16 v[70:73], v[110:113], v[70:73], v[54:57]
	v_mfma_f32_16x16x32_bf16 v[78:81], v[110:113], v[122:125], v[78:81]
	v_mfma_f32_16x16x32_bf16 v[82:85], v[110:113], v[82:85], v[58:61]
	v_mfma_f32_16x16x32_bf16 v[110:113], v[30:33], v[134:137], v[62:65]
	v_add_co_u32_e32 v0, vcc, s36, v168
	v_mfma_f32_16x16x32_bf16 v[74:77], v[30:33], v[138:141], v[74:77]
	s_nop 0
	v_addc_co_u32_e32 v1, vcc, 0, v169, vcc
	v_mfma_f32_16x16x32_bf16 v[86:89], v[30:33], v[142:145], v[86:89]
	v_mfma_f32_16x16x32_bf16 v[30:33], v[30:33], v[146:149], v[34:37]
	s_nop 2
	ds_read_b128 v[34:37], v151
	ds_read_b128 v[122:125], v151 offset:4096
	s_waitcnt lgkmcnt(0)
	v_mfma_f32_16x16x32_bf16 v[62:65], v[34:37], v[134:137], v[98:101]
	v_mfma_f32_16x16x32_bf16 v[58:61], v[34:37], v[138:141], v[102:105]
	v_mfma_f32_16x16x32_bf16 v[54:57], v[34:37], v[142:145], v[106:109]
	v_mfma_f32_16x16x32_bf16 v[50:53], v[34:37], v[146:149], v[38:41]
	v_mfma_f32_16x16x32_bf16 v[34:37], v[122:125], v[134:137], v[42:45]
	v_mfma_f32_16x16x32_bf16 v[42:45], v[122:125], v[142:145], v[94:97]
	s_nop 2
	global_load_dwordx4 v[94:97], v[0:1], off
	v_mfma_f32_16x16x32_bf16 v[38:41], v[122:125], v[138:141], v[46:49]
	v_mfma_f32_16x16x32_bf16 v[46:49], v[122:125], v[146:149], v[90:93]
	s_nop 2
	ds_read_b128 v[90:93], v151 offset:8192
	ds_read_b128 v[98:101], v150 offset:160
	ds_read_b128 v[102:105], v150 offset:8608
	ds_read_b128 v[106:109], v150 offset:17056
	ds_read_b128 v[122:125], v150 offset:25504
	s_waitcnt lgkmcnt(0)
	v_mfma_f32_16x16x32_bf16 v[66:69], v[90:93], v[134:137], v[66:69]
	v_mfma_f32_16x16x32_bf16 v[70:73], v[90:93], v[138:141], v[70:73]
	v_mfma_f32_16x16x32_bf16 v[78:81], v[90:93], v[146:149], v[78:81]
	v_mfma_f32_16x16x32_bf16 v[82:85], v[90:93], v[142:145], v[82:85]
	v_mfma_f32_16x16x32_bf16 v[90:93], v[26:29], v[98:101], v[110:113]
	v_mfma_f32_16x16x32_bf16 v[74:77], v[26:29], v[102:105], v[74:77]
	v_mfma_f32_16x16x32_bf16 v[86:89], v[26:29], v[106:109], v[86:89]
	v_mfma_f32_16x16x32_bf16 v[26:29], v[26:29], v[122:125], v[30:33]
	s_nop 2
	ds_read_b128 v[30:33], v151 offset:3072
	ds_read_b128 v[110:113], v151 offset:7168
	s_waitcnt lgkmcnt(0)
	v_mfma_f32_16x16x32_bf16 v[34:37], v[30:33], v[98:101], v[34:37]
	v_mfma_f32_16x16x32_bf16 v[38:41], v[30:33], v[102:105], v[38:41]
	v_mfma_f32_16x16x32_bf16 v[42:45], v[30:33], v[106:109], v[42:45]
	v_mfma_f32_16x16x32_bf16 v[30:33], v[30:33], v[122:125], v[46:49]
	v_mfma_f32_16x16x32_bf16 v[46:49], v[110:113], v[98:101], v[66:69]
	global_load_dwordx4 v[98:101], v[0:1], off offset:1024
	v_mfma_f32_16x16x32_bf16 v[66:69], v[110:113], v[102:105], v[70:73]
	v_mfma_f32_16x16x32_bf16 v[70:73], v[110:113], v[106:109], v[82:85]
	s_nop 2
	ds_read_b128 v[82:85], v150 offset:192
	ds_read_b128 v[102:105], v150 offset:8640
	ds_read_b128 v[106:109], v150 offset:17088
	ds_read_b128 v[134:137], v150 offset:25536
	v_mfma_f32_16x16x32_bf16 v[78:81], v[110:113], v[122:125], v[78:81]
	s_waitcnt lgkmcnt(0)
	v_mfma_f32_16x16x32_bf16 v[90:93], v[22:25], v[82:85], v[90:93]
	v_mfma_f32_16x16x32_bf16 v[74:77], v[22:25], v[102:105], v[74:77]
	v_mfma_f32_16x16x32_bf16 v[86:89], v[22:25], v[106:109], v[86:89]
	v_mfma_f32_16x16x32_bf16 v[22:25], v[22:25], v[134:137], v[26:29]
	s_nop 2
	ds_read_b128 v[26:29], v151 offset:2048
	ds_read_b128 v[110:113], v151 offset:6144
	s_waitcnt lgkmcnt(0)
	v_mfma_f32_16x16x32_bf16 v[34:37], v[26:29], v[82:85], v[34:37]
	v_mfma_f32_16x16x32_bf16 v[38:41], v[26:29], v[102:105], v[38:41]
	v_mfma_f32_16x16x32_bf16 v[42:45], v[26:29], v[106:109], v[42:45]
	v_mfma_f32_16x16x32_bf16 v[26:29], v[26:29], v[134:137], v[30:33]
	v_mfma_f32_16x16x32_bf16 v[30:33], v[110:113], v[82:85], v[46:49]
	global_load_dwordx4 v[82:85], v[0:1], off offset:2048
	v_mfma_f32_16x16x32_bf16 v[46:49], v[110:113], v[102:105], v[66:69]
	v_mfma_f32_16x16x32_bf16 v[66:69], v[110:113], v[106:109], v[70:73]
	s_nop 2
	ds_read_b128 v[70:73], v150 offset:224
	ds_read_b128 v[102:105], v150 offset:8672
	ds_read_b128 v[106:109], v150 offset:17120
	ds_read_b128 v[122:125], v150 offset:25568
	v_mfma_f32_16x16x32_bf16 v[78:81], v[110:113], v[134:137], v[78:81]
	s_waitcnt lgkmcnt(0)
	v_mfma_f32_16x16x32_bf16 v[90:93], v[18:21], v[70:73], v[90:93]
	v_mfma_f32_16x16x32_bf16 v[74:77], v[18:21], v[102:105], v[74:77]
	v_mfma_f32_16x16x32_bf16 v[86:89], v[18:21], v[106:109], v[86:89]
	v_mfma_f32_16x16x32_bf16 v[18:21], v[18:21], v[122:125], v[22:25]
	s_nop 2
	ds_read_b128 v[22:25], v151 offset:1024
	ds_read_b128 v[110:113], v151 offset:5120
	s_waitcnt lgkmcnt(0)
; #define LAS __attribute__((address_space(3)))
; template <int H2>
; DEV void s5_p1_all(LAS char* shm, int wid, int fr, int fq, bf16x8 (&wfr)[8], const bf16_t* wsp, f32x4 (&acc)[4][4], f32x4 (&sac)[4]) {
;     ...
;     for (int sp = 0; sp < 16; ++sp) {
;         bf16x8 bn[4], kf[4];
; #pragma unroll
;         for (int q = 0; q < 4; ++q) if (q >= S5_Q0(sp)) kf[q] = *(const LAS bf16x8*)(kb + (8 * q - 2 * sp + 30) * 512);
; #pragma unroll
;         for (int nt = 0; nt < 4; ++nt) bn[nt] = bu[nt];
;         if (sp < 15) {
; #pragma unroll
;             for (int nt = 0; nt < 4; ++nt) bn[nt] = *(const LAS bf16x8*)(ub + nt * 16 * 528 + (sp + 1) * 32);
;         }
; #pragma unroll
;         for (int nt = 0; nt < 4; ++nt) sac[nt] = __builtin_amdgcn_mfma_f32_16x16x32_bf16(wfr[sp & 7], bu[nt], sac[nt], 0, 0, 0);
;         if (sp < 8) wfr[sp & 7] = *(const bf16x8*)(wsp + (size_t)(sp + 8) * 64 * 8);
; #pragma unroll
;         for (int q = 0; q < 4; ++q) {
;             if (q >= S5_Q0(sp)) {
; #pragma unroll
;                 for (int nt = 0; nt < 4; ++nt) acc[q][nt] = __builtin_amdgcn_mfma_f32_16x16x32_bf16(kf[q], bu[nt], acc[q][nt], 0, 0, 0);
;             }
;         }
; #pragma unroll
;         for (int nt = 0; nt < 4; ++nt) bu[nt] = bn[nt];
;         __builtin_amdgcn_sched_barrier(0);
;     }
	v_mfma_f32_16x16x32_bf16 v[34:37], v[22:25], v[70:73], v[34:37]
	v_mfma_f32_16x16x32_bf16 v[38:41], v[22:25], v[102:105], v[38:41]
	v_mfma_f32_16x16x32_bf16 v[42:45], v[22:25], v[106:109], v[42:45]
	v_mfma_f32_16x16x32_bf16 v[22:25], v[22:25], v[122:125], v[26:29]
	v_mfma_f32_16x16x32_bf16 v[26:29], v[110:113], v[70:73], v[30:33]
	v_mfma_f32_16x16x32_bf16 v[30:33], v[110:113], v[102:105], v[46:49]
	s_nop 2
	global_load_dwordx4 v[46:49], v[0:1], off offset:3072
	v_mfma_f32_16x16x32_bf16 v[102:105], v[110:113], v[106:109], v[66:69]
	ds_read_b128 v[106:109], v150 offset:256
	ds_read_b128 v[134:137], v150 offset:8704
	ds_read_b128 v[138:141], v150 offset:17152
	ds_read_b128 v[142:145], v150 offset:25600
	v_mfma_f32_16x16x32_bf16 v[110:113], v[110:113], v[122:125], v[78:81]
	s_waitcnt vmcnt(0) lgkmcnt(0)
	v_mfma_f32_16x16x32_bf16 v[90:93], v[130:133], v[106:109], v[90:93]
	v_mfma_f32_16x16x32_bf16 v[122:125], v[130:133], v[134:137], v[74:77]
	v_mfma_f32_16x16x32_bf16 v[86:89], v[130:133], v[138:141], v[86:89]
	v_mfma_f32_16x16x32_bf16 v[18:21], v[130:133], v[142:145], v[18:21]
	ds_read_b128 v[66:69], v151
	ds_read_b128 v[130:133], v151 offset:4096
	s_waitcnt lgkmcnt(1)
	v_mfma_f32_16x16x32_bf16 v[78:81], v[66:69], v[106:109], v[34:37]
	v_mfma_f32_16x16x32_bf16 v[74:77], v[66:69], v[134:137], v[38:41]
	v_mfma_f32_16x16x32_bf16 v[70:73], v[66:69], v[138:141], v[42:45]
	v_mfma_f32_16x16x32_bf16 v[66:69], v[66:69], v[142:145], v[22:25]
	s_waitcnt lgkmcnt(0)
	v_mfma_f32_16x16x32_bf16 v[22:25], v[130:133], v[106:109], v[26:29]
	v_mfma_f32_16x16x32_bf16 v[26:29], v[130:133], v[134:137], v[30:33]
	v_mfma_f32_16x16x32_bf16 v[30:33], v[130:133], v[138:141], v[102:105]
	ds_read_b128 v[34:37], v150 offset:288
	ds_read_b128 v[38:41], v150 offset:8736
	ds_read_b128 v[42:45], v150 offset:17184
	ds_read_b128 v[102:105], v150 offset:25632
	v_mfma_f32_16x16x32_bf16 v[106:109], v[130:133], v[142:145], v[110:113]
	s_waitcnt lgkmcnt(2)
	v_mfma_f32_16x16x32_bf16 v[110:113], v[126:129], v[38:41], v[122:125]
	s_nop 2
	ds_read_b128 v[122:125], v151 offset:3072
	v_mfma_f32_16x16x32_bf16 v[90:93], v[126:129], v[34:37], v[90:93]
	s_waitcnt lgkmcnt(2)
	v_mfma_f32_16x16x32_bf16 v[86:89], v[126:129], v[42:45], v[86:89]
	s_waitcnt lgkmcnt(1)
	v_mfma_f32_16x16x32_bf16 v[18:21], v[126:129], v[102:105], v[18:21]
	s_waitcnt lgkmcnt(0)
	v_mfma_f32_16x16x32_bf16 v[22:25], v[122:125], v[34:37], v[22:25]
	v_mfma_f32_16x16x32_bf16 v[26:29], v[122:125], v[38:41], v[26:29]
	v_mfma_f32_16x16x32_bf16 v[30:33], v[122:125], v[42:45], v[30:33]
	ds_read_b128 v[34:37], v150 offset:320
	ds_read_b128 v[38:41], v150 offset:8768
	ds_read_b128 v[42:45], v150 offset:17216
	ds_read_b128 v[126:129], v150 offset:25664
	v_mfma_f32_16x16x32_bf16 v[102:105], v[122:125], v[102:105], v[106:109]
	s_waitcnt lgkmcnt(2)
	v_mfma_f32_16x16x32_bf16 v[106:109], v[118:121], v[38:41], v[110:113]
	s_nop 2
	ds_read_b128 v[110:113], v151 offset:2048
	v_mfma_f32_16x16x32_bf16 v[90:93], v[118:121], v[34:37], v[90:93]
	s_waitcnt lgkmcnt(2)
	v_mfma_f32_16x16x32_bf16 v[86:89], v[118:121], v[42:45], v[86:89]
	s_waitcnt lgkmcnt(1)
	v_mfma_f32_16x16x32_bf16 v[18:21], v[118:121], v[126:129], v[18:21]
	s_waitcnt lgkmcnt(0)
	v_mfma_f32_16x16x32_bf16 v[22:25], v[110:113], v[34:37], v[22:25]
	v_mfma_f32_16x16x32_bf16 v[26:29], v[110:113], v[38:41], v[26:29]
	v_mfma_f32_16x16x32_bf16 v[30:33], v[110:113], v[42:45], v[30:33]
	ds_read_b128 v[34:37], v150 offset:352
	ds_read_b128 v[38:41], v150 offset:8800
	ds_read_b128 v[42:45], v150 offset:17248
	ds_read_b128 v[118:121], v150 offset:25696
	v_mfma_f32_16x16x32_bf16 v[102:105], v[110:113], v[126:129], v[102:105]
	ds_read_b128 v[110:113], v151 offset:1024
	s_waitcnt lgkmcnt(4)
	v_mfma_f32_16x16x32_bf16 v[90:93], v[114:117], v[34:37], v[90:93]
	s_waitcnt lgkmcnt(3)
	v_mfma_f32_16x16x32_bf16 v[106:109], v[114:117], v[38:41], v[106:109]
	s_waitcnt lgkmcnt(2)
	v_mfma_f32_16x16x32_bf16 v[86:89], v[114:117], v[42:45], v[86:89]
	s_waitcnt lgkmcnt(1)
	v_mfma_f32_16x16x32_bf16 v[18:21], v[114:117], v[118:121], v[18:21]
	s_waitcnt lgkmcnt(0)
	v_mfma_f32_16x16x32_bf16 v[22:25], v[110:113], v[34:37], v[22:25]
	v_mfma_f32_16x16x32_bf16 v[26:29], v[110:113], v[38:41], v[26:29]
	v_mfma_f32_16x16x32_bf16 v[30:33], v[110:113], v[42:45], v[30:33]
	ds_read_b128 v[34:37], v150 offset:384
	ds_read_b128 v[38:41], v150 offset:8832
	ds_read_b128 v[42:45], v150 offset:17280
	ds_read_b128 v[114:117], v150 offset:25728
	v_mfma_f32_16x16x32_bf16 v[118:121], v[110:113], v[118:121], v[102:105]
	s_waitcnt lgkmcnt(3)
	v_mfma_f32_16x16x32_bf16 v[90:93], v[94:97], v[34:37], v[90:93]
	s_waitcnt lgkmcnt(2)
	v_mfma_f32_16x16x32_bf16 v[122:125], v[94:97], v[38:41], v[106:109]
	s_waitcnt lgkmcnt(1)
	v_mfma_f32_16x16x32_bf16 v[86:89], v[94:97], v[42:45], v[86:89]
	s_waitcnt lgkmcnt(0)
	v_mfma_f32_16x16x32_bf16 v[18:21], v[94:97], v[114:117], v[18:21]
	ds_read_b128 v[94:97], v151
	s_waitcnt lgkmcnt(0)
	v_mfma_f32_16x16x32_bf16 v[110:113], v[94:97], v[34:37], v[22:25]
	v_mfma_f32_16x16x32_bf16 v[106:109], v[94:97], v[38:41], v[26:29]
	v_mfma_f32_16x16x32_bf16 v[102:105], v[94:97], v[42:45], v[30:33]
	s_nop 0
	ds_read_b128 v[22:25], v150 offset:416
	ds_read_b128 v[26:29], v150 offset:8864
	ds_read_b128 v[30:33], v150 offset:17312
	ds_read_b128 v[34:37], v150 offset:25760
	v_mfma_f32_16x16x32_bf16 v[114:117], v[94:97], v[114:117], v[118:121]
	s_waitcnt lgkmcnt(3)
	v_mfma_f32_16x16x32_bf16 v[22:25], v[98:101], v[22:25], v[90:93]
	s_waitcnt lgkmcnt(1)
	v_mfma_f32_16x16x32_bf16 v[30:33], v[98:101], v[30:33], v[86:89]
	ds_read_b128 v[38:41], v150 offset:448
	ds_read_b128 v[42:45], v150 offset:8896
	s_nop 0
	ds_read_b128 v[86:89], v150 offset:17344
	ds_read_b128 v[90:93], v150 offset:25792
	v_mfma_f32_16x16x32_bf16 v[26:29], v[98:101], v[26:29], v[122:125]
	s_waitcnt lgkmcnt(4)
	v_mfma_f32_16x16x32_bf16 v[18:21], v[98:101], v[34:37], v[18:21]
	s_waitcnt lgkmcnt(3)
	v_mfma_f32_16x16x32_bf16 v[22:25], v[82:85], v[38:41], v[22:25]
	s_waitcnt lgkmcnt(2)
	v_mfma_f32_16x16x32_bf16 v[26:29], v[82:85], v[42:45], v[26:29]
	s_waitcnt lgkmcnt(1)
	v_mfma_f32_16x16x32_bf16 v[30:33], v[82:85], v[86:89], v[30:33]
	ds_read_b128 v[34:37], v150 offset:480
	ds_read_b128 v[38:41], v150 offset:8928
	ds_read_b128 v[42:45], v150 offset:17376
	ds_read_b128 v[86:89], v150 offset:25824
	s_waitcnt lgkmcnt(4)
	v_mfma_f32_16x16x32_bf16 v[18:21], v[82:85], v[90:93], v[18:21]
	s_waitcnt lgkmcnt(3)
	v_mfma_f32_16x16x32_bf16 v[162:165], v[46:49], v[34:37], v[22:25]
	s_waitcnt lgkmcnt(2)
	v_mfma_f32_16x16x32_bf16 v[158:161], v[46:49], v[38:41], v[26:29]
	s_waitcnt lgkmcnt(1)
	v_mfma_f32_16x16x32_bf16 v[154:157], v[46:49], v[42:45], v[30:33]
	s_waitcnt lgkmcnt(0)
	v_mfma_f32_16x16x32_bf16 v[150:153], v[46:49], v[86:89], v[18:21]
	v_mov_b32_e32 v136, s0
	v_mov_b32_e32 v171, v176
; #define LAS __attribute__((address_space(3)))
; DEV void s5_phase(LAS char* shm, const bf16_t* Uin, bf16_t* Yout, const char* tab, const float* dskip) {
;     ...
;         const float2 al = AL[g * NP + lane];
;         const float4 dsk = *(const float4*)(dskip + g * GC + 4 * fq);
;         const bf16_t* vvp = VV + (size_t)g * V_G + ((size_t)(wid * 4) * 64 + lane) * 8; asm volatile("" : "+v"(vvp));
;         bf16x8 va[4][4];
; #pragma unroll
;         for (int q = 0; q < 4; ++q)
; #pragma unroll
;             for (int ks = 0; ks < 4; ++ks) va[q][ks] = *(const bf16x8*)(vvp + ((size_t)((8 * q) * 4 + ks) * 64) * 8);
; #pragma unroll
;         for (int nt = 0; nt < 4; ++nt) *(LAS f32x4*)(shm + SL + (16 * nt + fr) * SRS + (16 * wid + 4 * fq) * 4) = sac[nt];
;         __syncthreads();
;         {
;             float hr = 0.f, hi = 0.f, lr[8], li[8];
; #pragma unroll
;             for (int n = 0; n < 8; ++n) {
;                 lr[n] = hr; li[n] = hi;
;                 const float sr = *(const LAS float*)(shm + SL + (8 * wid + n) * SRS + lane * 4), si = *(const LAS float*)(shm + SL + (8 * wid + n) * SRS + (64 + lane) * 4);
;                 const float nr = al.x * hr - al.y * hi + sr, ni = al.x * hi + al.y * hr + si; hr = nr; hi = ni;
;             }
;             *(LAS float*)(shm + TSEG + (wid * 128 + lane) * 4) = hr; *(LAS float*)(shm + TSEG + (wid * 128 + 64 + lane) * 4) = hi;
;             float pr = al.x, pi = al.y;
; #pragma unroll
;             for (int e = 0; e < 3; ++e) { const float nr = pr * pr - pi * pi, ni = 2.f * pr * pi; pr = nr; pi = ni; }
;             __syncthreads();
;             float cr = 0.f, ci = 0.f;
;             for (int w2 = 0; w2 < wid; ++w2) {
;                 const float tr = *(const LAS float*)(shm + TSEG + (w2 * 128 + lane) * 4), ti = *(const LAS float*)(shm + TSEG + (w2 * 128 + 64 + lane) * 4);
;                 const float nr = pr * cr - pi * ci + tr, ni = pr * ci + pi * cr + ti; cr = nr; ci = ni;
;             }
;             float qr = 1.f, qi = 0.f;
; #pragma unroll
;             for (int n = 0; n < 8; ++n) {
;                 const float fr_ = lr[n] + qr * cr - qi * ci, fi_ = li[n] + qr * ci + qi * cr;
;                 *(LAS bf16_t*)(shm + HB + (8 * wid + n) * HRS + lane * 2) = f2bf(fr_);
;                 *(LAS bf16_t*)(shm + HB + (8 * wid + n) * HRS + (64 + lane) * 2) = f2bf(fi_);
.LBB0_1155:
	s_lshl_b32 s0, s45, 6
	v_or_b32_e32 v0, s0, v173
	v_lshlrev_b32_e32 v0, 3, v0
	global_load_dwordx2 v[134:135], v0, s[4:5]
	s_add_u32 s0, s21, s0
	v_lshlrev_b32_e32 v168, 2, v173
	s_addc_u32 s1, s22, 0
	s_lshl_b32 s7, s7, 1
	v_and_b32_e32 v0, 48, v173
	s_mul_i32 s10, s43, 0x1080
	v_add_u32_e32 v138, s40, v168
	s_add_u32 s7, s25, s7
	v_add_u32_e32 v139, s10, v138
	global_load_dwordx4 v[18:21], v0, s[0:1]
	s_addc_u32 s10, s26, 0
	s_lshl_b32 s0, s43, 2
	v_lshrrev_b32_e32 v143, 4, v173
	s_ashr_i32 s1, s0, 31
	v_lshlrev_b32_e32 v144, 2, v143
	s_lshl_b64 s[0:1], s[0:1], 10
	v_or_b32_e32 v1, s6, v144
	s_add_u32 s0, s7, s0
	v_or_b32_e32 v142, 16, v175
	v_lshl_add_u32 v0, v1, 2, s40
	s_addc_u32 s1, s10, s1
	v_add_u32_e32 v140, v0, v171
	v_mad_u32_u24 v141, v142, s29, v0
	v_lshl_add_u64 v[0:1], s[0:1], 0, v[166:167]
	global_load_dwordx4 v[118:121], v[0:1], off
	global_load_dwordx4 v[86:89], v[0:1], off offset:1024
	global_load_dwordx4 v[46:49], v[0:1], off offset:2048
	global_load_dwordx4 v[34:37], v[0:1], off offset:3072
	v_add_co_u32_e32 v22, vcc, s37, v0
	s_lshl_b32 s7, s43, 3
	s_nop 0
	v_addc_co_u32_e32 v23, vcc, 0, v1, vcc
	v_add_co_u32_e32 v24, vcc, s38, v0
	s_or_b32 s0, s7, 1
	s_nop 0
	v_addc_co_u32_e32 v25, vcc, 0, v1, vcc
	v_add_co_u32_e32 v0, vcc, s39, v0
	s_mul_i32 s1, s0, 0x210
	s_nop 0
	v_addc_co_u32_e32 v1, vcc, 0, v1, vcc
	global_load_dwordx4 v[122:125], v[22:23], off
	global_load_dwordx4 v[90:93], v[22:23], off offset:1024
	s_waitcnt vmcnt(0)
	global_load_dwordx4 v[82:85], v[22:23], off offset:2048
	global_load_dwordx4 v[30:33], v[22:23], off offset:3072
	global_load_dwordx4 v[126:129], v[24:25], off
	global_load_dwordx4 v[94:97], v[24:25], off offset:1024
	global_load_dwordx4 v[42:45], v[24:25], off offset:2048
	s_nop 0
	global_load_dwordx4 v[22:25], v[24:25], off offset:3072
	s_nop 0
	global_load_dwordx4 v[130:133], v[0:1], off
	global_load_dwordx4 v[98:101], v[0:1], off offset:1024
	global_load_dwordx4 v[38:41], v[0:1], off offset:2048
	global_load_dwordx4 v[26:29], v[0:1], off offset:3072
	v_add_u32_e32 v166, s1, v138
	ds_write_b128 v140, v[162:165]
	ds_write_b128 v141, v[158:161]
	ds_write_b128 v141, v[154:157] offset:8448
	ds_write_b128 v141, v[150:153] offset:16896
	s_waitcnt lgkmcnt(0)
	s_barrier
	ds_read2st64_b32 v[0:1], v139 offset1:1
	ds_read2st64_b32 v[138:139], v166 offset1:1
	ds_read2_b32 v[140:141], v166 offset0:132 offset1:196
	v_add_u32_e32 v145, 32, v166
	ds_read2st64_b32 v[146:147], v145 offset0:4 offset1:5
	v_add_u32_e32 v136, 0, v136
	v_add_u32_e32 v136, v136, v168
	v_add_u32_e32 v136, 0x21200, v136
	v_mov_b32_e32 v137, 0
	s_cmp_lt_i32 s43, 1
	v_mul_f32_e32 v159, 0, v135
	v_fma_f32 v148, 0, v134, v159
	v_fma_f32 v145, v134, 0, -v159
	s_waitcnt lgkmcnt(0)
	v_add_f32_e32 v157, v148, v1
	v_add_f32_e32 v158, v145, v0
	v_mul_f32_e32 v0, v135, v157
	v_mul_f32_e32 v1, v134, v157
	v_fma_f32 v0, v134, v158, -v0
	v_fmac_f32_e32 v1, v135, v158
	v_add_f32_e32 v156, v138, v0
	v_add_f32_e32 v155, v139, v1
	v_mul_f32_e32 v1, v135, v156
	v_mul_f32_e32 v0, v135, v155
	v_fmac_f32_e32 v1, v134, v155
	v_fma_f32 v0, v134, v156, -v0
	v_add_f32_e32 v153, v141, v1
	v_add_f32_e32 v154, v140, v0
	v_mul_f32_e32 v0, v135, v153
	v_fma_f32 v0, v134, v154, -v0
	v_add_f32_e32 v151, v146, v0
	v_add_u32_e32 v0, 48, v166
	v_mul_f32_e32 v138, v135, v154
	ds_read2st64_b32 v[0:1], v0 offset0:6 offset1:7
	v_fmac_f32_e32 v138, v134, v153
	v_add_f32_e32 v152, v147, v138
	v_mul_f32_e32 v138, v135, v152
	v_fma_f32 v138, v134, v151, -v138
	s_waitcnt lgkmcnt(0)
	v_add_f32_e32 v149, v0, v138
	v_add_u32_e32 v138, 64, v166
	v_mul_f32_e32 v0, v135, v151
	ds_read2st64_b32 v[138:139], v138 offset0:8 offset1:9
	v_fmac_f32_e32 v0, v134, v152
	v_add_f32_e32 v150, v1, v0
	v_mul_f32_e32 v0, v135, v150
	v_fma_f32 v0, v134, v149, -v0
	s_waitcnt lgkmcnt(0)
	v_add_f32_e32 v147, v138, v0
	v_add_u32_e32 v0, 0x50, v166
	v_mul_f32_e32 v138, v135, v149
	ds_read2st64_b32 v[0:1], v0 offset0:10 offset1:11
	v_fmac_f32_e32 v138, v134, v150
	v_add_f32_e32 v148, v139, v138
	v_mul_f32_e32 v138, v135, v148
	v_fma_f32 v138, v134, v147, -v138
	s_waitcnt lgkmcnt(0)
	v_add_f32_e32 v145, v0, v138
	v_add_u32_e32 v138, 0x60, v166
	v_mul_f32_e32 v0, v135, v147
	ds_read2st64_b32 v[138:139], v138 offset0:12 offset1:13
	v_fmac_f32_e32 v0, v134, v148
	v_add_f32_e32 v146, v1, v0
	v_mul_f32_e32 v0, v135, v146
	v_mul_f32_e32 v1, v135, v145
	v_fma_f32 v0, v134, v145, -v0
	v_fmac_f32_e32 v1, v134, v146
	s_waitcnt lgkmcnt(0)
	v_add_f32_e32 v0, v138, v0
	v_add_f32_e32 v1, v139, v1
	ds_write2st64_b32 v136, v0, v1 offset1:1
	v_mov_b32_e32 v136, 0
	s_waitcnt lgkmcnt(0)
	s_barrier
	s_cbranch_scc1 .LBB0_1142
	v_mul_f32_e32 v1, v135, v135
	v_add_f32_e32 v0, v134, v134
	v_fma_f32 v1, v134, v134, -v1
	v_mul_f32_e32 v0, v0, v135
	v_add_f32_e32 v136, v1, v1
	v_mul_f32_e32 v136, v0, v136
	v_mul_f32_e32 v0, v0, v0
	v_fma_f32 v0, v1, v1, -v0
	v_add_f32_e32 v1, v0, v0
	v_mul_f32_e32 v138, v136, v1
	v_mul_f32_e32 v1, v136, v136
	v_fma_f32 v140, v0, v0, -v1
	s_cmp_lt_u32 s43, 8
	v_mov_b32_e32 v141, v140
	s_cbranch_scc1 .LBB0_1160
	s_add_i32 s7, 0, 0x21200
	v_mov_b32_e32 v136, 0
	s_and_b32 s1, s43, 0x7ffffff8
	v_mov_b32_e32 v139, v138
	v_add_u32_e32 v160, s7, v168
	s_mov_b32 s7, 0
	v_mov_b32_e32 v137, v136

; #define LAS __attribute__((address_space(3)))
; template <int H2>
; DEV void s5_p1_all(LAS char* shm, int wid, int fr, int fq, bf16x8 (&wfr)[8], const bf16_t* wsp, f32x4 (&acc)[4][4], f32x4 (&sac)[4]) {
;     ...
;     for (int sp = 0; sp < 16; ++sp) {
;         bf16x8 bn[4], kf[4];
; #pragma unroll
;         for (int q = 0; q < 4; ++q) if (q >= S5_Q0(sp)) kf[q] = *(const LAS bf16x8*)(kb + (8 * q - 2 * sp + 30) * 512);
; #pragma unroll
;         for (int nt = 0; nt < 4; ++nt) bn[nt] = bu[nt];
;         if (sp < 15) {
; #pragma unroll
;             for (int nt = 0; nt < 4; ++nt) bn[nt] = *(const LAS bf16x8*)(ub + nt * 16 * 528 + (sp + 1) * 32);
;         }
; #pragma unroll
;         for (int nt = 0; nt < 4; ++nt) sac[nt] = __builtin_amdgcn_mfma_f32_16x16x32_bf16(wfr[sp & 7], bu[nt], sac[nt], 0, 0, 0);
;         if (sp < 8) wfr[sp & 7] = *(const bf16x8*)(wsp + (size_t)(sp + 8) * 64 * 8);
; #pragma unroll
;         for (int q = 0; q < 4; ++q) {
;             if (q >= S5_Q0(sp)) {
; #pragma unroll
;                 for (int nt = 0; nt < 4; ++nt) acc[q][nt] = __builtin_amdgcn_mfma_f32_16x16x32_bf16(kf[q], bu[nt], acc[q][nt], 0, 0, 0);
;             }
;         }
; #pragma unroll
;         for (int nt = 0; nt < 4; ++nt) bu[nt] = bn[nt];
;         __builtin_amdgcn_sched_barrier(0);
;     }
.LBB0_1163:
	s_cmp_eq_u32 s47, 2
	s_mov_b64 s[12:13], -1
	s_cbranch_scc0 .LBB0_1165
	s_waitcnt lgkmcnt(0)
	v_mfma_f32_16x16x32_bf16 v[2:5], v[46:49], v[118:121], 0
	v_mfma_f32_16x16x32_bf16 v[6:9], v[46:49], v[126:129], 0
	v_mfma_f32_16x16x32_bf16 v[10:13], v[46:49], v[134:137], 0
	v_mfma_f32_16x16x32_bf16 v[14:17], v[46:49], v[138:141], 0
	v_mfma_f32_16x16x32_bf16 v[50:53], v[146:149], v[118:121], 0
	v_mfma_f32_16x16x32_bf16 v[54:57], v[146:149], v[126:129], 0
	v_mfma_f32_16x16x32_bf16 v[58:61], v[146:149], v[134:137], 0
	v_mfma_f32_16x16x32_bf16 v[62:65], v[146:149], v[138:141], 0
	v_mfma_f32_16x16x32_bf16 v[66:69], v[142:145], v[118:121], 0
	v_mfma_f32_16x16x32_bf16 v[70:73], v[142:145], v[126:129], 0
	v_mfma_f32_16x16x32_bf16 v[74:77], v[142:145], v[134:137], 0
	v_mfma_f32_16x16x32_bf16 v[78:81], v[142:145], v[138:141], 0
	v_mfma_f32_16x16x32_bf16 v[102:105], v[130:133], v[118:121], 0
	v_mfma_f32_16x16x32_bf16 v[106:109], v[130:133], v[126:129], 0
	v_mfma_f32_16x16x32_bf16 v[110:113], v[130:133], v[134:137], 0
	v_mfma_f32_16x16x32_bf16 v[114:117], v[130:133], v[138:141], 0
	v_mfma_f32_16x16x32_bf16 v[150:153], v[122:125], v[118:121], 0
	v_mfma_f32_16x16x32_bf16 v[154:157], v[122:125], v[126:129], 0
	v_mfma_f32_16x16x32_bf16 v[158:161], v[122:125], v[134:137], 0
	v_mfma_f32_16x16x32_bf16 v[162:165], v[122:125], v[138:141], 0
	v_add_u32_e32 v183, 0xfffffc00, v182
	ds_read_b128 v[184:187], v183
	ds_read_b128 v[188:191], v182 offset:11264
	v_add_co_u32_e32 v0, vcc, s34, v168
	v_mfma_f32_16x16x32_bf16 v[2:5], v[42:45], v[86:89], v[2:5]
	s_nop 0
	v_addc_co_u32_e32 v1, vcc, 0, v169, vcc
	s_waitcnt lgkmcnt(0)
	v_mfma_f32_16x16x32_bf16 v[50:53], v[184:187], v[86:89], v[50:53]
	v_mfma_f32_16x16x32_bf16 v[54:57], v[184:187], v[94:97], v[54:57]
	v_mfma_f32_16x16x32_bf16 v[58:61], v[184:187], v[98:101], v[58:61]
	v_mfma_f32_16x16x32_bf16 v[62:65], v[184:187], v[90:93], v[62:65]
	ds_read_b128 v[184:187], v182 offset:3072
	ds_read_b128 v[192:195], v182 offset:7168
	s_waitcnt lgkmcnt(0)
	v_mfma_f32_16x16x32_bf16 v[66:69], v[184:187], v[86:89], v[66:69]
	v_mfma_f32_16x16x32_bf16 v[70:73], v[184:187], v[94:97], v[70:73]
	v_mfma_f32_16x16x32_bf16 v[74:77], v[184:187], v[98:101], v[74:77]
	v_mfma_f32_16x16x32_bf16 v[78:81], v[184:187], v[90:93], v[78:81]
	global_load_dwordx4 v[184:187], v[0:1], off offset:1024
	v_mfma_f32_16x16x32_bf16 v[102:105], v[192:195], v[86:89], v[102:105]
	v_mfma_f32_16x16x32_bf16 v[106:109], v[192:195], v[94:97], v[106:109]
	v_mfma_f32_16x16x32_bf16 v[110:113], v[192:195], v[98:101], v[110:113]
	v_mfma_f32_16x16x32_bf16 v[114:117], v[192:195], v[90:93], v[114:117]
	ds_read_b128 v[192:195], v181 offset:64
	ds_read_b128 v[196:199], v181 offset:8512
	ds_read_b128 v[200:203], v181 offset:16960
	ds_read_b128 v[204:207], v181 offset:25408
	v_mfma_f32_16x16x32_bf16 v[6:9], v[42:45], v[94:97], v[6:9]
	v_mfma_f32_16x16x32_bf16 v[10:13], v[42:45], v[98:101], v[10:13]
	v_mfma_f32_16x16x32_bf16 v[14:17], v[42:45], v[90:93], v[14:17]
	v_mfma_f32_16x16x32_bf16 v[150:153], v[188:191], v[86:89], v[150:153]
	v_mfma_f32_16x16x32_bf16 v[154:157], v[188:191], v[94:97], v[154:157]
	v_mfma_f32_16x16x32_bf16 v[158:161], v[188:191], v[98:101], v[158:161]
	v_mfma_f32_16x16x32_bf16 v[162:165], v[188:191], v[90:93], v[162:165]
	v_add_u32_e32 v236, 0xfffff800, v182
	s_waitcnt lgkmcnt(0)
	v_mfma_f32_16x16x32_bf16 v[188:191], v[38:41], v[192:195], v[2:5]
	s_nop 2
	ds_read_b128 v[2:5], v236
	v_mfma_f32_16x16x32_bf16 v[212:215], v[38:41], v[200:203], v[10:13]
	v_mfma_f32_16x16x32_bf16 v[216:219], v[38:41], v[204:207], v[14:17]
	s_waitcnt lgkmcnt(0)
	v_mfma_f32_16x16x32_bf16 v[14:17], v[2:5], v[192:195], v[50:53]
	v_mfma_f32_16x16x32_bf16 v[10:13], v[2:5], v[196:199], v[54:57]
	s_nop 1
	ds_read_b128 v[50:53], v182 offset:2048
	ds_read_b128 v[54:57], v182 offset:6144
	v_mfma_f32_16x16x32_bf16 v[208:211], v[38:41], v[196:199], v[6:9]
	v_mfma_f32_16x16x32_bf16 v[6:9], v[2:5], v[200:203], v[58:61]
	v_mfma_f32_16x16x32_bf16 v[2:5], v[2:5], v[204:207], v[62:65]
	s_waitcnt lgkmcnt(0)
	v_mfma_f32_16x16x32_bf16 v[58:61], v[50:53], v[192:195], v[66:69]
	v_mfma_f32_16x16x32_bf16 v[62:65], v[50:53], v[196:199], v[70:73]
	v_mfma_f32_16x16x32_bf16 v[66:69], v[50:53], v[200:203], v[74:77]
	v_mfma_f32_16x16x32_bf16 v[50:53], v[50:53], v[204:207], v[78:81]
	v_mfma_f32_16x16x32_bf16 v[70:73], v[54:57], v[192:195], v[102:105]
	v_mfma_f32_16x16x32_bf16 v[74:77], v[54:57], v[196:199], v[106:109]
	s_nop 1
	ds_read_b128 v[102:105], v182 offset:10240
	v_mfma_f32_16x16x32_bf16 v[78:81], v[54:57], v[200:203], v[110:113]
	v_mfma_f32_16x16x32_bf16 v[54:57], v[54:57], v[204:207], v[114:117]
	s_nop 2
	global_load_dwordx4 v[114:117], v[0:1], off offset:2048
	s_waitcnt lgkmcnt(0)
	v_mfma_f32_16x16x32_bf16 v[106:109], v[102:105], v[192:195], v[150:153]
	v_mfma_f32_16x16x32_bf16 v[110:113], v[102:105], v[196:199], v[154:157]
	v_mfma_f32_16x16x32_bf16 v[150:153], v[102:105], v[200:203], v[158:161]
	s_nop 1
	ds_read_b128 v[154:157], v181 offset:96
	ds_read_b128 v[158:161], v181 offset:8544
	ds_read_b128 v[192:195], v181 offset:16992
	ds_read_b128 v[196:199], v181 offset:25440
	v_mfma_f32_16x16x32_bf16 v[102:105], v[102:105], v[204:207], v[162:165]
	s_waitcnt lgkmcnt(0)
	v_mfma_f32_16x16x32_bf16 v[162:165], v[34:37], v[154:157], v[188:191]
	v_mfma_f32_16x16x32_bf16 v[188:191], v[34:37], v[158:161], v[208:211]
	v_mfma_f32_16x16x32_bf16 v[200:203], v[34:37], v[192:195], v[212:215]
	s_nop 1
	ds_read_b128 v[208:211], v182 offset:1024
	ds_read_b128 v[212:215], v182 offset:5120
	s_waitcnt lgkmcnt(0)
; #define LAS __attribute__((address_space(3)))
; template <int H2>
; DEV void s5_p1_all(LAS char* shm, int wid, int fr, int fq, bf16x8 (&wfr)[8], const bf16_t* wsp, f32x4 (&acc)[4][4], f32x4 (&sac)[4]) {
;     ...
;     for (int sp = 0; sp < 16; ++sp) {
;         bf16x8 bn[4], kf[4];
; #pragma unroll
;         for (int q = 0; q < 4; ++q) if (q >= S5_Q0(sp)) kf[q] = *(const LAS bf16x8*)(kb + (8 * q - 2 * sp + 30) * 512);
; #pragma unroll
;         for (int nt = 0; nt < 4; ++nt) bn[nt] = bu[nt];
;         if (sp < 15) {
; #pragma unroll
;             for (int nt = 0; nt < 4; ++nt) bn[nt] = *(const LAS bf16x8*)(ub + nt * 16 * 528 + (sp + 1) * 32);
;         }
; #pragma unroll
;         for (int nt = 0; nt < 4; ++nt) sac[nt] = __builtin_amdgcn_mfma_f32_16x16x32_bf16(wfr[sp & 7], bu[nt], sac[nt], 0, 0, 0);
;         if (sp < 8) wfr[sp & 7] = *(const bf16x8*)(wsp + (size_t)(sp + 8) * 64 * 8);
; #pragma unroll
;         for (int q = 0; q < 4; ++q) {
;             if (q >= S5_Q0(sp)) {
; #pragma unroll
;                 for (int nt = 0; nt < 4; ++nt) acc[q][nt] = __builtin_amdgcn_mfma_f32_16x16x32_bf16(kf[q], bu[nt], acc[q][nt], 0, 0, 0);
;             }
;         }
; #pragma unroll
;         for (int nt = 0; nt < 4; ++nt) bu[nt] = bn[nt];
;         __builtin_amdgcn_sched_barrier(0);
;     }
	v_mfma_f32_16x16x32_bf16 v[58:61], v[208:211], v[154:157], v[58:61]
	v_mfma_f32_16x16x32_bf16 v[62:65], v[208:211], v[158:161], v[62:65]
	v_mfma_f32_16x16x32_bf16 v[66:69], v[208:211], v[192:195], v[66:69]
	v_mfma_f32_16x16x32_bf16 v[50:53], v[208:211], v[196:199], v[50:53]
	ds_read_b128 v[208:211], v182 offset:9216
	v_mfma_f32_16x16x32_bf16 v[70:73], v[212:215], v[154:157], v[70:73]
	s_waitcnt lgkmcnt(0)
	v_mfma_f32_16x16x32_bf16 v[106:109], v[208:211], v[154:157], v[106:109]
	global_load_dwordx4 v[154:157], v[0:1], off offset:3072
	v_mfma_f32_16x16x32_bf16 v[204:207], v[34:37], v[196:199], v[216:219]
	v_mfma_f32_16x16x32_bf16 v[74:77], v[212:215], v[158:161], v[74:77]
	v_mfma_f32_16x16x32_bf16 v[78:81], v[212:215], v[192:195], v[78:81]
	v_mfma_f32_16x16x32_bf16 v[54:57], v[212:215], v[196:199], v[54:57]
	v_mfma_f32_16x16x32_bf16 v[110:113], v[208:211], v[158:161], v[110:113]
	v_mfma_f32_16x16x32_bf16 v[150:153], v[208:211], v[192:195], v[150:153]
	ds_read_b128 v[158:161], v181 offset:128
	ds_read_b128 v[192:195], v181 offset:8576
	ds_read_b128 v[212:215], v181 offset:17024
	ds_read_b128 v[216:219], v181 offset:25472
	v_mfma_f32_16x16x32_bf16 v[102:105], v[208:211], v[196:199], v[102:105]
	s_waitcnt lgkmcnt(0)
	v_mfma_f32_16x16x32_bf16 v[196:199], v[30:33], v[212:215], v[200:203]
	v_add_co_u32_e32 v0, vcc, s36, v168
	v_mfma_f32_16x16x32_bf16 v[200:203], v[30:33], v[216:219], v[204:207]
	s_nop 2
	ds_read_b128 v[204:207], v182
	ds_read_b128 v[208:211], v182 offset:4096
	v_addc_co_u32_e32 v1, vcc, 0, v169, vcc
	s_waitcnt lgkmcnt(0)
	v_mfma_f32_16x16x32_bf16 v[58:61], v[204:207], v[158:161], v[58:61]
	v_mfma_f32_16x16x32_bf16 v[62:65], v[204:207], v[192:195], v[62:65]
	v_mfma_f32_16x16x32_bf16 v[66:69], v[204:207], v[212:215], v[66:69]
	v_mfma_f32_16x16x32_bf16 v[50:53], v[204:207], v[216:219], v[50:53]
	ds_read_b128 v[204:207], v182 offset:8192
	v_mfma_f32_16x16x32_bf16 v[162:165], v[30:33], v[158:161], v[162:165]
	v_mfma_f32_16x16x32_bf16 v[70:73], v[208:211], v[158:161], v[70:73]
	s_waitcnt lgkmcnt(0)
	v_mfma_f32_16x16x32_bf16 v[106:109], v[204:207], v[158:161], v[106:109]
	global_load_dwordx4 v[158:161], v[0:1], off
	v_mfma_f32_16x16x32_bf16 v[188:191], v[30:33], v[192:195], v[188:191]
	v_mfma_f32_16x16x32_bf16 v[74:77], v[208:211], v[192:195], v[74:77]
	v_mfma_f32_16x16x32_bf16 v[78:81], v[208:211], v[212:215], v[78:81]
	v_mfma_f32_16x16x32_bf16 v[54:57], v[208:211], v[216:219], v[54:57]
	v_mfma_f32_16x16x32_bf16 v[110:113], v[204:207], v[192:195], v[110:113]
	v_mfma_f32_16x16x32_bf16 v[150:153], v[204:207], v[212:215], v[150:153]
	ds_read_b128 v[192:195], v181 offset:160
	ds_read_b128 v[208:211], v181 offset:8608
	ds_read_b128 v[212:215], v181 offset:17056
	ds_read_b128 v[220:223], v181 offset:25504
	v_mfma_f32_16x16x32_bf16 v[102:105], v[204:207], v[216:219], v[102:105]
	ds_read_b128 v[204:207], v183
	s_waitcnt lgkmcnt(0)
	v_mfma_f32_16x16x32_bf16 v[162:165], v[26:29], v[192:195], v[162:165]
	v_mfma_f32_16x16x32_bf16 v[188:191], v[26:29], v[208:211], v[188:191]
	v_mfma_f32_16x16x32_bf16 v[58:61], v[204:207], v[192:195], v[58:61]
	v_mfma_f32_16x16x32_bf16 v[216:219], v[204:207], v[208:211], v[62:65]
	v_mfma_f32_16x16x32_bf16 v[66:69], v[204:207], v[212:215], v[66:69]
	v_mfma_f32_16x16x32_bf16 v[50:53], v[204:207], v[220:223], v[50:53]
	s_nop 0
	ds_read_b128 v[62:65], v182 offset:3072
	ds_read_b128 v[204:207], v182 offset:7168
	s_waitcnt lgkmcnt(0)
	v_mfma_f32_16x16x32_bf16 v[70:73], v[62:65], v[192:195], v[70:73]
	v_mfma_f32_16x16x32_bf16 v[106:109], v[204:207], v[192:195], v[106:109]
	global_load_dwordx4 v[192:195], v[0:1], off offset:1024
	v_mfma_f32_16x16x32_bf16 v[196:199], v[26:29], v[212:215], v[196:199]
	v_mfma_f32_16x16x32_bf16 v[74:77], v[62:65], v[208:211], v[74:77]
	v_mfma_f32_16x16x32_bf16 v[78:81], v[62:65], v[212:215], v[78:81]
	v_mfma_f32_16x16x32_bf16 v[110:113], v[204:207], v[208:211], v[110:113]
	v_mfma_f32_16x16x32_bf16 v[150:153], v[204:207], v[212:215], v[150:153]
	ds_read_b128 v[208:211], v181 offset:192
	ds_read_b128 v[212:215], v181 offset:8640
	ds_read_b128 v[228:231], v181 offset:17088
	ds_read_b128 v[232:235], v181 offset:25536
	v_mfma_f32_16x16x32_bf16 v[102:105], v[204:207], v[220:223], v[102:105]
	v_mfma_f32_16x16x32_bf16 v[200:203], v[26:29], v[220:223], v[200:203]
	v_mfma_f32_16x16x32_bf16 v[224:227], v[62:65], v[220:223], v[54:57]
	ds_read_b128 v[204:207], v236
	s_waitcnt lgkmcnt(0)
	v_mfma_f32_16x16x32_bf16 v[162:165], v[22:25], v[208:211], v[162:165]
	v_mfma_f32_16x16x32_bf16 v[188:191], v[22:25], v[212:215], v[188:191]
	v_mfma_f32_16x16x32_bf16 v[62:65], v[204:207], v[208:211], v[58:61]
	v_mfma_f32_16x16x32_bf16 v[58:61], v[204:207], v[212:215], v[216:219]
	v_mfma_f32_16x16x32_bf16 v[54:57], v[204:207], v[228:231], v[66:69]
	v_mfma_f32_16x16x32_bf16 v[50:53], v[204:207], v[232:235], v[50:53]
	s_nop 1
	ds_read_b128 v[66:69], v182 offset:2048
	ds_read_b128 v[204:207], v182 offset:6144
	s_waitcnt lgkmcnt(0)
	v_mfma_f32_16x16x32_bf16 v[70:73], v[66:69], v[208:211], v[70:73]
	v_mfma_f32_16x16x32_bf16 v[106:109], v[204:207], v[208:211], v[106:109]
	global_load_dwordx4 v[208:211], v[0:1], off offset:2048
	v_mfma_f32_16x16x32_bf16 v[74:77], v[66:69], v[212:215], v[74:77]
	v_mfma_f32_16x16x32_bf16 v[78:81], v[66:69], v[228:231], v[78:81]
	v_mfma_f32_16x16x32_bf16 v[66:69], v[66:69], v[232:235], v[224:227]
	v_mfma_f32_16x16x32_bf16 v[110:113], v[204:207], v[212:215], v[110:113]
	ds_read_b128 v[212:215], v181 offset:224
	ds_read_b128 v[216:219], v181 offset:8672
	ds_read_b128 v[220:223], v181 offset:17120
	ds_read_b128 v[224:227], v181 offset:25568
	v_mfma_f32_16x16x32_bf16 v[150:153], v[204:207], v[228:231], v[150:153]
	v_mfma_f32_16x16x32_bf16 v[102:105], v[204:207], v[232:235], v[102:105]
	v_mfma_f32_16x16x32_bf16 v[196:199], v[22:25], v[228:231], v[196:199]
	v_mfma_f32_16x16x32_bf16 v[200:203], v[22:25], v[232:235], v[200:203]
	ds_read_b128 v[204:207], v182 offset:1024
	ds_read_b128 v[228:231], v182 offset:5120
	s_waitcnt lgkmcnt(0)
; #define LAS __attribute__((address_space(3)))
; template <int H2>
; DEV void s5_p1_all(LAS char* shm, int wid, int fr, int fq, bf16x8 (&wfr)[8], const bf16_t* wsp, f32x4 (&acc)[4][4], f32x4 (&sac)[4]) {
;     ...
;     for (int sp = 0; sp < 16; ++sp) {
;         bf16x8 bn[4], kf[4];
; #pragma unroll
;         for (int q = 0; q < 4; ++q) if (q >= S5_Q0(sp)) kf[q] = *(const LAS bf16x8*)(kb + (8 * q - 2 * sp + 30) * 512);
; #pragma unroll
;         for (int nt = 0; nt < 4; ++nt) bn[nt] = bu[nt];
;         if (sp < 15) {
; #pragma unroll
;             for (int nt = 0; nt < 4; ++nt) bn[nt] = *(const LAS bf16x8*)(ub + nt * 16 * 528 + (sp + 1) * 32);
;         }
; #pragma unroll
;         for (int nt = 0; nt < 4; ++nt) sac[nt] = __builtin_amdgcn_mfma_f32_16x16x32_bf16(wfr[sp & 7], bu[nt], sac[nt], 0, 0, 0);
;         if (sp < 8) wfr[sp & 7] = *(const bf16x8*)(wsp + (size_t)(sp + 8) * 64 * 8);
; #pragma unroll
;         for (int q = 0; q < 4; ++q) {
;             if (q >= S5_Q0(sp)) {
; #pragma unroll
;                 for (int nt = 0; nt < 4; ++nt) acc[q][nt] = __builtin_amdgcn_mfma_f32_16x16x32_bf16(kf[q], bu[nt], acc[q][nt], 0, 0, 0);
;             }
;         }
; #pragma unroll
;         for (int nt = 0; nt < 4; ++nt) bu[nt] = bn[nt];
;         __builtin_amdgcn_sched_barrier(0);
;     }
	v_mfma_f32_16x16x32_bf16 v[162:165], v[18:21], v[212:215], v[162:165]
	v_mfma_f32_16x16x32_bf16 v[70:73], v[204:207], v[212:215], v[70:73]
	v_mfma_f32_16x16x32_bf16 v[74:77], v[204:207], v[216:219], v[74:77]
	v_mfma_f32_16x16x32_bf16 v[78:81], v[204:207], v[220:223], v[78:81]
	v_mfma_f32_16x16x32_bf16 v[66:69], v[204:207], v[224:227], v[66:69]
	global_load_dwordx4 v[204:207], v[0:1], off offset:3072
	v_mfma_f32_16x16x32_bf16 v[188:191], v[18:21], v[216:219], v[188:191]
	v_mfma_f32_16x16x32_bf16 v[196:199], v[18:21], v[220:223], v[196:199]
	v_mfma_f32_16x16x32_bf16 v[106:109], v[228:231], v[212:215], v[106:109]
	v_mfma_f32_16x16x32_bf16 v[110:113], v[228:231], v[216:219], v[110:113]
	v_mfma_f32_16x16x32_bf16 v[150:153], v[228:231], v[220:223], v[150:153]
	ds_read_b128 v[212:215], v181 offset:256
	ds_read_b128 v[216:219], v181 offset:8704
	ds_read_b128 v[220:223], v181 offset:17152
	ds_read_b128 v[232:235], v181 offset:25600
	v_mfma_f32_16x16x32_bf16 v[102:105], v[228:231], v[224:227], v[102:105]
	v_mfma_f32_16x16x32_bf16 v[200:203], v[18:21], v[224:227], v[200:203]
	ds_read_b128 v[224:227], v182
	ds_read_b128 v[228:231], v182 offset:4096
	s_waitcnt vmcnt(0) lgkmcnt(0)
	v_mfma_f32_16x16x32_bf16 v[162:165], v[82:85], v[212:215], v[162:165]
	v_mfma_f32_16x16x32_bf16 v[188:191], v[82:85], v[216:219], v[188:191]
	v_mfma_f32_16x16x32_bf16 v[196:199], v[82:85], v[220:223], v[196:199]
	v_mfma_f32_16x16x32_bf16 v[70:73], v[224:227], v[212:215], v[70:73]
	v_mfma_f32_16x16x32_bf16 v[74:77], v[224:227], v[216:219], v[74:77]
	v_mfma_f32_16x16x32_bf16 v[78:81], v[224:227], v[220:223], v[78:81]
	v_mfma_f32_16x16x32_bf16 v[66:69], v[224:227], v[232:235], v[66:69]
	v_mfma_f32_16x16x32_bf16 v[106:109], v[228:231], v[212:215], v[106:109]
	v_mfma_f32_16x16x32_bf16 v[110:113], v[228:231], v[216:219], v[110:113]
	v_mfma_f32_16x16x32_bf16 v[150:153], v[228:231], v[220:223], v[150:153]
	ds_read_b128 v[212:215], v181 offset:288
	ds_read_b128 v[216:219], v181 offset:8736
	ds_read_b128 v[220:223], v181 offset:17184
	ds_read_b128 v[224:227], v181 offset:25632
	v_mfma_f32_16x16x32_bf16 v[102:105], v[228:231], v[232:235], v[102:105]
	v_mfma_f32_16x16x32_bf16 v[200:203], v[82:85], v[232:235], v[200:203]
	s_waitcnt lgkmcnt(3)
	v_mfma_f32_16x16x32_bf16 v[162:165], v[184:187], v[212:215], v[162:165]
	s_waitcnt lgkmcnt(2)
	v_mfma_f32_16x16x32_bf16 v[188:191], v[184:187], v[216:219], v[188:191]
	s_waitcnt lgkmcnt(1)
	v_mfma_f32_16x16x32_bf16 v[196:199], v[184:187], v[220:223], v[196:199]
	s_waitcnt lgkmcnt(0)
	v_mfma_f32_16x16x32_bf16 v[184:187], v[184:187], v[224:227], v[200:203]
	s_nop 2
	ds_read_b128 v[200:203], v183
	ds_read_b128 v[228:231], v182 offset:3072
	s_waitcnt lgkmcnt(1)
	v_mfma_f32_16x16x32_bf16 v[70:73], v[200:203], v[212:215], v[70:73]
	v_mfma_f32_16x16x32_bf16 v[74:77], v[200:203], v[216:219], v[74:77]
	v_mfma_f32_16x16x32_bf16 v[232:235], v[200:203], v[220:223], v[78:81]
	v_mfma_f32_16x16x32_bf16 v[66:69], v[200:203], v[224:227], v[66:69]
	s_waitcnt lgkmcnt(0)
	v_mfma_f32_16x16x32_bf16 v[106:109], v[228:231], v[212:215], v[106:109]
	v_mfma_f32_16x16x32_bf16 v[110:113], v[228:231], v[216:219], v[110:113]
	v_mfma_f32_16x16x32_bf16 v[150:153], v[228:231], v[220:223], v[150:153]
	ds_read_b128 v[200:203], v181 offset:320
	ds_read_b128 v[212:215], v181 offset:8768
	ds_read_b128 v[216:219], v181 offset:17216
	ds_read_b128 v[220:223], v181 offset:25664
	v_mfma_f32_16x16x32_bf16 v[102:105], v[228:231], v[224:227], v[102:105]
	s_waitcnt lgkmcnt(3)
	v_mfma_f32_16x16x32_bf16 v[162:165], v[114:117], v[200:203], v[162:165]
	s_waitcnt lgkmcnt(2)
	v_mfma_f32_16x16x32_bf16 v[188:191], v[114:117], v[212:215], v[188:191]
	s_waitcnt lgkmcnt(1)
	v_mfma_f32_16x16x32_bf16 v[196:199], v[114:117], v[216:219], v[196:199]
	s_waitcnt lgkmcnt(0)
	v_mfma_f32_16x16x32_bf16 v[114:117], v[114:117], v[220:223], v[184:187]
	s_nop 2
	ds_read_b128 v[184:187], v236
	ds_read_b128 v[224:227], v182 offset:2048
	s_waitcnt lgkmcnt(1)
	v_mfma_f32_16x16x32_bf16 v[78:81], v[184:187], v[200:203], v[70:73]
	v_mfma_f32_16x16x32_bf16 v[74:77], v[184:187], v[212:215], v[74:77]
	v_mfma_f32_16x16x32_bf16 v[70:73], v[184:187], v[216:219], v[232:235]
	v_mfma_f32_16x16x32_bf16 v[66:69], v[184:187], v[220:223], v[66:69]
	s_waitcnt lgkmcnt(0)
; #define LAS __attribute__((address_space(3)))
; template <int H2>
; DEV void s5_p1_all(LAS char* shm, int wid, int fr, int fq, bf16x8 (&wfr)[8], const bf16_t* wsp, f32x4 (&acc)[4][4], f32x4 (&sac)[4]) {
;     ...
;     for (int sp = 0; sp < 16; ++sp) {
;         bf16x8 bn[4], kf[4];
; #pragma unroll
;         for (int q = 0; q < 4; ++q) if (q >= S5_Q0(sp)) kf[q] = *(const LAS bf16x8*)(kb + (8 * q - 2 * sp + 30) * 512);
; #pragma unroll
;         for (int nt = 0; nt < 4; ++nt) bn[nt] = bu[nt];
;         if (sp < 15) {
; #pragma unroll
;             for (int nt = 0; nt < 4; ++nt) bn[nt] = *(const LAS bf16x8*)(ub + nt * 16 * 528 + (sp + 1) * 32);
;         }
; #pragma unroll
;         for (int nt = 0; nt < 4; ++nt) sac[nt] = __builtin_amdgcn_mfma_f32_16x16x32_bf16(wfr[sp & 7], bu[nt], sac[nt], 0, 0, 0);
;         if (sp < 8) wfr[sp & 7] = *(const bf16x8*)(wsp + (size_t)(sp + 8) * 64 * 8);
; #pragma unroll
;         for (int q = 0; q < 4; ++q) {
;             if (q >= S5_Q0(sp)) {
; #pragma unroll
;                 for (int nt = 0; nt < 4; ++nt) acc[q][nt] = __builtin_amdgcn_mfma_f32_16x16x32_bf16(kf[q], bu[nt], acc[q][nt], 0, 0, 0);
;             }
;         }
; #pragma unroll
;         for (int nt = 0; nt < 4; ++nt) bu[nt] = bn[nt];
;         __builtin_amdgcn_sched_barrier(0);
;     }
	v_mfma_f32_16x16x32_bf16 v[106:109], v[224:227], v[200:203], v[106:109]
	v_mfma_f32_16x16x32_bf16 v[110:113], v[224:227], v[212:215], v[110:113]
	v_mfma_f32_16x16x32_bf16 v[150:153], v[224:227], v[216:219], v[150:153]
	ds_read_b128 v[184:187], v181 offset:352
	ds_read_b128 v[200:203], v181 offset:8800
	ds_read_b128 v[212:215], v181 offset:17248
	ds_read_b128 v[216:219], v181 offset:25696
	v_mfma_f32_16x16x32_bf16 v[102:105], v[224:227], v[220:223], v[102:105]
	s_waitcnt lgkmcnt(3)
	v_mfma_f32_16x16x32_bf16 v[162:165], v[154:157], v[184:187], v[162:165]
	s_waitcnt lgkmcnt(2)
	v_mfma_f32_16x16x32_bf16 v[188:191], v[154:157], v[200:203], v[188:191]
	s_waitcnt lgkmcnt(1)
	v_mfma_f32_16x16x32_bf16 v[196:199], v[154:157], v[212:215], v[196:199]
	s_waitcnt lgkmcnt(0)
	v_mfma_f32_16x16x32_bf16 v[114:117], v[154:157], v[216:219], v[114:117]
	ds_read_b128 v[154:157], v182 offset:1024
	s_waitcnt lgkmcnt(0)
	v_mfma_f32_16x16x32_bf16 v[106:109], v[154:157], v[184:187], v[106:109]
	v_mfma_f32_16x16x32_bf16 v[110:113], v[154:157], v[200:203], v[110:113]
	v_mfma_f32_16x16x32_bf16 v[150:153], v[154:157], v[212:215], v[150:153]
	ds_read_b128 v[184:187], v181 offset:384
	ds_read_b128 v[200:203], v181 offset:8832
	ds_read_b128 v[212:215], v181 offset:17280
	ds_read_b128 v[220:223], v181 offset:25728
	v_mfma_f32_16x16x32_bf16 v[102:105], v[154:157], v[216:219], v[102:105]
	s_waitcnt lgkmcnt(3)
	v_mfma_f32_16x16x32_bf16 v[154:157], v[158:161], v[184:187], v[162:165]
	s_waitcnt lgkmcnt(2)
	v_mfma_f32_16x16x32_bf16 v[162:165], v[158:161], v[200:203], v[188:191]
	s_waitcnt lgkmcnt(1)
	v_mfma_f32_16x16x32_bf16 v[188:191], v[158:161], v[212:215], v[196:199]
	s_waitcnt lgkmcnt(0)
	v_mfma_f32_16x16x32_bf16 v[114:117], v[158:161], v[220:223], v[114:117]
	ds_read_b128 v[158:161], v182
	s_waitcnt lgkmcnt(0)
	v_mfma_f32_16x16x32_bf16 v[106:109], v[158:161], v[184:187], v[106:109]
	v_mfma_f32_16x16x32_bf16 v[110:113], v[158:161], v[200:203], v[110:113]
	v_mfma_f32_16x16x32_bf16 v[150:153], v[158:161], v[212:215], v[150:153]
	ds_read_b128 v[184:187], v181 offset:416
	ds_read_b128 v[196:199], v181 offset:8864
	ds_read_b128 v[200:203], v181 offset:17312
	ds_read_b128 v[212:215], v181 offset:25760
	v_mfma_f32_16x16x32_bf16 v[102:105], v[158:161], v[220:223], v[102:105]
	s_waitcnt lgkmcnt(2)
	v_mfma_f32_16x16x32_bf16 v[158:161], v[192:195], v[196:199], v[162:165]
	s_waitcnt lgkmcnt(1)
	v_mfma_f32_16x16x32_bf16 v[162:165], v[192:195], v[200:203], v[188:191]
	s_nop 2
	ds_read_b128 v[188:191], v183
	v_mfma_f32_16x16x32_bf16 v[154:157], v[192:195], v[184:187], v[154:157]
	s_waitcnt lgkmcnt(1)
	v_mfma_f32_16x16x32_bf16 v[114:117], v[192:195], v[212:215], v[114:117]
	s_waitcnt lgkmcnt(0)
	v_mfma_f32_16x16x32_bf16 v[106:109], v[188:191], v[184:187], v[106:109]
	v_mfma_f32_16x16x32_bf16 v[184:187], v[188:191], v[196:199], v[110:113]
	v_mfma_f32_16x16x32_bf16 v[150:153], v[188:191], v[200:203], v[150:153]
	s_nop 1
	ds_read_b128 v[110:113], v181 offset:448
	ds_read_b128 v[192:195], v181 offset:8896
	ds_read_b128 v[196:199], v181 offset:17344
	ds_read_b128 v[200:203], v181 offset:25792
	v_mfma_f32_16x16x32_bf16 v[188:191], v[188:191], v[212:215], v[102:105]
	s_waitcnt lgkmcnt(3)
	v_mfma_f32_16x16x32_bf16 v[154:157], v[208:211], v[110:113], v[154:157]
	s_waitcnt lgkmcnt(2)
	v_mfma_f32_16x16x32_bf16 v[158:161], v[208:211], v[192:195], v[158:161]
	s_waitcnt lgkmcnt(1)
	v_mfma_f32_16x16x32_bf16 v[212:215], v[208:211], v[196:199], v[162:165]
	s_waitcnt lgkmcnt(0)
	v_mfma_f32_16x16x32_bf16 v[208:211], v[208:211], v[200:203], v[114:117]
	s_nop 2
	ds_read_b128 v[114:117], v236
	s_waitcnt lgkmcnt(0)
	v_mfma_f32_16x16x32_bf16 v[110:113], v[114:117], v[110:113], v[106:109]
	v_mfma_f32_16x16x32_bf16 v[106:109], v[114:117], v[192:195], v[184:187]
	v_mfma_f32_16x16x32_bf16 v[102:105], v[114:117], v[196:199], v[150:153]
	s_nop 2
	ds_read_b128 v[150:153], v181 offset:480
	ds_read_b128 v[184:187], v181 offset:8928
	ds_read_b128 v[192:195], v181 offset:17376
	ds_read_b128 v[196:199], v181 offset:25824
	v_mfma_f32_16x16x32_bf16 v[114:117], v[114:117], v[200:203], v[188:191]
	s_waitcnt lgkmcnt(3)
	v_mfma_f32_16x16x32_bf16 v[162:165], v[204:207], v[150:153], v[154:157]
	s_waitcnt lgkmcnt(2)
	v_mfma_f32_16x16x32_bf16 v[158:161], v[204:207], v[184:187], v[158:161]
	s_waitcnt lgkmcnt(1)
	v_mfma_f32_16x16x32_bf16 v[154:157], v[204:207], v[192:195], v[212:215]
	s_waitcnt lgkmcnt(0)
	v_mfma_f32_16x16x32_bf16 v[150:153], v[204:207], v[196:199], v[208:211]
	s_mov_b64 s[12:13], 0

; #define LAS __attribute__((address_space(3)))
; template <int H2>
; DEV void s5_p1_all(LAS char* shm, int wid, int fr, int fq, bf16x8 (&wfr)[8], const bf16_t* wsp, f32x4 (&acc)[4][4], f32x4 (&sac)[4]) {
;     ...
;     for (int sp = 0; sp < 16; ++sp) {
;         bf16x8 bn[4], kf[4];
; #pragma unroll
;         for (int q = 0; q < 4; ++q) if (q >= S5_Q0(sp)) kf[q] = *(const LAS bf16x8*)(kb + (8 * q - 2 * sp + 30) * 512);
; #pragma unroll
;         for (int nt = 0; nt < 4; ++nt) bn[nt] = bu[nt];
;         if (sp < 15) {
; #pragma unroll
;             for (int nt = 0; nt < 4; ++nt) bn[nt] = *(const LAS bf16x8*)(ub + nt * 16 * 528 + (sp + 1) * 32);
;         }
; #pragma unroll
;         for (int nt = 0; nt < 4; ++nt) sac[nt] = __builtin_amdgcn_mfma_f32_16x16x32_bf16(wfr[sp & 7], bu[nt], sac[nt], 0, 0, 0);
;         if (sp < 8) wfr[sp & 7] = *(const bf16x8*)(wsp + (size_t)(sp + 8) * 64 * 8);
; #pragma unroll
;         for (int q = 0; q < 4; ++q) {
;             if (q >= S5_Q0(sp)) {
; #pragma unroll
;                 for (int nt = 0; nt < 4; ++nt) acc[q][nt] = __builtin_amdgcn_mfma_f32_16x16x32_bf16(kf[q], bu[nt], acc[q][nt], 0, 0, 0);
;             }
;         }
; #pragma unroll
;         for (int nt = 0; nt < 4; ++nt) bu[nt] = bn[nt];
;         __builtin_amdgcn_sched_barrier(0);
;     }
.LBB0_1167:
	s_waitcnt lgkmcnt(0)
	v_mfma_f32_16x16x32_bf16 v[2:5], v[46:49], v[118:121], 0
	v_mfma_f32_16x16x32_bf16 v[6:9], v[46:49], v[126:129], 0
	v_mfma_f32_16x16x32_bf16 v[10:13], v[46:49], v[134:137], 0
	v_mfma_f32_16x16x32_bf16 v[14:17], v[46:49], v[138:141], 0
	v_mfma_f32_16x16x32_bf16 v[50:53], v[146:149], v[118:121], 0
	v_mfma_f32_16x16x32_bf16 v[54:57], v[146:149], v[126:129], 0
	v_mfma_f32_16x16x32_bf16 v[58:61], v[146:149], v[134:137], 0
	v_mfma_f32_16x16x32_bf16 v[62:65], v[146:149], v[138:141], 0
	v_mfma_f32_16x16x32_bf16 v[66:69], v[142:145], v[118:121], 0
	v_mfma_f32_16x16x32_bf16 v[70:73], v[142:145], v[126:129], 0
	v_mfma_f32_16x16x32_bf16 v[74:77], v[142:145], v[134:137], 0
	v_mfma_f32_16x16x32_bf16 v[78:81], v[142:145], v[138:141], 0
	v_mfma_f32_16x16x32_bf16 v[102:105], v[130:133], v[118:121], 0
	v_mfma_f32_16x16x32_bf16 v[106:109], v[130:133], v[126:129], 0
	v_mfma_f32_16x16x32_bf16 v[110:113], v[130:133], v[134:137], 0
	v_mfma_f32_16x16x32_bf16 v[114:117], v[130:133], v[138:141], 0
	v_mfma_f32_16x16x32_bf16 v[150:153], v[122:125], v[118:121], 0
	v_mfma_f32_16x16x32_bf16 v[154:157], v[122:125], v[126:129], 0
	v_mfma_f32_16x16x32_bf16 v[158:161], v[122:125], v[134:137], 0
	v_mfma_f32_16x16x32_bf16 v[162:165], v[122:125], v[138:141], 0
	ds_read_b128 v[184:187], v183
	v_add_co_u32_e32 v0, vcc, s34, v168
	v_mfma_f32_16x16x32_bf16 v[2:5], v[42:45], v[86:89], v[2:5]
	s_nop 0
	v_addc_co_u32_e32 v1, vcc, 0, v169, vcc
	v_mfma_f32_16x16x32_bf16 v[6:9], v[42:45], v[94:97], v[6:9]
	s_waitcnt lgkmcnt(0)
	v_mfma_f32_16x16x32_bf16 v[50:53], v[184:187], v[86:89], v[50:53]
	v_mfma_f32_16x16x32_bf16 v[54:57], v[184:187], v[94:97], v[54:57]
	v_mfma_f32_16x16x32_bf16 v[58:61], v[184:187], v[98:101], v[58:61]
	v_mfma_f32_16x16x32_bf16 v[62:65], v[184:187], v[90:93], v[62:65]
	ds_read_b128 v[184:187], v182 offset:3072
	ds_read_b128 v[188:191], v182 offset:7168
	s_waitcnt lgkmcnt(0)
	v_mfma_f32_16x16x32_bf16 v[192:195], v[184:187], v[86:89], v[66:69]
	s_nop 2
	global_load_dwordx4 v[66:69], v[0:1], off offset:1024
	v_mfma_f32_16x16x32_bf16 v[70:73], v[184:187], v[94:97], v[70:73]
	v_mfma_f32_16x16x32_bf16 v[74:77], v[184:187], v[98:101], v[74:77]
	v_mfma_f32_16x16x32_bf16 v[78:81], v[184:187], v[90:93], v[78:81]
	ds_read_b128 v[184:187], v182 offset:11264
	v_mfma_f32_16x16x32_bf16 v[102:105], v[188:191], v[86:89], v[102:105]
	v_mfma_f32_16x16x32_bf16 v[106:109], v[188:191], v[94:97], v[106:109]
	v_mfma_f32_16x16x32_bf16 v[110:113], v[188:191], v[98:101], v[110:113]
	v_mfma_f32_16x16x32_bf16 v[114:117], v[188:191], v[90:93], v[114:117]
	ds_read_b128 v[188:191], v181 offset:64
	ds_read_b128 v[196:199], v181 offset:8512
	ds_read_b128 v[200:203], v181 offset:16960
	ds_read_b128 v[204:207], v181 offset:25408
	v_mfma_f32_16x16x32_bf16 v[10:13], v[42:45], v[98:101], v[10:13]
	v_mfma_f32_16x16x32_bf16 v[14:17], v[42:45], v[90:93], v[14:17]
	s_waitcnt lgkmcnt(0)
	v_mfma_f32_16x16x32_bf16 v[150:153], v[184:187], v[86:89], v[150:153]
	v_mfma_f32_16x16x32_bf16 v[154:157], v[184:187], v[94:97], v[154:157]
	v_mfma_f32_16x16x32_bf16 v[158:161], v[184:187], v[98:101], v[158:161]
	v_mfma_f32_16x16x32_bf16 v[162:165], v[184:187], v[90:93], v[162:165]
	v_add_u32_e32 v241, 0xfffff800, v182
	ds_read_b128 v[184:187], v241
	v_mfma_f32_16x16x32_bf16 v[2:5], v[38:41], v[188:191], v[2:5]
	v_mfma_f32_16x16x32_bf16 v[6:9], v[38:41], v[196:199], v[6:9]
	s_waitcnt lgkmcnt(0)
	v_mfma_f32_16x16x32_bf16 v[50:53], v[184:187], v[188:191], v[50:53]
	v_mfma_f32_16x16x32_bf16 v[54:57], v[184:187], v[196:199], v[54:57]
	v_mfma_f32_16x16x32_bf16 v[58:61], v[184:187], v[200:203], v[58:61]
	v_mfma_f32_16x16x32_bf16 v[62:65], v[184:187], v[204:207], v[62:65]
	ds_read_b128 v[184:187], v182 offset:2048
	ds_read_b128 v[208:211], v182 offset:6144
	s_waitcnt lgkmcnt(0)
	v_mfma_f32_16x16x32_bf16 v[192:195], v[184:187], v[188:191], v[192:195]
	v_mfma_f32_16x16x32_bf16 v[70:73], v[184:187], v[196:199], v[70:73]
	v_mfma_f32_16x16x32_bf16 v[74:77], v[184:187], v[200:203], v[74:77]
	v_mfma_f32_16x16x32_bf16 v[78:81], v[184:187], v[204:207], v[78:81]
	ds_read_b128 v[184:187], v182 offset:10240
	v_mfma_f32_16x16x32_bf16 v[102:105], v[208:211], v[188:191], v[102:105]
	s_waitcnt lgkmcnt(0)
	v_mfma_f32_16x16x32_bf16 v[150:153], v[184:187], v[188:191], v[150:153]
	global_load_dwordx4 v[188:191], v[0:1], off offset:2048
	v_mfma_f32_16x16x32_bf16 v[10:13], v[38:41], v[200:203], v[10:13]
	v_mfma_f32_16x16x32_bf16 v[106:109], v[208:211], v[196:199], v[106:109]
	v_mfma_f32_16x16x32_bf16 v[110:113], v[208:211], v[200:203], v[110:113]
	v_mfma_f32_16x16x32_bf16 v[114:117], v[208:211], v[204:207], v[114:117]
	v_mfma_f32_16x16x32_bf16 v[154:157], v[184:187], v[196:199], v[154:157]
	v_mfma_f32_16x16x32_bf16 v[158:161], v[184:187], v[200:203], v[158:161]
	ds_read_b128 v[196:199], v181 offset:96
	ds_read_b128 v[200:203], v181 offset:8544
	ds_read_b128 v[208:211], v181 offset:16992
	ds_read_b128 v[212:215], v181 offset:25440
	v_mfma_f32_16x16x32_bf16 v[14:17], v[38:41], v[204:207], v[14:17]
	v_mfma_f32_16x16x32_bf16 v[162:165], v[184:187], v[204:207], v[162:165]
	v_add_u32_e32 v242, 0xfffff400, v182
	s_waitcnt lgkmcnt(0)
	v_mfma_f32_16x16x32_bf16 v[184:187], v[34:37], v[196:199], v[2:5]
	s_nop 2
	ds_read_b128 v[2:5], v242
	v_mfma_f32_16x16x32_bf16 v[216:219], v[34:37], v[208:211], v[10:13]
	v_mfma_f32_16x16x32_bf16 v[220:223], v[34:37], v[212:215], v[14:17]
	s_waitcnt lgkmcnt(0)
	v_mfma_f32_16x16x32_bf16 v[14:17], v[2:5], v[196:199], v[50:53]
	v_mfma_f32_16x16x32_bf16 v[10:13], v[2:5], v[200:203], v[54:57]
	s_nop 1
	ds_read_b128 v[50:53], v182 offset:1024
	ds_read_b128 v[54:57], v182 offset:5120
	v_mfma_f32_16x16x32_bf16 v[204:207], v[34:37], v[200:203], v[6:9]
	v_mfma_f32_16x16x32_bf16 v[6:9], v[2:5], v[208:211], v[58:61]
	v_mfma_f32_16x16x32_bf16 v[2:5], v[2:5], v[212:215], v[62:65]
	s_waitcnt lgkmcnt(0)
; #define LAS __attribute__((address_space(3)))
; template <int H2>
; DEV void s5_p1_all(LAS char* shm, int wid, int fr, int fq, bf16x8 (&wfr)[8], const bf16_t* wsp, f32x4 (&acc)[4][4], f32x4 (&sac)[4]) {
;     ...
;     for (int sp = 0; sp < 16; ++sp) {
;         bf16x8 bn[4], kf[4];
; #pragma unroll
;         for (int q = 0; q < 4; ++q) if (q >= S5_Q0(sp)) kf[q] = *(const LAS bf16x8*)(kb + (8 * q - 2 * sp + 30) * 512);
; #pragma unroll
;         for (int nt = 0; nt < 4; ++nt) bn[nt] = bu[nt];
;         if (sp < 15) {
; #pragma unroll
;             for (int nt = 0; nt < 4; ++nt) bn[nt] = *(const LAS bf16x8*)(ub + nt * 16 * 528 + (sp + 1) * 32);
;         }
; #pragma unroll
;         for (int nt = 0; nt < 4; ++nt) sac[nt] = __builtin_amdgcn_mfma_f32_16x16x32_bf16(wfr[sp & 7], bu[nt], sac[nt], 0, 0, 0);
;         if (sp < 8) wfr[sp & 7] = *(const bf16x8*)(wsp + (size_t)(sp + 8) * 64 * 8);
; #pragma unroll
;         for (int q = 0; q < 4; ++q) {
;             if (q >= S5_Q0(sp)) {
; #pragma unroll
;                 for (int nt = 0; nt < 4; ++nt) acc[q][nt] = __builtin_amdgcn_mfma_f32_16x16x32_bf16(kf[q], bu[nt], acc[q][nt], 0, 0, 0);
;             }
;         }
; #pragma unroll
;         for (int nt = 0; nt < 4; ++nt) bu[nt] = bn[nt];
;         __builtin_amdgcn_sched_barrier(0);
;     }
	v_mfma_f32_16x16x32_bf16 v[58:61], v[50:53], v[196:199], v[192:195]
	v_mfma_f32_16x16x32_bf16 v[62:65], v[50:53], v[200:203], v[70:73]
	v_mfma_f32_16x16x32_bf16 v[70:73], v[50:53], v[208:211], v[74:77]
	v_mfma_f32_16x16x32_bf16 v[50:53], v[50:53], v[212:215], v[78:81]
	v_mfma_f32_16x16x32_bf16 v[78:81], v[54:57], v[200:203], v[106:109]
	s_nop 2
	ds_read_b128 v[106:109], v182 offset:9216
	v_mfma_f32_16x16x32_bf16 v[74:77], v[54:57], v[196:199], v[102:105]
	v_mfma_f32_16x16x32_bf16 v[102:105], v[54:57], v[208:211], v[110:113]
	s_waitcnt lgkmcnt(0)
	v_mfma_f32_16x16x32_bf16 v[110:113], v[106:109], v[196:199], v[150:153]
	s_nop 2
	global_load_dwordx4 v[150:153], v[0:1], off offset:3072
	v_mfma_f32_16x16x32_bf16 v[54:57], v[54:57], v[212:215], v[114:117]
	v_mfma_f32_16x16x32_bf16 v[114:117], v[106:109], v[200:203], v[154:157]
	v_mfma_f32_16x16x32_bf16 v[154:157], v[106:109], v[208:211], v[158:161]
	s_nop 2
	ds_read_b128 v[158:161], v181 offset:128
	ds_read_b128 v[192:195], v181 offset:8576
	ds_read_b128 v[196:199], v181 offset:17024
	ds_read_b128 v[200:203], v181 offset:25472
	v_mfma_f32_16x16x32_bf16 v[106:109], v[106:109], v[212:215], v[162:165]
	s_waitcnt lgkmcnt(0)
	v_mfma_f32_16x16x32_bf16 v[162:165], v[30:33], v[158:161], v[184:187]
	v_add_co_u32_e32 v0, vcc, s36, v168
	v_mfma_f32_16x16x32_bf16 v[184:187], v[30:33], v[192:195], v[204:207]
	s_nop 0
	v_addc_co_u32_e32 v1, vcc, 0, v169, vcc
	v_mfma_f32_16x16x32_bf16 v[204:207], v[30:33], v[196:199], v[216:219]
	ds_read_b128 v[212:215], v182
	s_nop 1
	ds_read_b128 v[216:219], v182 offset:4096
	s_waitcnt lgkmcnt(0)
	v_mfma_f32_16x16x32_bf16 v[58:61], v[212:215], v[158:161], v[58:61]
	v_mfma_f32_16x16x32_bf16 v[62:65], v[212:215], v[192:195], v[62:65]
	v_mfma_f32_16x16x32_bf16 v[70:73], v[212:215], v[196:199], v[70:73]
	v_mfma_f32_16x16x32_bf16 v[50:53], v[212:215], v[200:203], v[50:53]
	ds_read_b128 v[212:215], v182 offset:8192
	v_mfma_f32_16x16x32_bf16 v[74:77], v[216:219], v[158:161], v[74:77]
	s_waitcnt lgkmcnt(0)
	v_mfma_f32_16x16x32_bf16 v[110:113], v[212:215], v[158:161], v[110:113]
	global_load_dwordx4 v[158:161], v[0:1], off
	v_mfma_f32_16x16x32_bf16 v[208:211], v[30:33], v[200:203], v[220:223]
	v_mfma_f32_16x16x32_bf16 v[78:81], v[216:219], v[192:195], v[78:81]
	v_mfma_f32_16x16x32_bf16 v[102:105], v[216:219], v[196:199], v[102:105]
	v_mfma_f32_16x16x32_bf16 v[54:57], v[216:219], v[200:203], v[54:57]
	v_mfma_f32_16x16x32_bf16 v[114:117], v[212:215], v[192:195], v[114:117]
	v_mfma_f32_16x16x32_bf16 v[154:157], v[212:215], v[196:199], v[154:157]
	ds_read_b128 v[192:195], v181 offset:160
	ds_read_b128 v[196:199], v181 offset:8608
	ds_read_b128 v[216:219], v181 offset:17056
	ds_read_b128 v[220:223], v181 offset:25504
	v_mfma_f32_16x16x32_bf16 v[106:109], v[212:215], v[200:203], v[106:109]
	s_waitcnt lgkmcnt(0)
	v_mfma_f32_16x16x32_bf16 v[200:203], v[26:29], v[216:219], v[204:207]
	v_mfma_f32_16x16x32_bf16 v[204:207], v[26:29], v[220:223], v[208:211]
	s_nop 2
	ds_read_b128 v[208:211], v183
	s_waitcnt lgkmcnt(0)
	v_mfma_f32_16x16x32_bf16 v[58:61], v[208:211], v[192:195], v[58:61]
	v_mfma_f32_16x16x32_bf16 v[62:65], v[208:211], v[196:199], v[62:65]
	v_mfma_f32_16x16x32_bf16 v[70:73], v[208:211], v[216:219], v[70:73]
	v_mfma_f32_16x16x32_bf16 v[50:53], v[208:211], v[220:223], v[50:53]
	ds_read_b128 v[208:211], v182 offset:3072
	ds_read_b128 v[212:215], v182 offset:7168
	v_mfma_f32_16x16x32_bf16 v[162:165], v[26:29], v[192:195], v[162:165]
	s_waitcnt lgkmcnt(0)
	v_mfma_f32_16x16x32_bf16 v[74:77], v[208:211], v[192:195], v[74:77]
	v_mfma_f32_16x16x32_bf16 v[110:113], v[212:215], v[192:195], v[110:113]
	global_load_dwordx4 v[192:195], v[0:1], off offset:1024
	v_mfma_f32_16x16x32_bf16 v[184:187], v[26:29], v[196:199], v[184:187]
	v_mfma_f32_16x16x32_bf16 v[78:81], v[208:211], v[196:199], v[78:81]
	v_mfma_f32_16x16x32_bf16 v[102:105], v[208:211], v[216:219], v[102:105]
	v_mfma_f32_16x16x32_bf16 v[54:57], v[208:211], v[220:223], v[54:57]
	v_mfma_f32_16x16x32_bf16 v[114:117], v[212:215], v[196:199], v[114:117]
	v_mfma_f32_16x16x32_bf16 v[154:157], v[212:215], v[216:219], v[154:157]
	ds_read_b128 v[196:199], v181 offset:192
	ds_read_b128 v[208:211], v181 offset:8640
	ds_read_b128 v[216:219], v181 offset:17088
	ds_read_b128 v[224:227], v181 offset:25536
	v_mfma_f32_16x16x32_bf16 v[106:109], v[212:215], v[220:223], v[106:109]
	ds_read_b128 v[212:215], v241
	s_waitcnt lgkmcnt(0)
	v_mfma_f32_16x16x32_bf16 v[162:165], v[22:25], v[196:199], v[162:165]
	v_mfma_f32_16x16x32_bf16 v[184:187], v[22:25], v[208:211], v[184:187]
	v_mfma_f32_16x16x32_bf16 v[58:61], v[212:215], v[196:199], v[58:61]
	v_mfma_f32_16x16x32_bf16 v[220:223], v[212:215], v[208:211], v[62:65]
	v_mfma_f32_16x16x32_bf16 v[70:73], v[212:215], v[216:219], v[70:73]
	v_mfma_f32_16x16x32_bf16 v[50:53], v[212:215], v[224:227], v[50:53]
	s_nop 0
	ds_read_b128 v[62:65], v182 offset:2048
	ds_read_b128 v[212:215], v182 offset:6144
	s_waitcnt lgkmcnt(0)
	v_mfma_f32_16x16x32_bf16 v[74:77], v[62:65], v[196:199], v[74:77]
	v_mfma_f32_16x16x32_bf16 v[110:113], v[212:215], v[196:199], v[110:113]
	global_load_dwordx4 v[196:199], v[0:1], off offset:2048
	v_mfma_f32_16x16x32_bf16 v[200:203], v[22:25], v[216:219], v[200:203]
	v_mfma_f32_16x16x32_bf16 v[78:81], v[62:65], v[208:211], v[78:81]
	v_mfma_f32_16x16x32_bf16 v[102:105], v[62:65], v[216:219], v[102:105]
	v_mfma_f32_16x16x32_bf16 v[114:117], v[212:215], v[208:211], v[114:117]
	v_mfma_f32_16x16x32_bf16 v[154:157], v[212:215], v[216:219], v[154:157]
	ds_read_b128 v[208:211], v181 offset:224
	ds_read_b128 v[216:219], v181 offset:8672
	ds_read_b128 v[232:235], v181 offset:17120
	ds_read_b128 v[236:239], v181 offset:25568
	v_mfma_f32_16x16x32_bf16 v[106:109], v[212:215], v[224:227], v[106:109]
	v_mfma_f32_16x16x32_bf16 v[204:207], v[22:25], v[224:227], v[204:207]
	v_mfma_f32_16x16x32_bf16 v[228:231], v[62:65], v[224:227], v[54:57]
	ds_read_b128 v[212:215], v242
	s_waitcnt lgkmcnt(0)
; #define LAS __attribute__((address_space(3)))
; template <int H2>
; DEV void s5_p1_all(LAS char* shm, int wid, int fr, int fq, bf16x8 (&wfr)[8], const bf16_t* wsp, f32x4 (&acc)[4][4], f32x4 (&sac)[4]) {
;     ...
;     for (int sp = 0; sp < 16; ++sp) {
;         bf16x8 bn[4], kf[4];
; #pragma unroll
;         for (int q = 0; q < 4; ++q) if (q >= S5_Q0(sp)) kf[q] = *(const LAS bf16x8*)(kb + (8 * q - 2 * sp + 30) * 512);
; #pragma unroll
;         for (int nt = 0; nt < 4; ++nt) bn[nt] = bu[nt];
;         if (sp < 15) {
; #pragma unroll
;             for (int nt = 0; nt < 4; ++nt) bn[nt] = *(const LAS bf16x8*)(ub + nt * 16 * 528 + (sp + 1) * 32);
;         }
; #pragma unroll
;         for (int nt = 0; nt < 4; ++nt) sac[nt] = __builtin_amdgcn_mfma_f32_16x16x32_bf16(wfr[sp & 7], bu[nt], sac[nt], 0, 0, 0);
;         if (sp < 8) wfr[sp & 7] = *(const bf16x8*)(wsp + (size_t)(sp + 8) * 64 * 8);
; #pragma unroll
;         for (int q = 0; q < 4; ++q) {
;             if (q >= S5_Q0(sp)) {
; #pragma unroll
;                 for (int nt = 0; nt < 4; ++nt) acc[q][nt] = __builtin_amdgcn_mfma_f32_16x16x32_bf16(kf[q], bu[nt], acc[q][nt], 0, 0, 0);
;             }
;         }
; #pragma unroll
;         for (int nt = 0; nt < 4; ++nt) bu[nt] = bn[nt];
;         __builtin_amdgcn_sched_barrier(0);
;     }
	v_mfma_f32_16x16x32_bf16 v[162:165], v[18:21], v[208:211], v[162:165]
	v_mfma_f32_16x16x32_bf16 v[184:187], v[18:21], v[216:219], v[184:187]
	v_mfma_f32_16x16x32_bf16 v[62:65], v[212:215], v[208:211], v[58:61]
	v_mfma_f32_16x16x32_bf16 v[58:61], v[212:215], v[216:219], v[220:223]
	v_mfma_f32_16x16x32_bf16 v[54:57], v[212:215], v[232:235], v[70:73]
	v_mfma_f32_16x16x32_bf16 v[50:53], v[212:215], v[236:239], v[50:53]
	s_nop 1
	ds_read_b128 v[70:73], v182 offset:1024
	ds_read_b128 v[212:215], v182 offset:5120
	s_waitcnt lgkmcnt(0)
	v_mfma_f32_16x16x32_bf16 v[74:77], v[70:73], v[208:211], v[74:77]
	v_mfma_f32_16x16x32_bf16 v[110:113], v[212:215], v[208:211], v[110:113]
	global_load_dwordx4 v[208:211], v[0:1], off offset:3072
	v_mfma_f32_16x16x32_bf16 v[78:81], v[70:73], v[216:219], v[78:81]
	v_mfma_f32_16x16x32_bf16 v[102:105], v[70:73], v[232:235], v[102:105]
	v_mfma_f32_16x16x32_bf16 v[70:73], v[70:73], v[236:239], v[228:231]
	v_mfma_f32_16x16x32_bf16 v[114:117], v[212:215], v[216:219], v[114:117]
	ds_read_b128 v[216:219], v181 offset:256
	ds_read_b128 v[220:223], v181 offset:8704
	ds_read_b128 v[224:227], v181 offset:17152
	ds_read_b128 v[228:231], v181 offset:25600
	v_mfma_f32_16x16x32_bf16 v[154:157], v[212:215], v[232:235], v[154:157]
	v_mfma_f32_16x16x32_bf16 v[106:109], v[212:215], v[236:239], v[106:109]
	v_mfma_f32_16x16x32_bf16 v[200:203], v[18:21], v[232:235], v[200:203]
	v_mfma_f32_16x16x32_bf16 v[204:207], v[18:21], v[236:239], v[204:207]
	ds_read_b128 v[212:215], v182
	ds_read_b128 v[232:235], v182 offset:4096
	s_waitcnt vmcnt(0) lgkmcnt(0)
	v_mfma_f32_16x16x32_bf16 v[162:165], v[82:85], v[216:219], v[162:165]
	v_mfma_f32_16x16x32_bf16 v[184:187], v[82:85], v[220:223], v[184:187]
	v_mfma_f32_16x16x32_bf16 v[200:203], v[82:85], v[224:227], v[200:203]
	v_mfma_f32_16x16x32_bf16 v[74:77], v[212:215], v[216:219], v[74:77]
	v_mfma_f32_16x16x32_bf16 v[78:81], v[212:215], v[220:223], v[78:81]
	v_mfma_f32_16x16x32_bf16 v[102:105], v[212:215], v[224:227], v[102:105]
	v_mfma_f32_16x16x32_bf16 v[70:73], v[212:215], v[228:231], v[70:73]
	v_mfma_f32_16x16x32_bf16 v[110:113], v[232:235], v[216:219], v[110:113]
	v_mfma_f32_16x16x32_bf16 v[114:117], v[232:235], v[220:223], v[114:117]
	v_mfma_f32_16x16x32_bf16 v[154:157], v[232:235], v[224:227], v[154:157]
	ds_read_b128 v[212:215], v181 offset:288
	ds_read_b128 v[216:219], v181 offset:8736
	ds_read_b128 v[220:223], v181 offset:17184
	ds_read_b128 v[224:227], v181 offset:25632
	v_mfma_f32_16x16x32_bf16 v[106:109], v[232:235], v[228:231], v[106:109]
	v_mfma_f32_16x16x32_bf16 v[204:207], v[82:85], v[228:231], v[204:207]
	s_waitcnt lgkmcnt(3)
	v_mfma_f32_16x16x32_bf16 v[162:165], v[66:69], v[212:215], v[162:165]
	s_waitcnt lgkmcnt(2)
	v_mfma_f32_16x16x32_bf16 v[184:187], v[66:69], v[216:219], v[184:187]
	s_waitcnt lgkmcnt(1)
	v_mfma_f32_16x16x32_bf16 v[200:203], v[66:69], v[220:223], v[200:203]
	s_waitcnt lgkmcnt(0)
	v_mfma_f32_16x16x32_bf16 v[66:69], v[66:69], v[224:227], v[204:207]
	s_nop 2
	ds_read_b128 v[204:207], v183
	ds_read_b128 v[228:231], v182 offset:3072
	s_waitcnt lgkmcnt(1)
	v_mfma_f32_16x16x32_bf16 v[74:77], v[204:207], v[212:215], v[74:77]
	v_mfma_f32_16x16x32_bf16 v[78:81], v[204:207], v[216:219], v[78:81]
	v_mfma_f32_16x16x32_bf16 v[102:105], v[204:207], v[220:223], v[102:105]
	v_mfma_f32_16x16x32_bf16 v[70:73], v[204:207], v[224:227], v[70:73]
	s_waitcnt lgkmcnt(0)
	v_mfma_f32_16x16x32_bf16 v[110:113], v[228:231], v[212:215], v[110:113]
	v_mfma_f32_16x16x32_bf16 v[114:117], v[228:231], v[216:219], v[114:117]
	v_mfma_f32_16x16x32_bf16 v[154:157], v[228:231], v[220:223], v[154:157]
	ds_read_b128 v[204:207], v181 offset:320
	ds_read_b128 v[212:215], v181 offset:8768
	ds_read_b128 v[216:219], v181 offset:17216
	ds_read_b128 v[220:223], v181 offset:25664
	v_mfma_f32_16x16x32_bf16 v[106:109], v[228:231], v[224:227], v[106:109]
	s_waitcnt lgkmcnt(3)
	v_mfma_f32_16x16x32_bf16 v[162:165], v[188:191], v[204:207], v[162:165]
	s_waitcnt lgkmcnt(2)
	v_mfma_f32_16x16x32_bf16 v[184:187], v[188:191], v[212:215], v[184:187]
	s_waitcnt lgkmcnt(1)
	v_mfma_f32_16x16x32_bf16 v[200:203], v[188:191], v[216:219], v[200:203]
	s_waitcnt lgkmcnt(0)
	v_mfma_f32_16x16x32_bf16 v[66:69], v[188:191], v[220:223], v[66:69]
	ds_read_b128 v[188:191], v241
	ds_read_b128 v[224:227], v182 offset:2048
	s_waitcnt lgkmcnt(1)
	v_mfma_f32_16x16x32_bf16 v[74:77], v[188:191], v[204:207], v[74:77]
	v_mfma_f32_16x16x32_bf16 v[228:231], v[188:191], v[212:215], v[78:81]
	v_mfma_f32_16x16x32_bf16 v[102:105], v[188:191], v[216:219], v[102:105]
	s_waitcnt lgkmcnt(0)
	v_mfma_f32_16x16x32_bf16 v[110:113], v[224:227], v[204:207], v[110:113]
	v_mfma_f32_16x16x32_bf16 v[114:117], v[224:227], v[212:215], v[114:117]
	v_mfma_f32_16x16x32_bf16 v[154:157], v[224:227], v[216:219], v[154:157]
	ds_read_b128 v[204:207], v181 offset:352
	ds_read_b128 v[212:215], v181 offset:8800
	ds_read_b128 v[216:219], v181 offset:17248
	ds_read_b128 v[232:235], v181 offset:25696
	v_mfma_f32_16x16x32_bf16 v[106:109], v[224:227], v[220:223], v[106:109]
	v_mfma_f32_16x16x32_bf16 v[188:191], v[188:191], v[220:223], v[70:73]
	s_waitcnt lgkmcnt(3)
; #define LAS __attribute__((address_space(3)))
; template <int H2>
; DEV void s5_p1_all(LAS char* shm, int wid, int fr, int fq, bf16x8 (&wfr)[8], const bf16_t* wsp, f32x4 (&acc)[4][4], f32x4 (&sac)[4]) {
;     ...
;     for (int sp = 0; sp < 16; ++sp) {
;         bf16x8 bn[4], kf[4];
; #pragma unroll
;         for (int q = 0; q < 4; ++q) if (q >= S5_Q0(sp)) kf[q] = *(const LAS bf16x8*)(kb + (8 * q - 2 * sp + 30) * 512);
; #pragma unroll
;         for (int nt = 0; nt < 4; ++nt) bn[nt] = bu[nt];
;         if (sp < 15) {
; #pragma unroll
;             for (int nt = 0; nt < 4; ++nt) bn[nt] = *(const LAS bf16x8*)(ub + nt * 16 * 528 + (sp + 1) * 32);
;         }
; #pragma unroll
;         for (int nt = 0; nt < 4; ++nt) sac[nt] = __builtin_amdgcn_mfma_f32_16x16x32_bf16(wfr[sp & 7], bu[nt], sac[nt], 0, 0, 0);
;         if (sp < 8) wfr[sp & 7] = *(const bf16x8*)(wsp + (size_t)(sp + 8) * 64 * 8);
; #pragma unroll
;         for (int q = 0; q < 4; ++q) {
;             if (q >= S5_Q0(sp)) {
; #pragma unroll
;                 for (int nt = 0; nt < 4; ++nt) acc[q][nt] = __builtin_amdgcn_mfma_f32_16x16x32_bf16(kf[q], bu[nt], acc[q][nt], 0, 0, 0);
;             }
;         }
; #pragma unroll
;         for (int nt = 0; nt < 4; ++nt) bu[nt] = bn[nt];
;         __builtin_amdgcn_sched_barrier(0);
;     }
	v_mfma_f32_16x16x32_bf16 v[162:165], v[150:153], v[204:207], v[162:165]
	s_waitcnt lgkmcnt(2)
	v_mfma_f32_16x16x32_bf16 v[184:187], v[150:153], v[212:215], v[184:187]
	s_waitcnt lgkmcnt(1)
	v_mfma_f32_16x16x32_bf16 v[200:203], v[150:153], v[216:219], v[200:203]
	s_waitcnt lgkmcnt(0)
	v_mfma_f32_16x16x32_bf16 v[150:153], v[150:153], v[232:235], v[66:69]
	s_nop 2
	ds_read_b128 v[66:69], v242
	ds_read_b128 v[220:223], v182 offset:1024
	s_waitcnt lgkmcnt(1)
	v_mfma_f32_16x16x32_bf16 v[78:81], v[66:69], v[204:207], v[74:77]
	v_mfma_f32_16x16x32_bf16 v[74:77], v[66:69], v[212:215], v[228:231]
	v_mfma_f32_16x16x32_bf16 v[70:73], v[66:69], v[216:219], v[102:105]
	v_mfma_f32_16x16x32_bf16 v[66:69], v[66:69], v[232:235], v[188:191]
	s_waitcnt lgkmcnt(0)
	v_mfma_f32_16x16x32_bf16 v[102:105], v[220:223], v[204:207], v[110:113]
	v_mfma_f32_16x16x32_bf16 v[110:113], v[220:223], v[212:215], v[114:117]
	v_mfma_f32_16x16x32_bf16 v[114:117], v[220:223], v[216:219], v[154:157]
	s_nop 2
	ds_read_b128 v[154:157], v181 offset:384
	ds_read_b128 v[188:191], v181 offset:8832
	ds_read_b128 v[204:207], v181 offset:17280
	ds_read_b128 v[212:215], v181 offset:25728
	v_mfma_f32_16x16x32_bf16 v[106:109], v[220:223], v[232:235], v[106:109]
	s_waitcnt lgkmcnt(3)
	v_mfma_f32_16x16x32_bf16 v[162:165], v[158:161], v[154:157], v[162:165]
	s_waitcnt lgkmcnt(2)
	v_mfma_f32_16x16x32_bf16 v[184:187], v[158:161], v[188:191], v[184:187]
	s_waitcnt lgkmcnt(1)
	v_mfma_f32_16x16x32_bf16 v[200:203], v[158:161], v[204:207], v[200:203]
	s_waitcnt lgkmcnt(0)
	v_mfma_f32_16x16x32_bf16 v[150:153], v[158:161], v[212:215], v[150:153]
	ds_read_b128 v[158:161], v182
	s_waitcnt lgkmcnt(0)
	v_mfma_f32_16x16x32_bf16 v[102:105], v[158:161], v[154:157], v[102:105]
	v_mfma_f32_16x16x32_bf16 v[110:113], v[158:161], v[188:191], v[110:113]
	v_mfma_f32_16x16x32_bf16 v[114:117], v[158:161], v[204:207], v[114:117]
	ds_read_b128 v[154:157], v181 offset:416
	ds_read_b128 v[188:191], v181 offset:8864
	ds_read_b128 v[204:207], v181 offset:17312
	ds_read_b128 v[216:219], v181 offset:25760
	v_mfma_f32_16x16x32_bf16 v[106:109], v[158:161], v[212:215], v[106:109]
	s_waitcnt lgkmcnt(3)
	v_mfma_f32_16x16x32_bf16 v[158:161], v[192:195], v[154:157], v[162:165]
	s_waitcnt lgkmcnt(2)
	v_mfma_f32_16x16x32_bf16 v[162:165], v[192:195], v[188:191], v[184:187]
	s_waitcnt lgkmcnt(1)
	v_mfma_f32_16x16x32_bf16 v[184:187], v[192:195], v[204:207], v[200:203]
	s_waitcnt lgkmcnt(0)
	v_mfma_f32_16x16x32_bf16 v[150:153], v[192:195], v[216:219], v[150:153]
	ds_read_b128 v[192:195], v183
	s_waitcnt lgkmcnt(0)
	v_mfma_f32_16x16x32_bf16 v[102:105], v[192:195], v[154:157], v[102:105]
	v_mfma_f32_16x16x32_bf16 v[110:113], v[192:195], v[188:191], v[110:113]
	v_mfma_f32_16x16x32_bf16 v[114:117], v[192:195], v[204:207], v[114:117]
	ds_read_b128 v[154:157], v181 offset:448
	ds_read_b128 v[188:191], v181 offset:8896
	ds_read_b128 v[200:203], v181 offset:17344
	ds_read_b128 v[204:207], v181 offset:25792
	v_mfma_f32_16x16x32_bf16 v[106:109], v[192:195], v[216:219], v[106:109]
	s_waitcnt lgkmcnt(2)
	v_mfma_f32_16x16x32_bf16 v[192:195], v[196:199], v[188:191], v[162:165]
	s_nop 2
	ds_read_b128 v[162:165], v241
	v_mfma_f32_16x16x32_bf16 v[158:161], v[196:199], v[154:157], v[158:161]
	s_waitcnt lgkmcnt(2)
	v_mfma_f32_16x16x32_bf16 v[184:187], v[196:199], v[200:203], v[184:187]
	s_waitcnt lgkmcnt(1)
	v_mfma_f32_16x16x32_bf16 v[150:153], v[196:199], v[204:207], v[150:153]
	s_waitcnt lgkmcnt(0)
	v_mfma_f32_16x16x32_bf16 v[188:191], v[162:165], v[188:191], v[110:113]
	v_mfma_f32_16x16x32_bf16 v[114:117], v[162:165], v[200:203], v[114:117]
	s_nop 1
	ds_read_b128 v[110:113], v181 offset:480
	ds_read_b128 v[196:199], v181 offset:8928
	ds_read_b128 v[200:203], v181 offset:17376
	ds_read_b128 v[212:215], v181 offset:25824
	v_mfma_f32_16x16x32_bf16 v[102:105], v[162:165], v[154:157], v[102:105]
	v_mfma_f32_16x16x32_bf16 v[204:207], v[162:165], v[204:207], v[106:109]
	s_waitcnt lgkmcnt(1)
	v_mfma_f32_16x16x32_bf16 v[154:157], v[208:211], v[200:203], v[184:187]
	s_nop 2
	ds_read_b128 v[184:187], v242
	v_mfma_f32_16x16x32_bf16 v[162:165], v[208:211], v[110:113], v[158:161]
	v_mfma_f32_16x16x32_bf16 v[158:161], v[208:211], v[196:199], v[192:195]
	s_waitcnt lgkmcnt(1)
	v_mfma_f32_16x16x32_bf16 v[150:153], v[208:211], v[212:215], v[150:153]
	s_waitcnt lgkmcnt(0)
	v_mfma_f32_16x16x32_bf16 v[110:113], v[184:187], v[110:113], v[102:105]
	v_mfma_f32_16x16x32_bf16 v[106:109], v[184:187], v[196:199], v[188:191]
	v_mfma_f32_16x16x32_bf16 v[102:105], v[184:187], v[200:203], v[114:117]
	v_mfma_f32_16x16x32_bf16 v[114:117], v[184:187], v[212:215], v[204:207]
	s_cbranch_execz .LBB0_1151
	s_branch .LBB0_1152
